# zero-setprio variant with the 32 duplicate compiler s_waitcnt lgkmcnt(0) between K-loop barrier and first MFMA deleted
# baseline (speedup 1.0000x reference)
;     __device__ __forceinline__ Pre prefetch(const Unit& u, int tid) const { return prenorm_load(stats, u.pn * BM, sW + (size_t)(u.pn >> 4) * SW_ROWS + u.pm * BM, tid); }
;     __device__ __forceinline__ Pre prefetch(const Unit& u, int tid) const { return prenorm_load(stats, u.pm * BM, sW + (size_t)(u.pm >> 4) * SW_ROWS + u.pn * BM, tid); }
;     __device__ __forceinline__ Pre prefetch(const Unit& u, int tid) const { return prenorm_load(stats, u.pm * BM, sW + (size_t)(u.pm >> 4) * SW_ROWS + u.pn * BM, tid); }
; #define PG8_STAGE(bufoff, gbase, voff) do { _Pragma("unroll") for (int _i = 0; _i < 2; ++_i) \
;         __builtin_amdgcn_global_load_lds((const unsigned*)((const char*)(gbase) + (voff)[_i]), (LAS unsigned*)(lds + (bufoff) + ldsw + _i * 8192), 16, 0, 0); } while (0)
; #define PG8_LDA(dst, b, h) do { _Pragma("unroll") for (int m = 0; m < 4; ++m) _Pragma("unroll") for (int k = 0; k < 2; ++k) dst[m][k] = *(const LAS bf16x8*)(lds + PG8_SA(b, h) + aoff + m * 2048 + k * 1024); } while (0)
; #define PG8_WAIT_V(n) asm volatile("s_waitcnt vmcnt(" #n ")" ::: "memory")
; #define PG8_WAIT_L(n) asm volatile("s_waitcnt lgkmcnt(" #n ")" ::: "memory")
; template <class Epi, class Sched>
; __device__ __forceinline__ void gemm_phase(LAS unsigned char* lds, const Gemm g, const Sched& S, const Epi& E, const int tid) {
;     ...
;         const bool has_next = S.next(ui + 1, nxt);
;         const char* nA = has_next ? (const char*)g.A + (size_t)nxt.pm * tstep : cA; const char* nB = has_next ? (const char*)g.Bt + (size_t)nxt.pn * tstep : cB;
;         const typename Epi::Pre pre = E.prefetch(cur, tid);
;         for (int t = 0; t < nt; t += 2) {
;             const bool last = (t == nt - 2);
;             const char* a1 = cA + (size_t)(t + 1) * kstep;
;             const char* a2 = last ? nA : cA + (size_t)(t + 2) * kstep; const char* b2 = last ? nB : cB + (size_t)(t + 2) * kstep;
;             const char* a3 = a2 + kstep; const char* b3 = b2 + kstep;
;             PG8_LDB(B0, 0, 0); PG8_LDB(B1, 0, 1); PG8_SCHED; PG8_LDA(At, 0, 0); PG8_STAGE(PG8_SA(1, 1), a1 + hstep, voffA);
;             PG8_WAIT_V(8); PG8_WAIT_L(0); PG8_BAR; PG8_MMA(0, 0, At, B0); PG8_MMA(0, 1, At, B1); PG8_BAR; PG8_SCHED;
;             PG8_LDA(At, 0, 1); PG8_STAGE(PG8_SB(0, 0), b2, voffB); PG8_STAGE(PG8_SB(0, 1), b2 + hstep, voffB); PG8_STAGE(PG8_SA(0, 0), a2, voffA);
.LBB0_167:
	s_or_b64 exec, exec, s[22:23]
	s_ashr_i32 s55, s54, 31
	s_lshl_b64 s[22:23], s[54:55], 19
	s_add_u32 s22, s46, s22
	s_addc_u32 s23, s47, s23
	s_and_b64 s[38:39], s[6:7], exec
	s_cselect_b32 s55, s23, s65
	s_cselect_b32 s56, s22, s64
	s_ashr_i32 s63, s62, 31
	s_lshl_b64 s[38:39], s[62:63], 19
	s_add_u32 s38, s12, s38
	s_addc_u32 s39, s73, s39
	s_and_b64 s[58:59], s[6:7], exec
	s_cselect_b32 s57, s39, s67
	s_cselect_b32 s58, s38, s66
	s_add_u32 s64, s64, 0x40080
	s_addc_u32 s65, s65, 0
	s_add_u32 s59, s66, 0x100
	s_addc_u32 s60, s67, 0
	s_mov_b32 s61, -2
	s_add_u32 s63, s64, 0xfffc0080
	s_addc_u32 s66, s65, -1
	s_add_i32 s78, 0, 0x10000
	s_cmp_eq_u32 s61, 12
	s_cselect_b32 s71, s55, s66
	s_cselect_b32 s70, s56, s63
	v_add_u32_e32 v145, s78, v166
	s_cselect_b32 s67, s57, s60
	s_cselect_b32 s66, s58, s59
	s_add_i32 s63, 0, 0x14000
	ds_read_b128 v[146:149], v145
	ds_read_b128 v[150:153], v145 offset:1024
	ds_read_b128 v[154:157], v145 offset:2048
	ds_read_b128 v[158:161], v145 offset:3072
	v_add_u32_e32 v145, s63, v166
	ds_read_b128 v[172:175], v145
	ds_read_b128 v[176:179], v145 offset:1024
	ds_read_b128 v[180:183], v145 offset:2048
	ds_read_b128 v[184:187], v145 offset:3072
	v_lshl_add_u64 v[162:163], s[64:65], 0, v[140:141]
	s_add_i32 m0, s75, 0xc000
	ds_read_b128 v[188:191], v171
	ds_read_b128 v[198:201], v171 offset:1024
	ds_read_b128 v[202:205], v171 offset:2048
	ds_read_b128 v[206:209], v171 offset:3072
	ds_read_b128 v[210:213], v171 offset:4096
	ds_read_b128 v[214:217], v171 offset:5120
	ds_read_b128 v[218:221], v171 offset:6144
	ds_read_b128 v[230:233], v171 offset:7168
	global_load_lds_dwordx4 v[162:163], off
	v_lshl_add_u64 v[162:163], s[64:65], 0, v[142:143]
	s_add_i32 m0, s75, 0xe000
	s_nop 0
	global_load_lds_dwordx4 v[162:163], off
	s_waitcnt vmcnt(8)
	s_waitcnt lgkmcnt(0)
	s_barrier
	v_mfma_f32_16x16x32_bf16 v[128:131], v[146:149], v[188:191], 0
	v_mfma_f32_16x16x32_bf16 v[124:127], v[154:157], v[188:191], 0
	v_mfma_f32_16x16x32_bf16 v[104:107], v[154:157], v[202:205], 0
	v_mfma_f32_16x16x32_bf16 v[108:111], v[146:149], v[202:205], 0
	v_mfma_f32_16x16x32_bf16 v[92:95], v[146:149], v[210:213], 0
	v_mfma_f32_16x16x32_bf16 v[88:91], v[154:157], v[210:213], 0
	v_mfma_f32_16x16x32_bf16 v[72:75], v[154:157], v[218:221], 0
	v_mfma_f32_16x16x32_bf16 v[76:79], v[146:149], v[218:221], 0
	v_mfma_f32_16x16x32_bf16 v[128:131], v[150:153], v[198:201], v[128:131]
	v_mfma_f32_16x16x32_bf16 v[124:127], v[158:161], v[198:201], v[124:127]
	v_mfma_f32_16x16x32_bf16 v[104:107], v[158:161], v[206:209], v[104:107]
	v_mfma_f32_16x16x32_bf16 v[108:111], v[150:153], v[206:209], v[108:111]
	v_mfma_f32_16x16x32_bf16 v[92:95], v[150:153], v[214:217], v[92:95]
	v_mfma_f32_16x16x32_bf16 v[88:91], v[158:161], v[214:217], v[88:91]
	v_mfma_f32_16x16x32_bf16 v[72:75], v[158:161], v[230:233], v[72:75]
	v_mfma_f32_16x16x32_bf16 v[76:79], v[150:153], v[230:233], v[76:79]
	v_mfma_f32_16x16x32_bf16 v[120:123], v[172:175], v[188:191], 0
	v_mfma_f32_16x16x32_bf16 v[116:119], v[180:183], v[188:191], 0
	v_mfma_f32_16x16x32_bf16 v[96:99], v[180:183], v[202:205], 0
	v_mfma_f32_16x16x32_bf16 v[100:103], v[172:175], v[202:205], 0
	v_mfma_f32_16x16x32_bf16 v[84:87], v[172:175], v[210:213], 0
	v_mfma_f32_16x16x32_bf16 v[80:83], v[180:183], v[210:213], 0
	v_mfma_f32_16x16x32_bf16 v[64:67], v[180:183], v[218:221], 0
	v_mfma_f32_16x16x32_bf16 v[68:71], v[172:175], v[218:221], 0
	v_mfma_f32_16x16x32_bf16 v[120:123], v[176:179], v[198:201], v[120:123]
	v_mfma_f32_16x16x32_bf16 v[116:119], v[184:187], v[198:201], v[116:119]
	v_mfma_f32_16x16x32_bf16 v[96:99], v[184:187], v[206:209], v[96:99]
	v_mfma_f32_16x16x32_bf16 v[100:103], v[176:179], v[206:209], v[100:103]
	v_mfma_f32_16x16x32_bf16 v[84:87], v[176:179], v[214:217], v[84:87]
	v_mfma_f32_16x16x32_bf16 v[80:83], v[184:187], v[214:217], v[80:83]
	v_mfma_f32_16x16x32_bf16 v[64:67], v[184:187], v[230:233], v[64:67]
	v_mfma_f32_16x16x32_bf16 v[68:71], v[176:179], v[230:233], v[68:71]
	s_barrier
	s_add_i32 s78, s78, s74
	v_lshl_add_u64 v[162:163], s[66:67], 0, v[192:193]
	s_mov_b32 m0, s78
	ds_read_b128 v[188:191], v171 offset:16384
	ds_read_b128 v[198:201], v171 offset:17408
	ds_read_b128 v[202:205], v171 offset:18432
	ds_read_b128 v[206:209], v171 offset:19456
	ds_read_b128 v[210:213], v171 offset:20480
	ds_read_b128 v[214:217], v171 offset:21504
	ds_read_b128 v[218:221], v171 offset:22528
	ds_read_b128 v[230:233], v171 offset:23552
	global_load_lds_dwordx4 v[162:163], off
	s_add_i32 m0, s78, 0x2000
	s_add_u32 s78, s66, 0x40000
	v_lshl_add_u64 v[234:235], s[66:67], 0, v[134:135]
	s_addc_u32 s79, s67, 0
	s_add_i32 s63, s63, s74
	global_load_lds_dwordx4 v[234:235], off
	v_lshl_add_u64 v[236:237], s[78:79], 0, v[192:193]
	s_mov_b32 m0, s63
	v_lshl_add_u64 v[238:239], s[70:71], 0, v[136:137]
	global_load_lds_dwordx4 v[236:237], off
	v_lshl_add_u64 v[236:237], s[78:79], 0, v[134:135]
	s_add_i32 m0, s63, 0x2000
	s_nop 0
	global_load_lds_dwordx4 v[236:237], off
	v_lshl_add_u64 v[236:237], s[70:71], 0, v[138:139]
	s_mov_b32 m0, s75
	s_nop 0
	global_load_lds_dwordx4 v[236:237], off
	s_mov_b32 m0, s81
	s_nop 0
	global_load_lds_dwordx4 v[238:239], off
	s_waitcnt vmcnt(8)
	s_waitcnt lgkmcnt(0)
	s_barrier
; #define PG8_STAGE(bufoff, gbase, voff) do { _Pragma("unroll") for (int _i = 0; _i < 2; ++_i) \
;         __builtin_amdgcn_global_load_lds((const unsigned*)((const char*)(gbase) + (voff)[_i]), (LAS unsigned*)(lds + (bufoff) + ldsw + _i * 8192), 16, 0, 0); } while (0)
; #define PG8_LDA(dst, b, h) do { _Pragma("unroll") for (int m = 0; m < 4; ++m) _Pragma("unroll") for (int k = 0; k < 2; ++k) dst[m][k] = *(const LAS bf16x8*)(lds + PG8_SA(b, h) + aoff + m * 2048 + k * 1024); } while (0)
; #define PG8_LDB(dst, b, h) do { _Pragma("unroll") for (int n = 0; n < 2; ++n) _Pragma("unroll") for (int k = 0; k < 2; ++k) dst[n][k] = *(const LAS bf16x8*)(lds + PG8_SB(b, h) + boff + n * 2048 + k * 1024); } while (0)
; #define PG8_MMA(ai, bj, At, Bt) do { __builtin_amdgcn_s_setprio(1); _Pragma("unroll") for (int m = 0; m < 4; ++m) _Pragma("unroll") for (int n = 0; n < 2; ++n) _Pragma("unroll") for (int k = 0; k < 2; ++k) \
;         acc[ai][bj][m][n] = __builtin_amdgcn_mfma_f32_16x16x32_bf16(Bt[n][k], At[m][k], acc[ai][bj][m][n], 0, 0, 0); __builtin_amdgcn_s_setprio(0); } while (0)
; #define PG8_WAIT_V(n) asm volatile("s_waitcnt vmcnt(" #n ")" ::: "memory")
; #define PG8_WAIT_L(n) asm volatile("s_waitcnt lgkmcnt(" #n ")" ::: "memory")
; #define PG8_BAR __builtin_amdgcn_s_barrier()
; #define PG8_SCHED __builtin_amdgcn_sched_barrier(0)
; template <class Epi, class Sched>
; __device__ __forceinline__ void gemm_phase(LAS unsigned char* lds, const Gemm g, const Sched& S, const Epi& E, const int tid) {
;     ...
;             PG8_WAIT_V(8); PG8_WAIT_L(0); PG8_BAR; PG8_MMA(1, 0, At, B0); PG8_MMA(1, 1, At, B1); PG8_BAR; PG8_SCHED;
;             PG8_LDB(B0, 1, 0); PG8_LDB(B1, 1, 1); PG8_SCHED; PG8_LDA(At, 1, 0); PG8_STAGE(PG8_SA(0, 1), a2 + hstep, voffA);
;             PG8_WAIT_V(8); PG8_WAIT_L(0); PG8_BAR; PG8_MMA(0, 0, At, B0); PG8_MMA(0, 1, At, B1); PG8_BAR; PG8_SCHED;
	v_mfma_f32_16x16x32_bf16 v[60:63], v[146:149], v[188:191], 0
	v_mfma_f32_16x16x32_bf16 v[56:59], v[154:157], v[188:191], 0
	v_mfma_f32_16x16x32_bf16 v[40:43], v[154:157], v[202:205], 0
	v_mfma_f32_16x16x32_bf16 v[44:47], v[146:149], v[202:205], 0
	v_mfma_f32_16x16x32_bf16 v[28:31], v[146:149], v[210:213], 0
	v_mfma_f32_16x16x32_bf16 v[24:27], v[154:157], v[210:213], 0
	v_mfma_f32_16x16x32_bf16 v[8:11], v[154:157], v[218:221], 0
	v_mfma_f32_16x16x32_bf16 v[12:15], v[146:149], v[218:221], 0
	v_mfma_f32_16x16x32_bf16 v[60:63], v[150:153], v[198:201], v[60:63]
	v_mfma_f32_16x16x32_bf16 v[56:59], v[158:161], v[198:201], v[56:59]
	v_mfma_f32_16x16x32_bf16 v[40:43], v[158:161], v[206:209], v[40:43]
	v_mfma_f32_16x16x32_bf16 v[44:47], v[150:153], v[206:209], v[44:47]
	v_mfma_f32_16x16x32_bf16 v[28:31], v[150:153], v[214:217], v[28:31]
	v_mfma_f32_16x16x32_bf16 v[24:27], v[158:161], v[214:217], v[24:27]
	v_mfma_f32_16x16x32_bf16 v[8:11], v[158:161], v[230:233], v[8:11]
	v_mfma_f32_16x16x32_bf16 v[12:15], v[150:153], v[230:233], v[12:15]
	v_mfma_f32_16x16x32_bf16 v[52:55], v[172:175], v[188:191], 0
	v_mfma_f32_16x16x32_bf16 v[48:51], v[180:183], v[188:191], 0
	v_mfma_f32_16x16x32_bf16 v[32:35], v[180:183], v[202:205], 0
	v_mfma_f32_16x16x32_bf16 v[36:39], v[172:175], v[202:205], 0
	v_mfma_f32_16x16x32_bf16 v[20:23], v[172:175], v[210:213], 0
	v_mfma_f32_16x16x32_bf16 v[16:19], v[180:183], v[210:213], 0
	v_mfma_f32_16x16x32_bf16 v[0:3], v[180:183], v[218:221], 0
	v_mfma_f32_16x16x32_bf16 v[4:7], v[172:175], v[218:221], 0
	v_mfma_f32_16x16x32_bf16 v[52:55], v[176:179], v[198:201], v[52:55]
	v_mfma_f32_16x16x32_bf16 v[48:51], v[184:187], v[198:201], v[48:51]
	v_mfma_f32_16x16x32_bf16 v[32:35], v[184:187], v[206:209], v[32:35]
	v_mfma_f32_16x16x32_bf16 v[36:39], v[176:179], v[206:209], v[36:39]
	v_mfma_f32_16x16x32_bf16 v[20:23], v[176:179], v[214:217], v[20:23]
	v_mfma_f32_16x16x32_bf16 v[16:19], v[184:187], v[214:217], v[16:19]
	v_mfma_f32_16x16x32_bf16 v[0:3], v[184:187], v[230:233], v[0:3]
	v_mfma_f32_16x16x32_bf16 v[4:7], v[176:179], v[230:233], v[4:7]
	s_barrier
	s_add_i32 s63, 0, 0x18000
	v_add_u32_e32 v145, s63, v166
	s_add_i32 s78, 0, 0x1c000
	ds_read_b128 v[146:149], v145
	ds_read_b128 v[150:153], v145 offset:1024
	ds_read_b128 v[154:157], v145 offset:2048
	ds_read_b128 v[158:161], v145 offset:3072
	v_add_u32_e32 v145, s78, v166
	ds_read_b128 v[172:175], v145
	ds_read_b128 v[176:179], v145 offset:1024
	ds_read_b128 v[180:183], v145 offset:2048
	ds_read_b128 v[184:187], v145 offset:3072
	s_add_u32 s70, s70, 0x40000
	s_addc_u32 s71, s71, 0
	s_mov_b32 m0, s82
	v_lshl_add_u64 v[240:241], s[70:71], 0, v[138:139]
	ds_read_b128 v[188:191], v171 offset:32768
	ds_read_b128 v[198:201], v171 offset:33792
	ds_read_b128 v[202:205], v171 offset:34816
	ds_read_b128 v[206:209], v171 offset:35840
	ds_read_b128 v[210:213], v171 offset:36864
	ds_read_b128 v[214:217], v171 offset:37888
	ds_read_b128 v[218:221], v171 offset:38912
	ds_read_b128 v[230:233], v171 offset:39936
	global_load_lds_dwordx4 v[240:241], off
	v_lshl_add_u64 v[240:241], s[70:71], 0, v[136:137]
	s_mov_b32 m0, s83
	s_nop 0
	global_load_lds_dwordx4 v[240:241], off
	s_waitcnt vmcnt(8)
	s_waitcnt lgkmcnt(0)
	s_barrier
	v_mfma_f32_16x16x32_bf16 v[128:131], v[146:149], v[188:191], v[128:131]
	v_mfma_f32_16x16x32_bf16 v[124:127], v[154:157], v[188:191], v[124:127]
	v_mfma_f32_16x16x32_bf16 v[104:107], v[154:157], v[202:205], v[104:107]
	v_mfma_f32_16x16x32_bf16 v[108:111], v[146:149], v[202:205], v[108:111]
	v_mfma_f32_16x16x32_bf16 v[92:95], v[146:149], v[210:213], v[92:95]
	v_mfma_f32_16x16x32_bf16 v[88:91], v[154:157], v[210:213], v[88:91]
	v_mfma_f32_16x16x32_bf16 v[72:75], v[154:157], v[218:221], v[72:75]
	v_mfma_f32_16x16x32_bf16 v[76:79], v[146:149], v[218:221], v[76:79]
	v_mfma_f32_16x16x32_bf16 v[128:131], v[150:153], v[198:201], v[128:131]
	v_mfma_f32_16x16x32_bf16 v[124:127], v[158:161], v[198:201], v[124:127]
	v_mfma_f32_16x16x32_bf16 v[104:107], v[158:161], v[206:209], v[104:107]
	v_mfma_f32_16x16x32_bf16 v[108:111], v[150:153], v[206:209], v[108:111]
	v_mfma_f32_16x16x32_bf16 v[92:95], v[150:153], v[214:217], v[92:95]
	v_mfma_f32_16x16x32_bf16 v[88:91], v[158:161], v[214:217], v[88:91]
	v_mfma_f32_16x16x32_bf16 v[72:75], v[158:161], v[230:233], v[72:75]
	v_mfma_f32_16x16x32_bf16 v[76:79], v[150:153], v[230:233], v[76:79]
	v_mfma_f32_16x16x32_bf16 v[120:123], v[172:175], v[188:191], v[120:123]
	v_mfma_f32_16x16x32_bf16 v[116:119], v[180:183], v[188:191], v[116:119]
	v_mfma_f32_16x16x32_bf16 v[96:99], v[180:183], v[202:205], v[96:99]
	v_mfma_f32_16x16x32_bf16 v[100:103], v[172:175], v[202:205], v[100:103]
	v_mfma_f32_16x16x32_bf16 v[84:87], v[172:175], v[210:213], v[84:87]
	v_mfma_f32_16x16x32_bf16 v[80:83], v[180:183], v[210:213], v[80:83]
	v_mfma_f32_16x16x32_bf16 v[64:67], v[180:183], v[218:221], v[64:67]
	v_mfma_f32_16x16x32_bf16 v[68:71], v[172:175], v[218:221], v[68:71]
	v_mfma_f32_16x16x32_bf16 v[120:123], v[176:179], v[198:201], v[120:123]
	v_mfma_f32_16x16x32_bf16 v[116:119], v[184:187], v[198:201], v[116:119]
	v_mfma_f32_16x16x32_bf16 v[96:99], v[184:187], v[206:209], v[96:99]
	v_mfma_f32_16x16x32_bf16 v[100:103], v[176:179], v[206:209], v[100:103]
	v_mfma_f32_16x16x32_bf16 v[84:87], v[176:179], v[214:217], v[84:87]
	v_mfma_f32_16x16x32_bf16 v[80:83], v[184:187], v[214:217], v[80:83]
	v_mfma_f32_16x16x32_bf16 v[64:67], v[184:187], v[230:233], v[64:67]
	v_mfma_f32_16x16x32_bf16 v[68:71], v[176:179], v[230:233], v[68:71]
	s_barrier
; #define PG8_STAGE(bufoff, gbase, voff) do { _Pragma("unroll") for (int _i = 0; _i < 2; ++_i) \
;         __builtin_amdgcn_global_load_lds((const unsigned*)((const char*)(gbase) + (voff)[_i]), (LAS unsigned*)(lds + (bufoff) + ldsw + _i * 8192), 16, 0, 0); } while (0)
; #define PG8_LDA(dst, b, h) do { _Pragma("unroll") for (int m = 0; m < 4; ++m) _Pragma("unroll") for (int k = 0; k < 2; ++k) dst[m][k] = *(const LAS bf16x8*)(lds + PG8_SA(b, h) + aoff + m * 2048 + k * 1024); } while (0)
; #define PG8_LDB(dst, b, h) do { _Pragma("unroll") for (int n = 0; n < 2; ++n) _Pragma("unroll") for (int k = 0; k < 2; ++k) dst[n][k] = *(const LAS bf16x8*)(lds + PG8_SB(b, h) + boff + n * 2048 + k * 1024); } while (0)
; #define PG8_WAIT_V(n) asm volatile("s_waitcnt vmcnt(" #n ")" ::: "memory")
; #define PG8_BAR __builtin_amdgcn_s_barrier()
; template <class Epi, class Sched>
; __device__ __forceinline__ void gemm_phase(LAS unsigned char* lds, const Gemm g, const Sched& S, const Epi& E, const int tid) {
;     ...
;         for (int t = 0; t < nt; t += 2) {
;             const bool last = (t == nt - 2);
;             const char* a1 = cA + (size_t)(t + 1) * kstep;
;             const char* a2 = last ? nA : cA + (size_t)(t + 2) * kstep; const char* b2 = last ? nB : cB + (size_t)(t + 2) * kstep;
;             const char* a3 = a2 + kstep; const char* b3 = b2 + kstep;
;             PG8_LDB(B0, 0, 0); PG8_LDB(B1, 0, 1); PG8_SCHED; PG8_LDA(At, 0, 0); PG8_STAGE(PG8_SA(1, 1), a1 + hstep, voffA);
;             PG8_WAIT_V(8); PG8_WAIT_L(0); PG8_BAR; PG8_MMA(0, 0, At, B0); PG8_MMA(0, 1, At, B1); PG8_BAR; PG8_SCHED;
;             PG8_LDA(At, 0, 1); PG8_STAGE(PG8_SB(0, 0), b2, voffB); PG8_STAGE(PG8_SB(0, 1), b2 + hstep, voffB); PG8_STAGE(PG8_SA(0, 0), a2, voffA);
;             PG8_WAIT_V(8); PG8_WAIT_L(0); PG8_BAR; PG8_MMA(1, 0, At, B0); PG8_MMA(1, 1, At, B1); PG8_BAR; PG8_SCHED;
;             PG8_LDB(B0, 1, 0); PG8_LDB(B1, 1, 1); PG8_SCHED; PG8_LDA(At, 1, 0); PG8_STAGE(PG8_SA(0, 1), a2 + hstep, voffA);
;             PG8_WAIT_V(8); PG8_WAIT_L(0); PG8_BAR; PG8_MMA(0, 0, At, B0); PG8_MMA(0, 1, At, B1); PG8_BAR; PG8_SCHED;
;             PG8_LDA(At, 1, 1); PG8_STAGE(PG8_SB(1, 0), b3, voffB); PG8_STAGE(PG8_SB(1, 1), b3 + hstep, voffB); PG8_STAGE(PG8_SA(1, 0), a3, voffA);
;             PG8_WAIT_V(8); PG8_WAIT_L(0); PG8_BAR; PG8_MMA(1, 0, At, B0); PG8_MMA(1, 1, At, B1); PG8_BAR; PG8_SCHED;
	s_add_i32 s63, s63, s74
	v_lshl_add_u64 v[162:163], v[162:163], 0, s[68:69]
	s_mov_b32 m0, s63
	ds_read_b128 v[188:191], v171 offset:49152
	ds_read_b128 v[198:201], v171 offset:50176
	ds_read_b128 v[202:205], v171 offset:51200
	ds_read_b128 v[206:209], v171 offset:52224
	ds_read_b128 v[210:213], v171 offset:53248
	ds_read_b128 v[214:217], v171 offset:54272
	ds_read_b128 v[218:221], v171 offset:55296
	ds_read_b128 v[230:233], v171 offset:56320
	global_load_lds_dwordx4 v[162:163], off
	s_add_i32 m0, s63, 0x2000
	s_add_u32 s66, s66, 0x40080
	v_lshl_add_u64 v[162:163], v[234:235], 0, s[68:69]
	s_addc_u32 s67, s67, 0
	s_add_i32 s63, s78, s74
	global_load_lds_dwordx4 v[162:163], off
	v_lshl_add_u64 v[162:163], s[66:67], 0, v[192:193]
	s_mov_b32 m0, s63
	s_nop 0
	global_load_lds_dwordx4 v[162:163], off
	v_lshl_add_u64 v[162:163], s[66:67], 0, v[134:135]
	s_add_i32 m0, s63, 0x2000
	s_nop 0
	global_load_lds_dwordx4 v[162:163], off
	v_lshl_add_u64 v[162:163], v[236:237], 0, s[68:69]
	s_mov_b32 m0, s93
	s_nop 0
	global_load_lds_dwordx4 v[162:163], off
	v_lshl_add_u64 v[162:163], v[238:239], 0, s[68:69]
	s_mov_b32 m0, s94
	s_nop 0
	global_load_lds_dwordx4 v[162:163], off
	s_waitcnt vmcnt(8)
	s_waitcnt lgkmcnt(0)
	s_barrier
	v_mfma_f32_16x16x32_bf16 v[60:63], v[146:149], v[188:191], v[60:63]
	v_mfma_f32_16x16x32_bf16 v[56:59], v[154:157], v[188:191], v[56:59]
	v_mfma_f32_16x16x32_bf16 v[40:43], v[154:157], v[202:205], v[40:43]
	v_mfma_f32_16x16x32_bf16 v[44:47], v[146:149], v[202:205], v[44:47]
	v_mfma_f32_16x16x32_bf16 v[28:31], v[146:149], v[210:213], v[28:31]
	v_mfma_f32_16x16x32_bf16 v[24:27], v[154:157], v[210:213], v[24:27]
	v_mfma_f32_16x16x32_bf16 v[8:11], v[154:157], v[218:221], v[8:11]
	v_mfma_f32_16x16x32_bf16 v[12:15], v[146:149], v[218:221], v[12:15]
	v_mfma_f32_16x16x32_bf16 v[60:63], v[150:153], v[198:201], v[60:63]
	v_mfma_f32_16x16x32_bf16 v[56:59], v[158:161], v[198:201], v[56:59]
	v_mfma_f32_16x16x32_bf16 v[40:43], v[158:161], v[206:209], v[40:43]
	v_mfma_f32_16x16x32_bf16 v[44:47], v[150:153], v[206:209], v[44:47]
	v_mfma_f32_16x16x32_bf16 v[28:31], v[150:153], v[214:217], v[28:31]
	v_mfma_f32_16x16x32_bf16 v[24:27], v[158:161], v[214:217], v[24:27]
	v_mfma_f32_16x16x32_bf16 v[8:11], v[158:161], v[230:233], v[8:11]
	v_mfma_f32_16x16x32_bf16 v[12:15], v[150:153], v[230:233], v[12:15]
	v_mfma_f32_16x16x32_bf16 v[52:55], v[172:175], v[188:191], v[52:55]
	v_mfma_f32_16x16x32_bf16 v[48:51], v[180:183], v[188:191], v[48:51]
	v_mfma_f32_16x16x32_bf16 v[32:35], v[180:183], v[202:205], v[32:35]
	v_mfma_f32_16x16x32_bf16 v[36:39], v[172:175], v[202:205], v[36:39]
	v_mfma_f32_16x16x32_bf16 v[20:23], v[172:175], v[210:213], v[20:23]
	v_mfma_f32_16x16x32_bf16 v[16:19], v[180:183], v[210:213], v[16:19]
	v_mfma_f32_16x16x32_bf16 v[0:3], v[180:183], v[218:221], v[0:3]
	v_mfma_f32_16x16x32_bf16 v[4:7], v[172:175], v[218:221], v[4:7]
	v_mfma_f32_16x16x32_bf16 v[52:55], v[176:179], v[198:201], v[52:55]
	v_mfma_f32_16x16x32_bf16 v[48:51], v[184:187], v[198:201], v[48:51]
	v_mfma_f32_16x16x32_bf16 v[32:35], v[184:187], v[206:209], v[32:35]
	v_mfma_f32_16x16x32_bf16 v[36:39], v[176:179], v[206:209], v[36:39]
	v_mfma_f32_16x16x32_bf16 v[20:23], v[176:179], v[214:217], v[20:23]
	v_mfma_f32_16x16x32_bf16 v[16:19], v[184:187], v[214:217], v[16:19]
	v_mfma_f32_16x16x32_bf16 v[0:3], v[184:187], v[230:233], v[0:3]
	v_mfma_f32_16x16x32_bf16 v[4:7], v[176:179], v[230:233], v[4:7]
	s_barrier
	s_add_i32 s61, s61, 2
	s_add_u32 s64, s64, 0x100
	s_addc_u32 s65, s65, 0
	s_add_u32 s59, s59, 0x100
	s_addc_u32 s60, s60, 0
	s_cmp_gt_u32 s61, 13
.LBB0_168:
	s_add_u32 s63, s64, 0xfffc0080
	s_addc_u32 s66, s65, -1
	s_add_i32 s78, 0, 0x10000
	s_cmp_eq_u32 s61, 12
	s_cselect_b32 s71, s55, s66
	s_cselect_b32 s70, s56, s63
	v_add_u32_e32 v145, s78, v166
	s_cselect_b32 s67, s57, s60
	s_cselect_b32 s66, s58, s59
	s_add_i32 s63, 0, 0x14000
	ds_read_b128 v[146:149], v145
	ds_read_b128 v[150:153], v145 offset:1024
	ds_read_b128 v[154:157], v145 offset:2048
	ds_read_b128 v[158:161], v145 offset:3072
	v_add_u32_e32 v145, s63, v166
	ds_read_b128 v[172:175], v145
	ds_read_b128 v[176:179], v145 offset:1024
	ds_read_b128 v[180:183], v145 offset:2048
	ds_read_b128 v[184:187], v145 offset:3072
	v_lshl_add_u64 v[162:163], s[64:65], 0, v[140:141]
	s_add_i32 m0, s75, 0xc000
	ds_read_b128 v[188:191], v171
	ds_read_b128 v[198:201], v171 offset:1024
	ds_read_b128 v[202:205], v171 offset:2048
	ds_read_b128 v[206:209], v171 offset:3072
	ds_read_b128 v[210:213], v171 offset:4096
	ds_read_b128 v[214:217], v171 offset:5120
	ds_read_b128 v[218:221], v171 offset:6144
	ds_read_b128 v[230:233], v171 offset:7168
	global_load_lds_dwordx4 v[162:163], off
	v_lshl_add_u64 v[162:163], s[64:65], 0, v[142:143]
	s_add_i32 m0, s75, 0xe000
	s_nop 0
	global_load_lds_dwordx4 v[162:163], off
	s_waitcnt vmcnt(8)
	s_waitcnt lgkmcnt(0)
	s_barrier
; #define PG8_STAGE(bufoff, gbase, voff) do { _Pragma("unroll") for (int _i = 0; _i < 2; ++_i) \
;         __builtin_amdgcn_global_load_lds((const unsigned*)((const char*)(gbase) + (voff)[_i]), (LAS unsigned*)(lds + (bufoff) + ldsw + _i * 8192), 16, 0, 0); } while (0)
; #define PG8_LDA(dst, b, h) do { _Pragma("unroll") for (int m = 0; m < 4; ++m) _Pragma("unroll") for (int k = 0; k < 2; ++k) dst[m][k] = *(const LAS bf16x8*)(lds + PG8_SA(b, h) + aoff + m * 2048 + k * 1024); } while (0)
; #define PG8_MMA(ai, bj, At, Bt) do { __builtin_amdgcn_s_setprio(1); _Pragma("unroll") for (int m = 0; m < 4; ++m) _Pragma("unroll") for (int n = 0; n < 2; ++n) _Pragma("unroll") for (int k = 0; k < 2; ++k) \
;         acc[ai][bj][m][n] = __builtin_amdgcn_mfma_f32_16x16x32_bf16(Bt[n][k], At[m][k], acc[ai][bj][m][n], 0, 0, 0); __builtin_amdgcn_s_setprio(0); } while (0)
; #define PG8_WAIT_V(n) asm volatile("s_waitcnt vmcnt(" #n ")" ::: "memory")
; #define PG8_WAIT_L(n) asm volatile("s_waitcnt lgkmcnt(" #n ")" ::: "memory")
; #define PG8_BAR __builtin_amdgcn_s_barrier()
; #define PG8_SCHED __builtin_amdgcn_sched_barrier(0)
; template <class Epi, class Sched>
; __device__ __forceinline__ void gemm_phase(LAS unsigned char* lds, const Gemm g, const Sched& S, const Epi& E, const int tid) {
;     ...
;             PG8_WAIT_V(8); PG8_WAIT_L(0); PG8_BAR; PG8_MMA(0, 0, At, B0); PG8_MMA(0, 1, At, B1); PG8_BAR; PG8_SCHED;
;             PG8_LDA(At, 0, 1); PG8_STAGE(PG8_SB(0, 0), b2, voffB); PG8_STAGE(PG8_SB(0, 1), b2 + hstep, voffB); PG8_STAGE(PG8_SA(0, 0), a2, voffA);
;             PG8_WAIT_V(8); PG8_WAIT_L(0); PG8_BAR; PG8_MMA(1, 0, At, B0); PG8_MMA(1, 1, At, B1); PG8_BAR; PG8_SCHED;
	v_mfma_f32_16x16x32_bf16 v[128:131], v[146:149], v[188:191], v[128:131]
	v_mfma_f32_16x16x32_bf16 v[124:127], v[154:157], v[188:191], v[124:127]
	v_mfma_f32_16x16x32_bf16 v[104:107], v[154:157], v[202:205], v[104:107]
	v_mfma_f32_16x16x32_bf16 v[108:111], v[146:149], v[202:205], v[108:111]
	v_mfma_f32_16x16x32_bf16 v[92:95], v[146:149], v[210:213], v[92:95]
	v_mfma_f32_16x16x32_bf16 v[88:91], v[154:157], v[210:213], v[88:91]
	v_mfma_f32_16x16x32_bf16 v[72:75], v[154:157], v[218:221], v[72:75]
	v_mfma_f32_16x16x32_bf16 v[76:79], v[146:149], v[218:221], v[76:79]
	v_mfma_f32_16x16x32_bf16 v[128:131], v[150:153], v[198:201], v[128:131]
	v_mfma_f32_16x16x32_bf16 v[124:127], v[158:161], v[198:201], v[124:127]
	v_mfma_f32_16x16x32_bf16 v[104:107], v[158:161], v[206:209], v[104:107]
	v_mfma_f32_16x16x32_bf16 v[108:111], v[150:153], v[206:209], v[108:111]
	v_mfma_f32_16x16x32_bf16 v[92:95], v[150:153], v[214:217], v[92:95]
	v_mfma_f32_16x16x32_bf16 v[88:91], v[158:161], v[214:217], v[88:91]
	v_mfma_f32_16x16x32_bf16 v[72:75], v[158:161], v[230:233], v[72:75]
	v_mfma_f32_16x16x32_bf16 v[76:79], v[150:153], v[230:233], v[76:79]
	v_mfma_f32_16x16x32_bf16 v[120:123], v[172:175], v[188:191], v[120:123]
	v_mfma_f32_16x16x32_bf16 v[116:119], v[180:183], v[188:191], v[116:119]
	v_mfma_f32_16x16x32_bf16 v[96:99], v[180:183], v[202:205], v[96:99]
	v_mfma_f32_16x16x32_bf16 v[100:103], v[172:175], v[202:205], v[100:103]
	v_mfma_f32_16x16x32_bf16 v[84:87], v[172:175], v[210:213], v[84:87]
	v_mfma_f32_16x16x32_bf16 v[80:83], v[180:183], v[210:213], v[80:83]
	v_mfma_f32_16x16x32_bf16 v[64:67], v[180:183], v[218:221], v[64:67]
	v_mfma_f32_16x16x32_bf16 v[68:71], v[172:175], v[218:221], v[68:71]
	v_mfma_f32_16x16x32_bf16 v[120:123], v[176:179], v[198:201], v[120:123]
	v_mfma_f32_16x16x32_bf16 v[116:119], v[184:187], v[198:201], v[116:119]
	v_mfma_f32_16x16x32_bf16 v[96:99], v[184:187], v[206:209], v[96:99]
	v_mfma_f32_16x16x32_bf16 v[100:103], v[176:179], v[206:209], v[100:103]
	v_mfma_f32_16x16x32_bf16 v[84:87], v[176:179], v[214:217], v[84:87]
	v_mfma_f32_16x16x32_bf16 v[80:83], v[184:187], v[214:217], v[80:83]
	v_mfma_f32_16x16x32_bf16 v[64:67], v[184:187], v[230:233], v[64:67]
	v_mfma_f32_16x16x32_bf16 v[68:71], v[176:179], v[230:233], v[68:71]
	s_barrier
	s_add_i32 s78, s78, s74
	v_lshl_add_u64 v[162:163], s[66:67], 0, v[192:193]
	s_mov_b32 m0, s78
	ds_read_b128 v[188:191], v171 offset:16384
	ds_read_b128 v[198:201], v171 offset:17408
	ds_read_b128 v[202:205], v171 offset:18432
	ds_read_b128 v[206:209], v171 offset:19456
	ds_read_b128 v[210:213], v171 offset:20480
	ds_read_b128 v[214:217], v171 offset:21504
	ds_read_b128 v[218:221], v171 offset:22528
	ds_read_b128 v[230:233], v171 offset:23552
	global_load_lds_dwordx4 v[162:163], off
	s_add_i32 m0, s78, 0x2000
	s_add_u32 s78, s66, 0x40000
	v_lshl_add_u64 v[234:235], s[66:67], 0, v[134:135]
	s_addc_u32 s79, s67, 0
	s_add_i32 s63, s63, s74
	global_load_lds_dwordx4 v[234:235], off
	v_lshl_add_u64 v[236:237], s[78:79], 0, v[192:193]
	s_mov_b32 m0, s63
	v_lshl_add_u64 v[238:239], s[70:71], 0, v[136:137]
	global_load_lds_dwordx4 v[236:237], off
	v_lshl_add_u64 v[236:237], s[78:79], 0, v[134:135]
	s_add_i32 m0, s63, 0x2000
	s_nop 0
	global_load_lds_dwordx4 v[236:237], off
	v_lshl_add_u64 v[236:237], s[70:71], 0, v[138:139]
	s_mov_b32 m0, s75
	s_nop 0
	global_load_lds_dwordx4 v[236:237], off
	s_mov_b32 m0, s81
	s_nop 0
	global_load_lds_dwordx4 v[238:239], off
	s_waitcnt vmcnt(8)
	s_waitcnt lgkmcnt(0)
	s_barrier
	v_mfma_f32_16x16x32_bf16 v[60:63], v[146:149], v[188:191], v[60:63]
	v_mfma_f32_16x16x32_bf16 v[56:59], v[154:157], v[188:191], v[56:59]
	v_mfma_f32_16x16x32_bf16 v[40:43], v[154:157], v[202:205], v[40:43]
	v_mfma_f32_16x16x32_bf16 v[44:47], v[146:149], v[202:205], v[44:47]
	v_mfma_f32_16x16x32_bf16 v[28:31], v[146:149], v[210:213], v[28:31]
	v_mfma_f32_16x16x32_bf16 v[24:27], v[154:157], v[210:213], v[24:27]
	v_mfma_f32_16x16x32_bf16 v[8:11], v[154:157], v[218:221], v[8:11]
	v_mfma_f32_16x16x32_bf16 v[12:15], v[146:149], v[218:221], v[12:15]
	v_mfma_f32_16x16x32_bf16 v[60:63], v[150:153], v[198:201], v[60:63]
	v_mfma_f32_16x16x32_bf16 v[56:59], v[158:161], v[198:201], v[56:59]
	v_mfma_f32_16x16x32_bf16 v[40:43], v[158:161], v[206:209], v[40:43]
	v_mfma_f32_16x16x32_bf16 v[44:47], v[150:153], v[206:209], v[44:47]
	v_mfma_f32_16x16x32_bf16 v[28:31], v[150:153], v[214:217], v[28:31]
	v_mfma_f32_16x16x32_bf16 v[24:27], v[158:161], v[214:217], v[24:27]
	v_mfma_f32_16x16x32_bf16 v[8:11], v[158:161], v[230:233], v[8:11]
	v_mfma_f32_16x16x32_bf16 v[12:15], v[150:153], v[230:233], v[12:15]
	v_mfma_f32_16x16x32_bf16 v[52:55], v[172:175], v[188:191], v[52:55]
	v_mfma_f32_16x16x32_bf16 v[48:51], v[180:183], v[188:191], v[48:51]
	v_mfma_f32_16x16x32_bf16 v[32:35], v[180:183], v[202:205], v[32:35]
	v_mfma_f32_16x16x32_bf16 v[36:39], v[172:175], v[202:205], v[36:39]
	v_mfma_f32_16x16x32_bf16 v[20:23], v[172:175], v[210:213], v[20:23]
	v_mfma_f32_16x16x32_bf16 v[16:19], v[180:183], v[210:213], v[16:19]
	v_mfma_f32_16x16x32_bf16 v[0:3], v[180:183], v[218:221], v[0:3]
	v_mfma_f32_16x16x32_bf16 v[4:7], v[172:175], v[218:221], v[4:7]
	v_mfma_f32_16x16x32_bf16 v[52:55], v[176:179], v[198:201], v[52:55]
	v_mfma_f32_16x16x32_bf16 v[48:51], v[184:187], v[198:201], v[48:51]
	v_mfma_f32_16x16x32_bf16 v[32:35], v[184:187], v[206:209], v[32:35]
	v_mfma_f32_16x16x32_bf16 v[36:39], v[176:179], v[206:209], v[36:39]
	v_mfma_f32_16x16x32_bf16 v[20:23], v[176:179], v[214:217], v[20:23]
	v_mfma_f32_16x16x32_bf16 v[16:19], v[184:187], v[214:217], v[16:19]
	v_mfma_f32_16x16x32_bf16 v[0:3], v[184:187], v[230:233], v[0:3]
	v_mfma_f32_16x16x32_bf16 v[4:7], v[176:179], v[230:233], v[4:7]
	s_barrier
; #define PG8_STAGE(bufoff, gbase, voff) do { _Pragma("unroll") for (int _i = 0; _i < 2; ++_i) \
;         __builtin_amdgcn_global_load_lds((const unsigned*)((const char*)(gbase) + (voff)[_i]), (LAS unsigned*)(lds + (bufoff) + ldsw + _i * 8192), 16, 0, 0); } while (0)
; #define PG8_LDA(dst, b, h) do { _Pragma("unroll") for (int m = 0; m < 4; ++m) _Pragma("unroll") for (int k = 0; k < 2; ++k) dst[m][k] = *(const LAS bf16x8*)(lds + PG8_SA(b, h) + aoff + m * 2048 + k * 1024); } while (0)
; #define PG8_LDB(dst, b, h) do { _Pragma("unroll") for (int n = 0; n < 2; ++n) _Pragma("unroll") for (int k = 0; k < 2; ++k) dst[n][k] = *(const LAS bf16x8*)(lds + PG8_SB(b, h) + boff + n * 2048 + k * 1024); } while (0)
; #define PG8_MMA(ai, bj, At, Bt) do { __builtin_amdgcn_s_setprio(1); _Pragma("unroll") for (int m = 0; m < 4; ++m) _Pragma("unroll") for (int n = 0; n < 2; ++n) _Pragma("unroll") for (int k = 0; k < 2; ++k) \
;         acc[ai][bj][m][n] = __builtin_amdgcn_mfma_f32_16x16x32_bf16(Bt[n][k], At[m][k], acc[ai][bj][m][n], 0, 0, 0); __builtin_amdgcn_s_setprio(0); } while (0)
; #define PG8_WAIT_V(n) asm volatile("s_waitcnt vmcnt(" #n ")" ::: "memory")
; #define PG8_WAIT_L(n) asm volatile("s_waitcnt lgkmcnt(" #n ")" ::: "memory")
; #define PG8_BAR __builtin_amdgcn_s_barrier()
; #define PG8_SCHED __builtin_amdgcn_sched_barrier(0)
; template <class Epi, class Sched>
; __device__ __forceinline__ void gemm_phase(LAS unsigned char* lds, const Gemm g, const Sched& S, const Epi& E, const int tid) {
;     ...
;             PG8_LDB(B0, 1, 0); PG8_LDB(B1, 1, 1); PG8_SCHED; PG8_LDA(At, 1, 0); PG8_STAGE(PG8_SA(0, 1), a2 + hstep, voffA);
;             PG8_WAIT_V(8); PG8_WAIT_L(0); PG8_BAR; PG8_MMA(0, 0, At, B0); PG8_MMA(0, 1, At, B1); PG8_BAR; PG8_SCHED;
	s_add_i32 s63, 0, 0x18000
	v_add_u32_e32 v145, s63, v166
	s_add_i32 s78, 0, 0x1c000
	ds_read_b128 v[146:149], v145
	ds_read_b128 v[150:153], v145 offset:1024
	ds_read_b128 v[154:157], v145 offset:2048
	ds_read_b128 v[158:161], v145 offset:3072
	v_add_u32_e32 v145, s78, v166
	ds_read_b128 v[172:175], v145
	ds_read_b128 v[176:179], v145 offset:1024
	ds_read_b128 v[180:183], v145 offset:2048
	ds_read_b128 v[184:187], v145 offset:3072
	s_add_u32 s70, s70, 0x40000
	s_addc_u32 s71, s71, 0
	s_mov_b32 m0, s82
	v_lshl_add_u64 v[240:241], s[70:71], 0, v[138:139]
	ds_read_b128 v[188:191], v171 offset:32768
	ds_read_b128 v[198:201], v171 offset:33792
	ds_read_b128 v[202:205], v171 offset:34816
	ds_read_b128 v[206:209], v171 offset:35840
	ds_read_b128 v[210:213], v171 offset:36864
	ds_read_b128 v[214:217], v171 offset:37888
	ds_read_b128 v[218:221], v171 offset:38912
	ds_read_b128 v[230:233], v171 offset:39936
	global_load_lds_dwordx4 v[240:241], off
	v_lshl_add_u64 v[240:241], s[70:71], 0, v[136:137]
	s_mov_b32 m0, s83
	s_nop 0
	global_load_lds_dwordx4 v[240:241], off
	s_waitcnt vmcnt(8)
	s_waitcnt lgkmcnt(0)
	s_barrier
	v_mfma_f32_16x16x32_bf16 v[128:131], v[146:149], v[188:191], v[128:131]
	v_mfma_f32_16x16x32_bf16 v[124:127], v[154:157], v[188:191], v[124:127]
	v_mfma_f32_16x16x32_bf16 v[104:107], v[154:157], v[202:205], v[104:107]
	v_mfma_f32_16x16x32_bf16 v[108:111], v[146:149], v[202:205], v[108:111]
	v_mfma_f32_16x16x32_bf16 v[92:95], v[146:149], v[210:213], v[92:95]
	v_mfma_f32_16x16x32_bf16 v[88:91], v[154:157], v[210:213], v[88:91]
	v_mfma_f32_16x16x32_bf16 v[72:75], v[154:157], v[218:221], v[72:75]
	v_mfma_f32_16x16x32_bf16 v[76:79], v[146:149], v[218:221], v[76:79]
	v_mfma_f32_16x16x32_bf16 v[128:131], v[150:153], v[198:201], v[128:131]
	v_mfma_f32_16x16x32_bf16 v[124:127], v[158:161], v[198:201], v[124:127]
	v_mfma_f32_16x16x32_bf16 v[104:107], v[158:161], v[206:209], v[104:107]
	v_mfma_f32_16x16x32_bf16 v[108:111], v[150:153], v[206:209], v[108:111]
	v_mfma_f32_16x16x32_bf16 v[92:95], v[150:153], v[214:217], v[92:95]
	v_mfma_f32_16x16x32_bf16 v[88:91], v[158:161], v[214:217], v[88:91]
	v_mfma_f32_16x16x32_bf16 v[72:75], v[158:161], v[230:233], v[72:75]
	v_mfma_f32_16x16x32_bf16 v[76:79], v[150:153], v[230:233], v[76:79]
	v_mfma_f32_16x16x32_bf16 v[120:123], v[172:175], v[188:191], v[120:123]
	v_mfma_f32_16x16x32_bf16 v[116:119], v[180:183], v[188:191], v[116:119]
	v_mfma_f32_16x16x32_bf16 v[96:99], v[180:183], v[202:205], v[96:99]
	v_mfma_f32_16x16x32_bf16 v[100:103], v[172:175], v[202:205], v[100:103]
	v_mfma_f32_16x16x32_bf16 v[84:87], v[172:175], v[210:213], v[84:87]
	v_mfma_f32_16x16x32_bf16 v[80:83], v[180:183], v[210:213], v[80:83]
	v_mfma_f32_16x16x32_bf16 v[64:67], v[180:183], v[218:221], v[64:67]
	v_mfma_f32_16x16x32_bf16 v[68:71], v[172:175], v[218:221], v[68:71]
	v_mfma_f32_16x16x32_bf16 v[120:123], v[176:179], v[198:201], v[120:123]
	v_mfma_f32_16x16x32_bf16 v[116:119], v[184:187], v[198:201], v[116:119]
	v_mfma_f32_16x16x32_bf16 v[96:99], v[184:187], v[206:209], v[96:99]
	v_mfma_f32_16x16x32_bf16 v[100:103], v[176:179], v[206:209], v[100:103]
	v_mfma_f32_16x16x32_bf16 v[84:87], v[176:179], v[214:217], v[84:87]
	v_mfma_f32_16x16x32_bf16 v[80:83], v[184:187], v[214:217], v[80:83]
	v_mfma_f32_16x16x32_bf16 v[64:67], v[184:187], v[230:233], v[64:67]
	v_mfma_f32_16x16x32_bf16 v[68:71], v[176:179], v[230:233], v[68:71]
	s_barrier
; #define PG8_STAGE(bufoff, gbase, voff) do { _Pragma("unroll") for (int _i = 0; _i < 2; ++_i) \
;         __builtin_amdgcn_global_load_lds((const unsigned*)((const char*)(gbase) + (voff)[_i]), (LAS unsigned*)(lds + (bufoff) + ldsw + _i * 8192), 16, 0, 0); } while (0)
; #define PG8_LDA(dst, b, h) do { _Pragma("unroll") for (int m = 0; m < 4; ++m) _Pragma("unroll") for (int k = 0; k < 2; ++k) dst[m][k] = *(const LAS bf16x8*)(lds + PG8_SA(b, h) + aoff + m * 2048 + k * 1024); } while (0)
; #define PG8_MMA(ai, bj, At, Bt) do { __builtin_amdgcn_s_setprio(1); _Pragma("unroll") for (int m = 0; m < 4; ++m) _Pragma("unroll") for (int n = 0; n < 2; ++n) _Pragma("unroll") for (int k = 0; k < 2; ++k) \
;         acc[ai][bj][m][n] = __builtin_amdgcn_mfma_f32_16x16x32_bf16(Bt[n][k], At[m][k], acc[ai][bj][m][n], 0, 0, 0); __builtin_amdgcn_s_setprio(0); } while (0)
; #define PG8_WAIT_V(n) asm volatile("s_waitcnt vmcnt(" #n ")" ::: "memory")
; #define PG8_WAIT_L(n) asm volatile("s_waitcnt lgkmcnt(" #n ")" ::: "memory")
; #define PG8_BAR __builtin_amdgcn_s_barrier()
; #define PG8_SCHED __builtin_amdgcn_sched_barrier(0)
; template <class Epi, class Sched>
; __device__ __forceinline__ void gemm_phase(LAS unsigned char* lds, const Gemm g, const Sched& S, const Epi& E, const int tid) {
;     ...
;             PG8_LDA(At, 1, 1); PG8_STAGE(PG8_SB(1, 0), b3, voffB); PG8_STAGE(PG8_SB(1, 1), b3 + hstep, voffB); PG8_STAGE(PG8_SA(1, 0), a3, voffA);
;             PG8_WAIT_V(8); PG8_WAIT_L(0); PG8_BAR; PG8_MMA(1, 0, At, B0); PG8_MMA(1, 1, At, B1); PG8_BAR; PG8_SCHED;
;         }
;         if (wr == 0) PG8_BAR;
	s_add_i32 s63, s63, s74
	v_lshl_add_u64 v[162:163], v[162:163], 0, s[68:69]
	s_mov_b32 m0, s63
	ds_read_b128 v[188:191], v171 offset:49152
	ds_read_b128 v[198:201], v171 offset:50176
	ds_read_b128 v[202:205], v171 offset:51200
	ds_read_b128 v[206:209], v171 offset:52224
	ds_read_b128 v[210:213], v171 offset:53248
	ds_read_b128 v[214:217], v171 offset:54272
	ds_read_b128 v[218:221], v171 offset:55296
	ds_read_b128 v[230:233], v171 offset:56320
	global_load_lds_dwordx4 v[162:163], off
	s_add_i32 m0, s63, 0x2000
	s_add_u32 s66, s66, 0x40080
	v_lshl_add_u64 v[162:163], v[234:235], 0, s[68:69]
	s_addc_u32 s67, s67, 0
	s_add_i32 s63, s78, s74
	global_load_lds_dwordx4 v[162:163], off
	v_lshl_add_u64 v[162:163], s[66:67], 0, v[192:193]
	s_mov_b32 m0, s63
	s_nop 0
	global_load_lds_dwordx4 v[162:163], off
	v_lshl_add_u64 v[162:163], s[66:67], 0, v[134:135]
	s_add_i32 m0, s63, 0x2000
	s_nop 0
	global_load_lds_dwordx4 v[162:163], off
	v_lshl_add_u64 v[162:163], v[236:237], 0, s[68:69]
	s_mov_b32 m0, s93
	s_nop 0
	global_load_lds_dwordx4 v[162:163], off
	v_lshl_add_u64 v[162:163], v[238:239], 0, s[68:69]
	s_mov_b32 m0, s94
	s_nop 0
	global_load_lds_dwordx4 v[162:163], off
	s_waitcnt vmcnt(8)
	s_waitcnt lgkmcnt(0)
	s_barrier
	v_mfma_f32_16x16x32_bf16 v[60:63], v[146:149], v[188:191], v[60:63]
	v_mfma_f32_16x16x32_bf16 v[56:59], v[154:157], v[188:191], v[56:59]
	v_mfma_f32_16x16x32_bf16 v[40:43], v[154:157], v[202:205], v[40:43]
	v_mfma_f32_16x16x32_bf16 v[44:47], v[146:149], v[202:205], v[44:47]
	v_mfma_f32_16x16x32_bf16 v[28:31], v[146:149], v[210:213], v[28:31]
	v_mfma_f32_16x16x32_bf16 v[24:27], v[154:157], v[210:213], v[24:27]
	v_mfma_f32_16x16x32_bf16 v[8:11], v[154:157], v[218:221], v[8:11]
	v_mfma_f32_16x16x32_bf16 v[12:15], v[146:149], v[218:221], v[12:15]
	v_mfma_f32_16x16x32_bf16 v[60:63], v[150:153], v[198:201], v[60:63]
	v_mfma_f32_16x16x32_bf16 v[56:59], v[158:161], v[198:201], v[56:59]
	v_mfma_f32_16x16x32_bf16 v[40:43], v[158:161], v[206:209], v[40:43]
	v_mfma_f32_16x16x32_bf16 v[44:47], v[150:153], v[206:209], v[44:47]
	v_mfma_f32_16x16x32_bf16 v[28:31], v[150:153], v[214:217], v[28:31]
	v_mfma_f32_16x16x32_bf16 v[24:27], v[158:161], v[214:217], v[24:27]
	v_mfma_f32_16x16x32_bf16 v[8:11], v[158:161], v[230:233], v[8:11]
	v_mfma_f32_16x16x32_bf16 v[12:15], v[150:153], v[230:233], v[12:15]
	v_mfma_f32_16x16x32_bf16 v[52:55], v[172:175], v[188:191], v[52:55]
	v_mfma_f32_16x16x32_bf16 v[48:51], v[180:183], v[188:191], v[48:51]
	v_mfma_f32_16x16x32_bf16 v[32:35], v[180:183], v[202:205], v[32:35]
	v_mfma_f32_16x16x32_bf16 v[36:39], v[172:175], v[202:205], v[36:39]
	v_mfma_f32_16x16x32_bf16 v[20:23], v[172:175], v[210:213], v[20:23]
	v_mfma_f32_16x16x32_bf16 v[16:19], v[180:183], v[210:213], v[16:19]
	v_mfma_f32_16x16x32_bf16 v[0:3], v[180:183], v[218:221], v[0:3]
	v_mfma_f32_16x16x32_bf16 v[4:7], v[172:175], v[218:221], v[4:7]
	v_mfma_f32_16x16x32_bf16 v[52:55], v[176:179], v[198:201], v[52:55]
	v_mfma_f32_16x16x32_bf16 v[48:51], v[184:187], v[198:201], v[48:51]
	v_mfma_f32_16x16x32_bf16 v[32:35], v[184:187], v[206:209], v[32:35]
	v_mfma_f32_16x16x32_bf16 v[36:39], v[176:179], v[206:209], v[36:39]
	v_mfma_f32_16x16x32_bf16 v[20:23], v[176:179], v[214:217], v[20:23]
	v_mfma_f32_16x16x32_bf16 v[16:19], v[184:187], v[214:217], v[16:19]
	v_mfma_f32_16x16x32_bf16 v[0:3], v[184:187], v[230:233], v[0:3]
	v_mfma_f32_16x16x32_bf16 v[4:7], v[176:179], v[230:233], v[4:7]
	s_barrier
	s_add_i32 s61, s61, 2
	s_add_u32 s64, s64, 0x100
	s_addc_u32 s65, s65, 0
	s_add_u32 s59, s59, 0x100
	s_addc_u32 s60, s60, 0
	s_cmp_gt_u32 s61, 13
	s_cbranch_scc0 .LBB0_168
	s_and_b64 vcc, exec, s[50:51]
	s_cbranch_vccz .LBB0_171
	s_barrier

;     __device__ __forceinline__ Pre prefetch(const Unit& u, int tid) const { return prenorm_load(stats, u.pn * BM, sW + (size_t)(u.pn >> 4) * SW_ROWS + u.pm * BM, tid); }
;     __device__ __forceinline__ Pre prefetch(const Unit& u, int tid) const { return prenorm_load(stats, u.pm * BM, sW + (size_t)(u.pm >> 4) * SW_ROWS + u.pn * BM, tid); }
;     __device__ __forceinline__ Pre prefetch(const Unit& u, int tid) const { return prenorm_load(stats, u.pm * BM, sW + (size_t)(u.pm >> 4) * SW_ROWS + u.pn * BM, tid); }
; #define PG8_STAGE(bufoff, gbase, voff) do { _Pragma("unroll") for (int _i = 0; _i < 2; ++_i) \
;         __builtin_amdgcn_global_load_lds((const unsigned*)((const char*)(gbase) + (voff)[_i]), (LAS unsigned*)(lds + (bufoff) + ldsw + _i * 8192), 16, 0, 0); } while (0)
; #define PG8_LDA(dst, b, h) do { _Pragma("unroll") for (int m = 0; m < 4; ++m) _Pragma("unroll") for (int k = 0; k < 2; ++k) dst[m][k] = *(const LAS bf16x8*)(lds + PG8_SA(b, h) + aoff + m * 2048 + k * 1024); } while (0)
; #define PG8_WAIT_V(n) asm volatile("s_waitcnt vmcnt(" #n ")" ::: "memory")
; #define PG8_WAIT_L(n) asm volatile("s_waitcnt lgkmcnt(" #n ")" ::: "memory")
; template <class Epi, class Sched>
; __device__ __forceinline__ void gemm_phase(LAS unsigned char* lds, const Gemm g, const Sched& S, const Epi& E, const int tid) {
;     ...
;         const bool has_next = S.next(ui + 1, nxt);
;         const char* nA = has_next ? (const char*)g.A + (size_t)nxt.pm * tstep : cA; const char* nB = has_next ? (const char*)g.Bt + (size_t)nxt.pn * tstep : cB;
;         const typename Epi::Pre pre = E.prefetch(cur, tid);
;         for (int t = 0; t < nt; t += 2) {
;             const bool last = (t == nt - 2);
;             const char* a1 = cA + (size_t)(t + 1) * kstep;
;             const char* a2 = last ? nA : cA + (size_t)(t + 2) * kstep; const char* b2 = last ? nB : cB + (size_t)(t + 2) * kstep;
;             const char* a3 = a2 + kstep; const char* b3 = b2 + kstep;
;             PG8_LDB(B0, 0, 0); PG8_LDB(B1, 0, 1); PG8_SCHED; PG8_LDA(At, 0, 0); PG8_STAGE(PG8_SA(1, 1), a1 + hstep, voffA);
;             PG8_WAIT_V(8); PG8_WAIT_L(0); PG8_BAR; PG8_MMA(0, 0, At, B0); PG8_MMA(0, 1, At, B1); PG8_BAR; PG8_SCHED;
;             PG8_LDA(At, 0, 1); PG8_STAGE(PG8_SB(0, 0), b2, voffB); PG8_STAGE(PG8_SB(0, 1), b2 + hstep, voffB); PG8_STAGE(PG8_SA(0, 0), a2, voffA);
.LBB0_265:
	s_or_b64 exec, exec, s[38:39]
	s_ashr_i32 s23, s22, 31
	s_lshl_b64 s[38:39], s[22:23], 19
	s_add_u32 s38, s46, s38
	s_addc_u32 s39, s47, s39
	s_and_b64 s[56:57], s[4:5], exec
	s_cselect_b32 s23, s39, s7
	s_cselect_b32 s56, s38, s6
	s_ashr_i32 s55, s54, 31
	s_lshl_b64 s[58:59], s[54:55], 19
	s_add_u32 s62, s35, s58
	s_addc_u32 s63, s84, s59
	s_and_b64 s[58:59], s[4:5], exec
	s_cselect_b32 s55, s63, s65
	s_cselect_b32 s57, s62, s64
	s_add_u32 s6, s6, 0x40080
	s_addc_u32 s7, s7, 0
	s_add_u32 s58, s64, 0x100
	s_addc_u32 s59, s65, 0
	s_mov_b32 s60, -2
	s_add_u32 s61, s6, 0xfffc0080
	s_addc_u32 s64, s7, -1
	s_add_i32 s70, 0, 0x10000
	s_cmp_eq_u32 s60, 12
	s_cselect_b32 s67, s23, s64
	s_cselect_b32 s66, s56, s61
	v_add_u32_e32 v81, s70, v216
	s_cselect_b32 s65, s55, s59
	s_cselect_b32 s64, s57, s58
	s_add_i32 s61, 0, 0x14000
	ds_read_b128 v[88:91], v81
	ds_read_b128 v[92:95], v81 offset:1024
	ds_read_b128 v[144:147], v81 offset:2048
	ds_read_b128 v[148:151], v81 offset:3072
	v_add_u32_e32 v81, s61, v216
	ds_read_b128 v[152:155], v81
	ds_read_b128 v[156:159], v81 offset:1024
	ds_read_b128 v[178:181], v81 offset:2048
	ds_read_b128 v[182:185], v81 offset:3072
	v_lshl_add_u64 v[82:83], s[6:7], 0, v[174:175]
	s_add_i32 m0, s73, 0xc000
	ds_read_b128 v[186:189], v230
	ds_read_b128 v[198:201], v230 offset:1024
	ds_read_b128 v[202:205], v230 offset:2048
	ds_read_b128 v[206:209], v230 offset:3072
	ds_read_b128 v[234:237], v230 offset:4096
	ds_read_b128 v[238:241], v230 offset:5120
	ds_read_b128 v[242:245], v230 offset:6144
	ds_read_b128 v[246:249], v230 offset:7168
	global_load_lds_dwordx4 v[82:83], off
	v_lshl_add_u64 v[82:83], s[6:7], 0, v[176:177]
	s_add_i32 m0, s73, 0xe000
	s_nop 0
	global_load_lds_dwordx4 v[82:83], off
	s_waitcnt vmcnt(8)
	s_waitcnt lgkmcnt(0)
	s_barrier
	v_mfma_f32_16x16x32_bf16 v[140:143], v[88:91], v[186:189], 0
	v_mfma_f32_16x16x32_bf16 v[136:139], v[144:147], v[186:189], 0
	v_mfma_f32_16x16x32_bf16 v[120:123], v[144:147], v[202:205], 0
	v_mfma_f32_16x16x32_bf16 v[124:127], v[88:91], v[202:205], 0
	v_mfma_f32_16x16x32_bf16 v[108:111], v[88:91], v[234:237], 0
	v_mfma_f32_16x16x32_bf16 v[104:107], v[144:147], v[234:237], 0
	v_mfma_f32_16x16x32_bf16 v[76:79], v[144:147], v[242:245], 0
	v_mfma_f32_16x16x32_bf16 v[82:85], v[88:91], v[242:245], 0
	v_mfma_f32_16x16x32_bf16 v[140:143], v[92:95], v[198:201], v[140:143]
	v_mfma_f32_16x16x32_bf16 v[136:139], v[148:151], v[198:201], v[136:139]
	v_mfma_f32_16x16x32_bf16 v[120:123], v[148:151], v[206:209], v[120:123]
	v_mfma_f32_16x16x32_bf16 v[124:127], v[92:95], v[206:209], v[124:127]
	v_mfma_f32_16x16x32_bf16 v[108:111], v[92:95], v[238:241], v[108:111]
	v_mfma_f32_16x16x32_bf16 v[104:107], v[148:151], v[238:241], v[104:107]
	v_mfma_f32_16x16x32_bf16 v[76:79], v[148:151], v[246:249], v[76:79]
	v_mfma_f32_16x16x32_bf16 v[82:85], v[92:95], v[246:249], v[82:85]
	v_mfma_f32_16x16x32_bf16 v[132:135], v[152:155], v[186:189], 0
	v_mfma_f32_16x16x32_bf16 v[128:131], v[178:181], v[186:189], 0
	v_mfma_f32_16x16x32_bf16 v[112:115], v[178:181], v[202:205], 0
	v_mfma_f32_16x16x32_bf16 v[116:119], v[152:155], v[202:205], 0
	v_mfma_f32_16x16x32_bf16 v[100:103], v[152:155], v[234:237], 0
	v_mfma_f32_16x16x32_bf16 v[96:99], v[178:181], v[234:237], 0
	v_mfma_f32_16x16x32_bf16 v[64:67], v[178:181], v[242:245], 0
	v_mfma_f32_16x16x32_bf16 v[68:71], v[152:155], v[242:245], 0
	v_mfma_f32_16x16x32_bf16 v[132:135], v[156:159], v[198:201], v[132:135]
	v_mfma_f32_16x16x32_bf16 v[128:131], v[182:185], v[198:201], v[128:131]
	v_mfma_f32_16x16x32_bf16 v[112:115], v[182:185], v[206:209], v[112:115]
	v_mfma_f32_16x16x32_bf16 v[116:119], v[156:159], v[206:209], v[116:119]
	v_mfma_f32_16x16x32_bf16 v[100:103], v[156:159], v[238:241], v[100:103]
	v_mfma_f32_16x16x32_bf16 v[96:99], v[182:185], v[238:241], v[96:99]
	v_mfma_f32_16x16x32_bf16 v[64:67], v[182:185], v[246:249], v[64:67]
	v_mfma_f32_16x16x32_bf16 v[68:71], v[156:159], v[246:249], v[68:71]
	s_barrier
	s_add_i32 s70, s70, s12
	v_lshl_add_u64 v[190:191], s[64:65], 0, v[164:165]
	s_mov_b32 m0, s70
	ds_read_b128 v[186:189], v230 offset:16384
	ds_read_b128 v[198:201], v230 offset:17408
	ds_read_b128 v[202:205], v230 offset:18432
	ds_read_b128 v[206:209], v230 offset:19456
	ds_read_b128 v[234:237], v230 offset:20480
	ds_read_b128 v[238:241], v230 offset:21504
	ds_read_b128 v[242:245], v230 offset:22528
	ds_read_b128 v[246:249], v230 offset:23552
	global_load_lds_dwordx4 v[190:191], off
	s_add_i32 m0, s70, 0x2000
	s_add_u32 s70, s64, 0x40000
	v_lshl_add_u64 v[250:251], s[64:65], 0, v[168:169]
	s_addc_u32 s71, s65, 0
	s_add_i32 s61, s61, s12
	global_load_lds_dwordx4 v[250:251], off
	v_lshl_add_u64 v[86:87], s[70:71], 0, v[164:165]
	s_mov_b32 m0, s61
	v_lshl_add_u64 v[224:225], s[66:67], 0, v[162:163]
	global_load_lds_dwordx4 v[86:87], off
	v_lshl_add_u64 v[86:87], s[70:71], 0, v[168:169]
	s_add_i32 m0, s61, 0x2000
	v_lshl_add_u64 v[226:227], s[66:67], 0, v[166:167]
	global_load_lds_dwordx4 v[86:87], off
	s_mov_b32 m0, s73
	s_nop 0
	global_load_lds_dwordx4 v[224:225], off
	s_mov_b32 m0, s74
	s_nop 0
	global_load_lds_dwordx4 v[226:227], off
	s_waitcnt vmcnt(8)
	s_waitcnt lgkmcnt(0)
	s_barrier
; #define PG8_STAGE(bufoff, gbase, voff) do { _Pragma("unroll") for (int _i = 0; _i < 2; ++_i) \
;         __builtin_amdgcn_global_load_lds((const unsigned*)((const char*)(gbase) + (voff)[_i]), (LAS unsigned*)(lds + (bufoff) + ldsw + _i * 8192), 16, 0, 0); } while (0)
; #define PG8_LDA(dst, b, h) do { _Pragma("unroll") for (int m = 0; m < 4; ++m) _Pragma("unroll") for (int k = 0; k < 2; ++k) dst[m][k] = *(const LAS bf16x8*)(lds + PG8_SA(b, h) + aoff + m * 2048 + k * 1024); } while (0)
; #define PG8_LDB(dst, b, h) do { _Pragma("unroll") for (int n = 0; n < 2; ++n) _Pragma("unroll") for (int k = 0; k < 2; ++k) dst[n][k] = *(const LAS bf16x8*)(lds + PG8_SB(b, h) + boff + n * 2048 + k * 1024); } while (0)
; #define PG8_MMA(ai, bj, At, Bt) do { __builtin_amdgcn_s_setprio(1); _Pragma("unroll") for (int m = 0; m < 4; ++m) _Pragma("unroll") for (int n = 0; n < 2; ++n) _Pragma("unroll") for (int k = 0; k < 2; ++k) \
;         acc[ai][bj][m][n] = __builtin_amdgcn_mfma_f32_16x16x32_bf16(Bt[n][k], At[m][k], acc[ai][bj][m][n], 0, 0, 0); __builtin_amdgcn_s_setprio(0); } while (0)
; #define PG8_WAIT_V(n) asm volatile("s_waitcnt vmcnt(" #n ")" ::: "memory")
; #define PG8_WAIT_L(n) asm volatile("s_waitcnt lgkmcnt(" #n ")" ::: "memory")
; #define PG8_BAR __builtin_amdgcn_s_barrier()
; #define PG8_SCHED __builtin_amdgcn_sched_barrier(0)
; template <class Epi, class Sched>
; __device__ __forceinline__ void gemm_phase(LAS unsigned char* lds, const Gemm g, const Sched& S, const Epi& E, const int tid) {
;     ...
;             PG8_WAIT_V(8); PG8_WAIT_L(0); PG8_BAR; PG8_MMA(1, 0, At, B0); PG8_MMA(1, 1, At, B1); PG8_BAR; PG8_SCHED;
;             PG8_LDB(B0, 1, 0); PG8_LDB(B1, 1, 1); PG8_SCHED; PG8_LDA(At, 1, 0); PG8_STAGE(PG8_SA(0, 1), a2 + hstep, voffA);
;             PG8_WAIT_V(8); PG8_WAIT_L(0); PG8_BAR; PG8_MMA(0, 0, At, B0); PG8_MMA(0, 1, At, B1); PG8_BAR; PG8_SCHED;
	v_mfma_f32_16x16x32_bf16 v[60:63], v[88:91], v[186:189], 0
	v_mfma_f32_16x16x32_bf16 v[56:59], v[144:147], v[186:189], 0
	v_mfma_f32_16x16x32_bf16 v[40:43], v[144:147], v[202:205], 0
	v_mfma_f32_16x16x32_bf16 v[44:47], v[88:91], v[202:205], 0
	v_mfma_f32_16x16x32_bf16 v[28:31], v[88:91], v[234:237], 0
	v_mfma_f32_16x16x32_bf16 v[24:27], v[144:147], v[234:237], 0
	v_mfma_f32_16x16x32_bf16 v[8:11], v[144:147], v[242:245], 0
	v_mfma_f32_16x16x32_bf16 v[12:15], v[88:91], v[242:245], 0
	v_mfma_f32_16x16x32_bf16 v[60:63], v[92:95], v[198:201], v[60:63]
	v_mfma_f32_16x16x32_bf16 v[56:59], v[148:151], v[198:201], v[56:59]
	v_mfma_f32_16x16x32_bf16 v[40:43], v[148:151], v[206:209], v[40:43]
	v_mfma_f32_16x16x32_bf16 v[44:47], v[92:95], v[206:209], v[44:47]
	v_mfma_f32_16x16x32_bf16 v[28:31], v[92:95], v[238:241], v[28:31]
	v_mfma_f32_16x16x32_bf16 v[24:27], v[148:151], v[238:241], v[24:27]
	v_mfma_f32_16x16x32_bf16 v[8:11], v[148:151], v[246:249], v[8:11]
	v_mfma_f32_16x16x32_bf16 v[12:15], v[92:95], v[246:249], v[12:15]
	v_mfma_f32_16x16x32_bf16 v[52:55], v[152:155], v[186:189], 0
	v_mfma_f32_16x16x32_bf16 v[48:51], v[178:181], v[186:189], 0
	v_mfma_f32_16x16x32_bf16 v[32:35], v[178:181], v[202:205], 0
	v_mfma_f32_16x16x32_bf16 v[36:39], v[152:155], v[202:205], 0
	v_mfma_f32_16x16x32_bf16 v[20:23], v[152:155], v[234:237], 0
	v_mfma_f32_16x16x32_bf16 v[16:19], v[178:181], v[234:237], 0
	v_mfma_f32_16x16x32_bf16 v[0:3], v[178:181], v[242:245], 0
	v_mfma_f32_16x16x32_bf16 v[4:7], v[152:155], v[242:245], 0
	v_mfma_f32_16x16x32_bf16 v[52:55], v[156:159], v[198:201], v[52:55]
	v_mfma_f32_16x16x32_bf16 v[48:51], v[182:185], v[198:201], v[48:51]
	v_mfma_f32_16x16x32_bf16 v[32:35], v[182:185], v[206:209], v[32:35]
	v_mfma_f32_16x16x32_bf16 v[36:39], v[156:159], v[206:209], v[36:39]
	v_mfma_f32_16x16x32_bf16 v[20:23], v[156:159], v[238:241], v[20:23]
	v_mfma_f32_16x16x32_bf16 v[16:19], v[182:185], v[238:241], v[16:19]
	v_mfma_f32_16x16x32_bf16 v[0:3], v[182:185], v[246:249], v[0:3]
	v_mfma_f32_16x16x32_bf16 v[4:7], v[156:159], v[246:249], v[4:7]
	s_barrier
	s_add_i32 s61, 0, 0x18000
	v_add_u32_e32 v81, s61, v216
	s_add_i32 s70, 0, 0x1c000
	ds_read_b128 v[88:91], v81
	ds_read_b128 v[92:95], v81 offset:1024
	ds_read_b128 v[144:147], v81 offset:2048
	ds_read_b128 v[148:151], v81 offset:3072
	v_add_u32_e32 v81, s70, v216
	ds_read_b128 v[152:155], v81
	ds_read_b128 v[156:159], v81 offset:1024
	ds_read_b128 v[178:181], v81 offset:2048
	ds_read_b128 v[182:185], v81 offset:3072
	s_add_u32 s66, s66, 0x40000
	s_addc_u32 s67, s67, 0
	s_mov_b32 m0, s75
	v_lshl_add_u64 v[86:87], s[66:67], 0, v[162:163]
	ds_read_b128 v[186:189], v230 offset:32768
	ds_read_b128 v[198:201], v230 offset:33792
	ds_read_b128 v[202:205], v230 offset:34816
	ds_read_b128 v[206:209], v230 offset:35840
	ds_read_b128 v[234:237], v230 offset:36864
	ds_read_b128 v[238:241], v230 offset:37888
	ds_read_b128 v[242:245], v230 offset:38912
	ds_read_b128 v[246:249], v230 offset:39936
	global_load_lds_dwordx4 v[86:87], off
	v_lshl_add_u64 v[86:87], s[66:67], 0, v[166:167]
	s_mov_b32 m0, s81
	s_nop 0
	global_load_lds_dwordx4 v[86:87], off
	s_waitcnt vmcnt(8)
	s_waitcnt lgkmcnt(0)
	s_barrier
	v_mfma_f32_16x16x32_bf16 v[140:143], v[88:91], v[186:189], v[140:143]
	v_mfma_f32_16x16x32_bf16 v[136:139], v[144:147], v[186:189], v[136:139]
	v_mfma_f32_16x16x32_bf16 v[120:123], v[144:147], v[202:205], v[120:123]
	v_mfma_f32_16x16x32_bf16 v[124:127], v[88:91], v[202:205], v[124:127]
	v_mfma_f32_16x16x32_bf16 v[108:111], v[88:91], v[234:237], v[108:111]
	v_mfma_f32_16x16x32_bf16 v[104:107], v[144:147], v[234:237], v[104:107]
	v_mfma_f32_16x16x32_bf16 v[76:79], v[144:147], v[242:245], v[76:79]
	v_mfma_f32_16x16x32_bf16 v[82:85], v[88:91], v[242:245], v[82:85]
	v_mfma_f32_16x16x32_bf16 v[140:143], v[92:95], v[198:201], v[140:143]
	v_mfma_f32_16x16x32_bf16 v[136:139], v[148:151], v[198:201], v[136:139]
	v_mfma_f32_16x16x32_bf16 v[120:123], v[148:151], v[206:209], v[120:123]
	v_mfma_f32_16x16x32_bf16 v[124:127], v[92:95], v[206:209], v[124:127]
	v_mfma_f32_16x16x32_bf16 v[108:111], v[92:95], v[238:241], v[108:111]
	v_mfma_f32_16x16x32_bf16 v[104:107], v[148:151], v[238:241], v[104:107]
	v_mfma_f32_16x16x32_bf16 v[76:79], v[148:151], v[246:249], v[76:79]
	v_mfma_f32_16x16x32_bf16 v[84:87], v[92:95], v[246:249], v[82:85]
	v_mfma_f32_16x16x32_bf16 v[132:135], v[152:155], v[186:189], v[132:135]
	v_mfma_f32_16x16x32_bf16 v[128:131], v[178:181], v[186:189], v[128:131]
	v_mfma_f32_16x16x32_bf16 v[112:115], v[178:181], v[202:205], v[112:115]
	v_mfma_f32_16x16x32_bf16 v[116:119], v[152:155], v[202:205], v[116:119]
	v_mfma_f32_16x16x32_bf16 v[100:103], v[152:155], v[234:237], v[100:103]
	v_mfma_f32_16x16x32_bf16 v[96:99], v[178:181], v[234:237], v[96:99]
	v_mfma_f32_16x16x32_bf16 v[64:67], v[178:181], v[242:245], v[64:67]
	v_mfma_f32_16x16x32_bf16 v[68:71], v[152:155], v[242:245], v[68:71]
	v_mfma_f32_16x16x32_bf16 v[132:135], v[156:159], v[198:201], v[132:135]
	v_mfma_f32_16x16x32_bf16 v[128:131], v[182:185], v[198:201], v[128:131]
	v_mfma_f32_16x16x32_bf16 v[112:115], v[182:185], v[206:209], v[112:115]
	v_mfma_f32_16x16x32_bf16 v[116:119], v[156:159], v[206:209], v[116:119]
	v_mfma_f32_16x16x32_bf16 v[100:103], v[156:159], v[238:241], v[100:103]
	v_mfma_f32_16x16x32_bf16 v[96:99], v[182:185], v[238:241], v[96:99]
	v_mfma_f32_16x16x32_bf16 v[64:67], v[182:185], v[246:249], v[64:67]
	v_mfma_f32_16x16x32_bf16 v[68:71], v[156:159], v[246:249], v[68:71]
	s_barrier
; #define PG8_STAGE(bufoff, gbase, voff) do { _Pragma("unroll") for (int _i = 0; _i < 2; ++_i) \
;         __builtin_amdgcn_global_load_lds((const unsigned*)((const char*)(gbase) + (voff)[_i]), (LAS unsigned*)(lds + (bufoff) + ldsw + _i * 8192), 16, 0, 0); } while (0)
; #define PG8_LDA(dst, b, h) do { _Pragma("unroll") for (int m = 0; m < 4; ++m) _Pragma("unroll") for (int k = 0; k < 2; ++k) dst[m][k] = *(const LAS bf16x8*)(lds + PG8_SA(b, h) + aoff + m * 2048 + k * 1024); } while (0)
; #define PG8_LDB(dst, b, h) do { _Pragma("unroll") for (int n = 0; n < 2; ++n) _Pragma("unroll") for (int k = 0; k < 2; ++k) dst[n][k] = *(const LAS bf16x8*)(lds + PG8_SB(b, h) + boff + n * 2048 + k * 1024); } while (0)
; #define PG8_WAIT_V(n) asm volatile("s_waitcnt vmcnt(" #n ")" ::: "memory")
; #define PG8_BAR __builtin_amdgcn_s_barrier()
; template <class Epi, class Sched>
; __device__ __forceinline__ void gemm_phase(LAS unsigned char* lds, const Gemm g, const Sched& S, const Epi& E, const int tid) {
;     ...
;         for (int t = 0; t < nt; t += 2) {
;             const bool last = (t == nt - 2);
;             const char* a1 = cA + (size_t)(t + 1) * kstep;
;             const char* a2 = last ? nA : cA + (size_t)(t + 2) * kstep; const char* b2 = last ? nB : cB + (size_t)(t + 2) * kstep;
;             const char* a3 = a2 + kstep; const char* b3 = b2 + kstep;
;             PG8_LDB(B0, 0, 0); PG8_LDB(B1, 0, 1); PG8_SCHED; PG8_LDA(At, 0, 0); PG8_STAGE(PG8_SA(1, 1), a1 + hstep, voffA);
;             PG8_WAIT_V(8); PG8_WAIT_L(0); PG8_BAR; PG8_MMA(0, 0, At, B0); PG8_MMA(0, 1, At, B1); PG8_BAR; PG8_SCHED;
;             PG8_LDA(At, 0, 1); PG8_STAGE(PG8_SB(0, 0), b2, voffB); PG8_STAGE(PG8_SB(0, 1), b2 + hstep, voffB); PG8_STAGE(PG8_SA(0, 0), a2, voffA);
;             PG8_WAIT_V(8); PG8_WAIT_L(0); PG8_BAR; PG8_MMA(1, 0, At, B0); PG8_MMA(1, 1, At, B1); PG8_BAR; PG8_SCHED;
;             PG8_LDB(B0, 1, 0); PG8_LDB(B1, 1, 1); PG8_SCHED; PG8_LDA(At, 1, 0); PG8_STAGE(PG8_SA(0, 1), a2 + hstep, voffA);
;             PG8_WAIT_V(8); PG8_WAIT_L(0); PG8_BAR; PG8_MMA(0, 0, At, B0); PG8_MMA(0, 1, At, B1); PG8_BAR; PG8_SCHED;
;             PG8_LDA(At, 1, 1); PG8_STAGE(PG8_SB(1, 0), b3, voffB); PG8_STAGE(PG8_SB(1, 1), b3 + hstep, voffB); PG8_STAGE(PG8_SA(1, 0), a3, voffA);
;             PG8_WAIT_V(8); PG8_WAIT_L(0); PG8_BAR; PG8_MMA(1, 0, At, B0); PG8_MMA(1, 1, At, B1); PG8_BAR; PG8_SCHED;
	s_add_i32 s61, s61, s12
	v_lshl_add_u64 v[82:83], v[190:191], 0, s[68:69]
	s_mov_b32 m0, s61
	ds_read_b128 v[186:189], v230 offset:49152
	ds_read_b128 v[198:201], v230 offset:50176
	ds_read_b128 v[202:205], v230 offset:51200
	ds_read_b128 v[206:209], v230 offset:52224
	ds_read_b128 v[234:237], v230 offset:53248
	ds_read_b128 v[238:241], v230 offset:54272
	ds_read_b128 v[242:245], v230 offset:55296
	ds_read_b128 v[246:249], v230 offset:56320
	global_load_lds_dwordx4 v[82:83], off
	s_add_i32 m0, s61, 0x2000
	s_add_u32 s64, s64, 0x40080
	v_lshl_add_u64 v[82:83], v[250:251], 0, s[68:69]
	s_addc_u32 s65, s65, 0
	s_add_i32 s61, s70, s12
	global_load_lds_dwordx4 v[82:83], off
	v_lshl_add_u64 v[82:83], s[64:65], 0, v[164:165]
	s_mov_b32 m0, s61
	s_nop 0
	global_load_lds_dwordx4 v[82:83], off
	v_lshl_add_u64 v[82:83], s[64:65], 0, v[168:169]
	s_add_i32 m0, s61, 0x2000
	s_nop 0
	global_load_lds_dwordx4 v[82:83], off
	v_lshl_add_u64 v[82:83], v[224:225], 0, s[68:69]
	s_mov_b32 m0, s82
	s_nop 0
	global_load_lds_dwordx4 v[82:83], off
	v_lshl_add_u64 v[82:83], v[226:227], 0, s[68:69]
	s_mov_b32 m0, s83
	s_nop 0
	global_load_lds_dwordx4 v[82:83], off
	s_waitcnt vmcnt(8)
	s_waitcnt lgkmcnt(0)
	s_barrier
	v_mfma_f32_16x16x32_bf16 v[60:63], v[88:91], v[186:189], v[60:63]
	v_mfma_f32_16x16x32_bf16 v[56:59], v[144:147], v[186:189], v[56:59]
	v_mfma_f32_16x16x32_bf16 v[40:43], v[144:147], v[202:205], v[40:43]
	v_mfma_f32_16x16x32_bf16 v[44:47], v[88:91], v[202:205], v[44:47]
	v_mfma_f32_16x16x32_bf16 v[28:31], v[88:91], v[234:237], v[28:31]
	v_mfma_f32_16x16x32_bf16 v[24:27], v[144:147], v[234:237], v[24:27]
	v_mfma_f32_16x16x32_bf16 v[8:11], v[144:147], v[242:245], v[8:11]
	v_mfma_f32_16x16x32_bf16 v[12:15], v[88:91], v[242:245], v[12:15]
	v_mfma_f32_16x16x32_bf16 v[60:63], v[92:95], v[198:201], v[60:63]
	v_mfma_f32_16x16x32_bf16 v[56:59], v[148:151], v[198:201], v[56:59]
	v_mfma_f32_16x16x32_bf16 v[40:43], v[148:151], v[206:209], v[40:43]
	v_mfma_f32_16x16x32_bf16 v[44:47], v[92:95], v[206:209], v[44:47]
	v_mfma_f32_16x16x32_bf16 v[28:31], v[92:95], v[238:241], v[28:31]
	v_mfma_f32_16x16x32_bf16 v[24:27], v[148:151], v[238:241], v[24:27]
	v_mfma_f32_16x16x32_bf16 v[8:11], v[148:151], v[246:249], v[8:11]
	v_mfma_f32_16x16x32_bf16 v[12:15], v[92:95], v[246:249], v[12:15]
	v_mfma_f32_16x16x32_bf16 v[52:55], v[152:155], v[186:189], v[52:55]
	v_mfma_f32_16x16x32_bf16 v[48:51], v[178:181], v[186:189], v[48:51]
	v_mfma_f32_16x16x32_bf16 v[32:35], v[178:181], v[202:205], v[32:35]
	v_mfma_f32_16x16x32_bf16 v[36:39], v[152:155], v[202:205], v[36:39]
	v_mfma_f32_16x16x32_bf16 v[20:23], v[152:155], v[234:237], v[20:23]
	v_mfma_f32_16x16x32_bf16 v[16:19], v[178:181], v[234:237], v[16:19]
	v_mfma_f32_16x16x32_bf16 v[0:3], v[178:181], v[242:245], v[0:3]
	v_mfma_f32_16x16x32_bf16 v[4:7], v[152:155], v[242:245], v[4:7]
	v_mfma_f32_16x16x32_bf16 v[52:55], v[156:159], v[198:201], v[52:55]
	v_mfma_f32_16x16x32_bf16 v[48:51], v[182:185], v[198:201], v[48:51]
	v_mfma_f32_16x16x32_bf16 v[32:35], v[182:185], v[206:209], v[32:35]
	v_mfma_f32_16x16x32_bf16 v[36:39], v[156:159], v[206:209], v[36:39]
	v_mfma_f32_16x16x32_bf16 v[20:23], v[156:159], v[238:241], v[20:23]
	v_mfma_f32_16x16x32_bf16 v[16:19], v[182:185], v[238:241], v[16:19]
	v_mfma_f32_16x16x32_bf16 v[0:3], v[182:185], v[246:249], v[0:3]
	v_mfma_f32_16x16x32_bf16 v[4:7], v[156:159], v[246:249], v[4:7]
	s_barrier
	s_add_i32 s60, s60, 2
	s_add_u32 s6, s6, 0x100
	s_addc_u32 s7, s7, 0
	s_add_u32 s58, s58, 0x100
	s_addc_u32 s59, s59, 0
	s_cmp_gt_u32 s60, 13
.LBB0_266:
	s_add_u32 s61, s6, 0xfffc0080
	s_addc_u32 s64, s7, -1
	s_add_i32 s70, 0, 0x10000
	s_cmp_eq_u32 s60, 12
	s_cselect_b32 s67, s23, s64
	s_cselect_b32 s66, s56, s61
	v_add_u32_e32 v81, s70, v216
	s_cselect_b32 s65, s55, s59
	s_cselect_b32 s64, s57, s58
	s_add_i32 s61, 0, 0x14000
	ds_read_b128 v[88:91], v81
	ds_read_b128 v[92:95], v81 offset:1024
	ds_read_b128 v[144:147], v81 offset:2048
	ds_read_b128 v[148:151], v81 offset:3072
	v_add_u32_e32 v81, s61, v216
	ds_read_b128 v[152:155], v81
	ds_read_b128 v[156:159], v81 offset:1024
	ds_read_b128 v[178:181], v81 offset:2048
	ds_read_b128 v[182:185], v81 offset:3072
	v_lshl_add_u64 v[82:83], s[6:7], 0, v[174:175]
	s_add_i32 m0, s73, 0xc000
	ds_read_b128 v[186:189], v230
	ds_read_b128 v[198:201], v230 offset:1024
	ds_read_b128 v[202:205], v230 offset:2048
	ds_read_b128 v[206:209], v230 offset:3072
	ds_read_b128 v[234:237], v230 offset:4096
	ds_read_b128 v[238:241], v230 offset:5120
	ds_read_b128 v[242:245], v230 offset:6144
	ds_read_b128 v[246:249], v230 offset:7168
	global_load_lds_dwordx4 v[82:83], off
	v_lshl_add_u64 v[82:83], s[6:7], 0, v[176:177]
	s_add_i32 m0, s73, 0xe000
	s_nop 0
	global_load_lds_dwordx4 v[82:83], off
	s_waitcnt vmcnt(8)
	s_waitcnt lgkmcnt(0)
	s_barrier
; #define PG8_STAGE(bufoff, gbase, voff) do { _Pragma("unroll") for (int _i = 0; _i < 2; ++_i) \
;         __builtin_amdgcn_global_load_lds((const unsigned*)((const char*)(gbase) + (voff)[_i]), (LAS unsigned*)(lds + (bufoff) + ldsw + _i * 8192), 16, 0, 0); } while (0)
; #define PG8_LDA(dst, b, h) do { _Pragma("unroll") for (int m = 0; m < 4; ++m) _Pragma("unroll") for (int k = 0; k < 2; ++k) dst[m][k] = *(const LAS bf16x8*)(lds + PG8_SA(b, h) + aoff + m * 2048 + k * 1024); } while (0)
; #define PG8_MMA(ai, bj, At, Bt) do { __builtin_amdgcn_s_setprio(1); _Pragma("unroll") for (int m = 0; m < 4; ++m) _Pragma("unroll") for (int n = 0; n < 2; ++n) _Pragma("unroll") for (int k = 0; k < 2; ++k) \
;         acc[ai][bj][m][n] = __builtin_amdgcn_mfma_f32_16x16x32_bf16(Bt[n][k], At[m][k], acc[ai][bj][m][n], 0, 0, 0); __builtin_amdgcn_s_setprio(0); } while (0)
; #define PG8_WAIT_V(n) asm volatile("s_waitcnt vmcnt(" #n ")" ::: "memory")
; #define PG8_WAIT_L(n) asm volatile("s_waitcnt lgkmcnt(" #n ")" ::: "memory")
; #define PG8_BAR __builtin_amdgcn_s_barrier()
; #define PG8_SCHED __builtin_amdgcn_sched_barrier(0)
; template <class Epi, class Sched>
; __device__ __forceinline__ void gemm_phase(LAS unsigned char* lds, const Gemm g, const Sched& S, const Epi& E, const int tid) {
;     ...
;             PG8_WAIT_V(8); PG8_WAIT_L(0); PG8_BAR; PG8_MMA(0, 0, At, B0); PG8_MMA(0, 1, At, B1); PG8_BAR; PG8_SCHED;
;             PG8_LDA(At, 0, 1); PG8_STAGE(PG8_SB(0, 0), b2, voffB); PG8_STAGE(PG8_SB(0, 1), b2 + hstep, voffB); PG8_STAGE(PG8_SA(0, 0), a2, voffA);
;             PG8_WAIT_V(8); PG8_WAIT_L(0); PG8_BAR; PG8_MMA(1, 0, At, B0); PG8_MMA(1, 1, At, B1); PG8_BAR; PG8_SCHED;
	v_mfma_f32_16x16x32_bf16 v[140:143], v[88:91], v[186:189], v[140:143]
	v_mfma_f32_16x16x32_bf16 v[136:139], v[144:147], v[186:189], v[136:139]
	v_mfma_f32_16x16x32_bf16 v[120:123], v[144:147], v[202:205], v[120:123]
	v_mfma_f32_16x16x32_bf16 v[124:127], v[88:91], v[202:205], v[124:127]
	v_mfma_f32_16x16x32_bf16 v[108:111], v[88:91], v[234:237], v[108:111]
	v_mfma_f32_16x16x32_bf16 v[104:107], v[144:147], v[234:237], v[104:107]
	v_mfma_f32_16x16x32_bf16 v[76:79], v[144:147], v[242:245], v[76:79]
	v_mfma_f32_16x16x32_bf16 v[82:85], v[88:91], v[242:245], v[84:87]
	v_mfma_f32_16x16x32_bf16 v[140:143], v[92:95], v[198:201], v[140:143]
	v_mfma_f32_16x16x32_bf16 v[136:139], v[148:151], v[198:201], v[136:139]
	v_mfma_f32_16x16x32_bf16 v[120:123], v[148:151], v[206:209], v[120:123]
	v_mfma_f32_16x16x32_bf16 v[124:127], v[92:95], v[206:209], v[124:127]
	v_mfma_f32_16x16x32_bf16 v[108:111], v[92:95], v[238:241], v[108:111]
	v_mfma_f32_16x16x32_bf16 v[104:107], v[148:151], v[238:241], v[104:107]
	v_mfma_f32_16x16x32_bf16 v[76:79], v[148:151], v[246:249], v[76:79]
	v_mfma_f32_16x16x32_bf16 v[82:85], v[92:95], v[246:249], v[82:85]
	v_mfma_f32_16x16x32_bf16 v[132:135], v[152:155], v[186:189], v[132:135]
	v_mfma_f32_16x16x32_bf16 v[128:131], v[178:181], v[186:189], v[128:131]
	v_mfma_f32_16x16x32_bf16 v[112:115], v[178:181], v[202:205], v[112:115]
	v_mfma_f32_16x16x32_bf16 v[116:119], v[152:155], v[202:205], v[116:119]
	v_mfma_f32_16x16x32_bf16 v[100:103], v[152:155], v[234:237], v[100:103]
	v_mfma_f32_16x16x32_bf16 v[96:99], v[178:181], v[234:237], v[96:99]
	v_mfma_f32_16x16x32_bf16 v[64:67], v[178:181], v[242:245], v[64:67]
	v_mfma_f32_16x16x32_bf16 v[68:71], v[152:155], v[242:245], v[68:71]
	v_mfma_f32_16x16x32_bf16 v[132:135], v[156:159], v[198:201], v[132:135]
	v_mfma_f32_16x16x32_bf16 v[128:131], v[182:185], v[198:201], v[128:131]
	v_mfma_f32_16x16x32_bf16 v[112:115], v[182:185], v[206:209], v[112:115]
	v_mfma_f32_16x16x32_bf16 v[116:119], v[156:159], v[206:209], v[116:119]
	v_mfma_f32_16x16x32_bf16 v[100:103], v[156:159], v[238:241], v[100:103]
	v_mfma_f32_16x16x32_bf16 v[96:99], v[182:185], v[238:241], v[96:99]
	v_mfma_f32_16x16x32_bf16 v[64:67], v[182:185], v[246:249], v[64:67]
	v_mfma_f32_16x16x32_bf16 v[68:71], v[156:159], v[246:249], v[68:71]
	s_barrier
	s_add_i32 s70, s70, s12
	v_lshl_add_u64 v[190:191], s[64:65], 0, v[164:165]
	s_mov_b32 m0, s70
	ds_read_b128 v[186:189], v230 offset:16384
	ds_read_b128 v[198:201], v230 offset:17408
	ds_read_b128 v[202:205], v230 offset:18432
	ds_read_b128 v[206:209], v230 offset:19456
	ds_read_b128 v[234:237], v230 offset:20480
	ds_read_b128 v[238:241], v230 offset:21504
	ds_read_b128 v[242:245], v230 offset:22528
	ds_read_b128 v[246:249], v230 offset:23552
	global_load_lds_dwordx4 v[190:191], off
	s_add_i32 m0, s70, 0x2000
	s_add_u32 s70, s64, 0x40000
	v_lshl_add_u64 v[250:251], s[64:65], 0, v[168:169]
	s_addc_u32 s71, s65, 0
	s_add_i32 s61, s61, s12
	global_load_lds_dwordx4 v[250:251], off
	v_lshl_add_u64 v[86:87], s[70:71], 0, v[164:165]
	s_mov_b32 m0, s61
	v_lshl_add_u64 v[224:225], s[66:67], 0, v[162:163]
	global_load_lds_dwordx4 v[86:87], off
	v_lshl_add_u64 v[86:87], s[70:71], 0, v[168:169]
	s_add_i32 m0, s61, 0x2000
	v_lshl_add_u64 v[226:227], s[66:67], 0, v[166:167]
	global_load_lds_dwordx4 v[86:87], off
	s_mov_b32 m0, s73
	s_nop 0
	global_load_lds_dwordx4 v[224:225], off
	s_mov_b32 m0, s74
	s_nop 0
	global_load_lds_dwordx4 v[226:227], off
	s_waitcnt vmcnt(8)
	s_waitcnt lgkmcnt(0)
	s_barrier
	v_mfma_f32_16x16x32_bf16 v[60:63], v[88:91], v[186:189], v[60:63]
	v_mfma_f32_16x16x32_bf16 v[56:59], v[144:147], v[186:189], v[56:59]
	v_mfma_f32_16x16x32_bf16 v[40:43], v[144:147], v[202:205], v[40:43]
	v_mfma_f32_16x16x32_bf16 v[44:47], v[88:91], v[202:205], v[44:47]
	v_mfma_f32_16x16x32_bf16 v[28:31], v[88:91], v[234:237], v[28:31]
	v_mfma_f32_16x16x32_bf16 v[24:27], v[144:147], v[234:237], v[24:27]
	v_mfma_f32_16x16x32_bf16 v[8:11], v[144:147], v[242:245], v[8:11]
	v_mfma_f32_16x16x32_bf16 v[12:15], v[88:91], v[242:245], v[12:15]
	v_mfma_f32_16x16x32_bf16 v[60:63], v[92:95], v[198:201], v[60:63]
	v_mfma_f32_16x16x32_bf16 v[56:59], v[148:151], v[198:201], v[56:59]
	v_mfma_f32_16x16x32_bf16 v[40:43], v[148:151], v[206:209], v[40:43]
	v_mfma_f32_16x16x32_bf16 v[44:47], v[92:95], v[206:209], v[44:47]
	v_mfma_f32_16x16x32_bf16 v[28:31], v[92:95], v[238:241], v[28:31]
	v_mfma_f32_16x16x32_bf16 v[24:27], v[148:151], v[238:241], v[24:27]
	v_mfma_f32_16x16x32_bf16 v[8:11], v[148:151], v[246:249], v[8:11]
	v_mfma_f32_16x16x32_bf16 v[12:15], v[92:95], v[246:249], v[12:15]
	v_mfma_f32_16x16x32_bf16 v[52:55], v[152:155], v[186:189], v[52:55]
	v_mfma_f32_16x16x32_bf16 v[48:51], v[178:181], v[186:189], v[48:51]
	v_mfma_f32_16x16x32_bf16 v[32:35], v[178:181], v[202:205], v[32:35]
	v_mfma_f32_16x16x32_bf16 v[36:39], v[152:155], v[202:205], v[36:39]
	v_mfma_f32_16x16x32_bf16 v[20:23], v[152:155], v[234:237], v[20:23]
	v_mfma_f32_16x16x32_bf16 v[16:19], v[178:181], v[234:237], v[16:19]
	v_mfma_f32_16x16x32_bf16 v[0:3], v[178:181], v[242:245], v[0:3]
	v_mfma_f32_16x16x32_bf16 v[4:7], v[152:155], v[242:245], v[4:7]
	v_mfma_f32_16x16x32_bf16 v[52:55], v[156:159], v[198:201], v[52:55]
	v_mfma_f32_16x16x32_bf16 v[48:51], v[182:185], v[198:201], v[48:51]
	v_mfma_f32_16x16x32_bf16 v[32:35], v[182:185], v[206:209], v[32:35]
	v_mfma_f32_16x16x32_bf16 v[36:39], v[156:159], v[206:209], v[36:39]
	v_mfma_f32_16x16x32_bf16 v[20:23], v[156:159], v[238:241], v[20:23]
	v_mfma_f32_16x16x32_bf16 v[16:19], v[182:185], v[238:241], v[16:19]
	v_mfma_f32_16x16x32_bf16 v[0:3], v[182:185], v[246:249], v[0:3]
	v_mfma_f32_16x16x32_bf16 v[4:7], v[156:159], v[246:249], v[4:7]
	s_barrier
; #define PG8_STAGE(bufoff, gbase, voff) do { _Pragma("unroll") for (int _i = 0; _i < 2; ++_i) \
;         __builtin_amdgcn_global_load_lds((const unsigned*)((const char*)(gbase) + (voff)[_i]), (LAS unsigned*)(lds + (bufoff) + ldsw + _i * 8192), 16, 0, 0); } while (0)
; #define PG8_LDA(dst, b, h) do { _Pragma("unroll") for (int m = 0; m < 4; ++m) _Pragma("unroll") for (int k = 0; k < 2; ++k) dst[m][k] = *(const LAS bf16x8*)(lds + PG8_SA(b, h) + aoff + m * 2048 + k * 1024); } while (0)
; #define PG8_LDB(dst, b, h) do { _Pragma("unroll") for (int n = 0; n < 2; ++n) _Pragma("unroll") for (int k = 0; k < 2; ++k) dst[n][k] = *(const LAS bf16x8*)(lds + PG8_SB(b, h) + boff + n * 2048 + k * 1024); } while (0)
; #define PG8_MMA(ai, bj, At, Bt) do { __builtin_amdgcn_s_setprio(1); _Pragma("unroll") for (int m = 0; m < 4; ++m) _Pragma("unroll") for (int n = 0; n < 2; ++n) _Pragma("unroll") for (int k = 0; k < 2; ++k) \
;         acc[ai][bj][m][n] = __builtin_amdgcn_mfma_f32_16x16x32_bf16(Bt[n][k], At[m][k], acc[ai][bj][m][n], 0, 0, 0); __builtin_amdgcn_s_setprio(0); } while (0)
; #define PG8_WAIT_V(n) asm volatile("s_waitcnt vmcnt(" #n ")" ::: "memory")
; #define PG8_WAIT_L(n) asm volatile("s_waitcnt lgkmcnt(" #n ")" ::: "memory")
; #define PG8_BAR __builtin_amdgcn_s_barrier()
; #define PG8_SCHED __builtin_amdgcn_sched_barrier(0)
; template <class Epi, class Sched>
; __device__ __forceinline__ void gemm_phase(LAS unsigned char* lds, const Gemm g, const Sched& S, const Epi& E, const int tid) {
;     ...
;             PG8_LDB(B0, 1, 0); PG8_LDB(B1, 1, 1); PG8_SCHED; PG8_LDA(At, 1, 0); PG8_STAGE(PG8_SA(0, 1), a2 + hstep, voffA);
;             PG8_WAIT_V(8); PG8_WAIT_L(0); PG8_BAR; PG8_MMA(0, 0, At, B0); PG8_MMA(0, 1, At, B1); PG8_BAR; PG8_SCHED;
;             PG8_LDA(At, 1, 1); PG8_STAGE(PG8_SB(1, 0), b3, voffB); PG8_STAGE(PG8_SB(1, 1), b3 + hstep, voffB); PG8_STAGE(PG8_SA(1, 0), a3, voffA);
;             PG8_WAIT_V(8); PG8_WAIT_L(0); PG8_BAR; PG8_MMA(1, 0, At, B0); PG8_MMA(1, 1, At, B1); PG8_BAR; PG8_SCHED;
;         }
;         if (wr == 0) PG8_BAR;
	s_add_i32 s61, 0, 0x18000
	v_add_u32_e32 v81, s61, v216
	s_add_i32 s70, 0, 0x1c000
	ds_read_b128 v[88:91], v81
	ds_read_b128 v[92:95], v81 offset:1024
	ds_read_b128 v[144:147], v81 offset:2048
	ds_read_b128 v[148:151], v81 offset:3072
	v_add_u32_e32 v81, s70, v216
	ds_read_b128 v[152:155], v81
	ds_read_b128 v[156:159], v81 offset:1024
	ds_read_b128 v[178:181], v81 offset:2048
	ds_read_b128 v[182:185], v81 offset:3072
	s_add_u32 s66, s66, 0x40000
	s_addc_u32 s67, s67, 0
	s_mov_b32 m0, s75
	v_lshl_add_u64 v[86:87], s[66:67], 0, v[162:163]
	ds_read_b128 v[186:189], v230 offset:32768
	ds_read_b128 v[198:201], v230 offset:33792
	ds_read_b128 v[202:205], v230 offset:34816
	ds_read_b128 v[206:209], v230 offset:35840
	ds_read_b128 v[234:237], v230 offset:36864
	ds_read_b128 v[238:241], v230 offset:37888
	ds_read_b128 v[242:245], v230 offset:38912
	ds_read_b128 v[246:249], v230 offset:39936
	global_load_lds_dwordx4 v[86:87], off
	v_lshl_add_u64 v[86:87], s[66:67], 0, v[166:167]
	s_mov_b32 m0, s81
	s_nop 0
	global_load_lds_dwordx4 v[86:87], off
	s_waitcnt vmcnt(8)
	s_waitcnt lgkmcnt(0)
	s_barrier
	v_mfma_f32_16x16x32_bf16 v[140:143], v[88:91], v[186:189], v[140:143]
	v_mfma_f32_16x16x32_bf16 v[136:139], v[144:147], v[186:189], v[136:139]
	v_mfma_f32_16x16x32_bf16 v[120:123], v[144:147], v[202:205], v[120:123]
	v_mfma_f32_16x16x32_bf16 v[124:127], v[88:91], v[202:205], v[124:127]
	v_mfma_f32_16x16x32_bf16 v[108:111], v[88:91], v[234:237], v[108:111]
	v_mfma_f32_16x16x32_bf16 v[104:107], v[144:147], v[234:237], v[104:107]
	v_mfma_f32_16x16x32_bf16 v[76:79], v[144:147], v[242:245], v[76:79]
	v_mfma_f32_16x16x32_bf16 v[82:85], v[88:91], v[242:245], v[82:85]
	v_mfma_f32_16x16x32_bf16 v[140:143], v[92:95], v[198:201], v[140:143]
	v_mfma_f32_16x16x32_bf16 v[136:139], v[148:151], v[198:201], v[136:139]
	v_mfma_f32_16x16x32_bf16 v[120:123], v[148:151], v[206:209], v[120:123]
	v_mfma_f32_16x16x32_bf16 v[124:127], v[92:95], v[206:209], v[124:127]
	v_mfma_f32_16x16x32_bf16 v[108:111], v[92:95], v[238:241], v[108:111]
	v_mfma_f32_16x16x32_bf16 v[104:107], v[148:151], v[238:241], v[104:107]
	v_mfma_f32_16x16x32_bf16 v[76:79], v[148:151], v[246:249], v[76:79]
	v_mfma_f32_16x16x32_bf16 v[84:87], v[92:95], v[246:249], v[82:85]
	v_mfma_f32_16x16x32_bf16 v[132:135], v[152:155], v[186:189], v[132:135]
	v_mfma_f32_16x16x32_bf16 v[128:131], v[178:181], v[186:189], v[128:131]
	v_mfma_f32_16x16x32_bf16 v[112:115], v[178:181], v[202:205], v[112:115]
	v_mfma_f32_16x16x32_bf16 v[116:119], v[152:155], v[202:205], v[116:119]
	v_mfma_f32_16x16x32_bf16 v[100:103], v[152:155], v[234:237], v[100:103]
	v_mfma_f32_16x16x32_bf16 v[96:99], v[178:181], v[234:237], v[96:99]
	v_mfma_f32_16x16x32_bf16 v[64:67], v[178:181], v[242:245], v[64:67]
	v_mfma_f32_16x16x32_bf16 v[68:71], v[152:155], v[242:245], v[68:71]
	v_mfma_f32_16x16x32_bf16 v[132:135], v[156:159], v[198:201], v[132:135]
	v_mfma_f32_16x16x32_bf16 v[128:131], v[182:185], v[198:201], v[128:131]
	v_mfma_f32_16x16x32_bf16 v[112:115], v[182:185], v[206:209], v[112:115]
	v_mfma_f32_16x16x32_bf16 v[116:119], v[156:159], v[206:209], v[116:119]
	v_mfma_f32_16x16x32_bf16 v[100:103], v[156:159], v[238:241], v[100:103]
	v_mfma_f32_16x16x32_bf16 v[96:99], v[182:185], v[238:241], v[96:99]
	v_mfma_f32_16x16x32_bf16 v[64:67], v[182:185], v[246:249], v[64:67]
	v_mfma_f32_16x16x32_bf16 v[68:71], v[156:159], v[246:249], v[68:71]
	s_barrier
	s_add_i32 s61, s61, s12
	v_lshl_add_u64 v[82:83], v[190:191], 0, s[68:69]
	s_mov_b32 m0, s61
	ds_read_b128 v[186:189], v230 offset:49152
	ds_read_b128 v[198:201], v230 offset:50176
	ds_read_b128 v[202:205], v230 offset:51200
	ds_read_b128 v[206:209], v230 offset:52224
	ds_read_b128 v[234:237], v230 offset:53248
	ds_read_b128 v[238:241], v230 offset:54272
	ds_read_b128 v[242:245], v230 offset:55296
	ds_read_b128 v[246:249], v230 offset:56320
	global_load_lds_dwordx4 v[82:83], off
	s_add_i32 m0, s61, 0x2000
	s_add_u32 s64, s64, 0x40080
	v_lshl_add_u64 v[82:83], v[250:251], 0, s[68:69]
	s_addc_u32 s65, s65, 0
	s_add_i32 s61, s70, s12
	global_load_lds_dwordx4 v[82:83], off
	v_lshl_add_u64 v[82:83], s[64:65], 0, v[164:165]
	s_mov_b32 m0, s61
	s_nop 0
	global_load_lds_dwordx4 v[82:83], off
	v_lshl_add_u64 v[82:83], s[64:65], 0, v[168:169]
	s_add_i32 m0, s61, 0x2000
	s_nop 0
	global_load_lds_dwordx4 v[82:83], off
	v_lshl_add_u64 v[82:83], v[224:225], 0, s[68:69]
	s_mov_b32 m0, s82
	s_nop 0
	global_load_lds_dwordx4 v[82:83], off
	v_lshl_add_u64 v[82:83], v[226:227], 0, s[68:69]
	s_mov_b32 m0, s83
	s_nop 0
	global_load_lds_dwordx4 v[82:83], off
	s_waitcnt vmcnt(8)
	s_waitcnt lgkmcnt(0)
	s_barrier
	v_mfma_f32_16x16x32_bf16 v[60:63], v[88:91], v[186:189], v[60:63]
	v_mfma_f32_16x16x32_bf16 v[56:59], v[144:147], v[186:189], v[56:59]
	v_mfma_f32_16x16x32_bf16 v[40:43], v[144:147], v[202:205], v[40:43]
	v_mfma_f32_16x16x32_bf16 v[44:47], v[88:91], v[202:205], v[44:47]
	v_mfma_f32_16x16x32_bf16 v[28:31], v[88:91], v[234:237], v[28:31]
	v_mfma_f32_16x16x32_bf16 v[24:27], v[144:147], v[234:237], v[24:27]
	v_mfma_f32_16x16x32_bf16 v[8:11], v[144:147], v[242:245], v[8:11]
	v_mfma_f32_16x16x32_bf16 v[12:15], v[88:91], v[242:245], v[12:15]
	v_mfma_f32_16x16x32_bf16 v[60:63], v[92:95], v[198:201], v[60:63]
	v_mfma_f32_16x16x32_bf16 v[56:59], v[148:151], v[198:201], v[56:59]
	v_mfma_f32_16x16x32_bf16 v[40:43], v[148:151], v[206:209], v[40:43]
	v_mfma_f32_16x16x32_bf16 v[44:47], v[92:95], v[206:209], v[44:47]
	v_mfma_f32_16x16x32_bf16 v[28:31], v[92:95], v[238:241], v[28:31]
	v_mfma_f32_16x16x32_bf16 v[24:27], v[148:151], v[238:241], v[24:27]
	v_mfma_f32_16x16x32_bf16 v[8:11], v[148:151], v[246:249], v[8:11]
	v_mfma_f32_16x16x32_bf16 v[12:15], v[92:95], v[246:249], v[12:15]
	v_mfma_f32_16x16x32_bf16 v[52:55], v[152:155], v[186:189], v[52:55]
	v_mfma_f32_16x16x32_bf16 v[48:51], v[178:181], v[186:189], v[48:51]
	v_mfma_f32_16x16x32_bf16 v[32:35], v[178:181], v[202:205], v[32:35]
	v_mfma_f32_16x16x32_bf16 v[36:39], v[152:155], v[202:205], v[36:39]
	v_mfma_f32_16x16x32_bf16 v[20:23], v[152:155], v[234:237], v[20:23]
	v_mfma_f32_16x16x32_bf16 v[16:19], v[178:181], v[234:237], v[16:19]
	v_mfma_f32_16x16x32_bf16 v[0:3], v[178:181], v[242:245], v[0:3]
	v_mfma_f32_16x16x32_bf16 v[4:7], v[152:155], v[242:245], v[4:7]
	v_mfma_f32_16x16x32_bf16 v[52:55], v[156:159], v[198:201], v[52:55]
	v_mfma_f32_16x16x32_bf16 v[48:51], v[182:185], v[198:201], v[48:51]
	v_mfma_f32_16x16x32_bf16 v[32:35], v[182:185], v[206:209], v[32:35]
	v_mfma_f32_16x16x32_bf16 v[36:39], v[156:159], v[206:209], v[36:39]
	v_mfma_f32_16x16x32_bf16 v[20:23], v[156:159], v[238:241], v[20:23]
	v_mfma_f32_16x16x32_bf16 v[16:19], v[182:185], v[238:241], v[16:19]
	v_mfma_f32_16x16x32_bf16 v[0:3], v[182:185], v[246:249], v[0:3]
	v_mfma_f32_16x16x32_bf16 v[4:7], v[156:159], v[246:249], v[4:7]
	s_barrier
	s_add_i32 s60, s60, 2
	s_add_u32 s6, s6, 0x100
	s_addc_u32 s7, s7, 0
	s_add_u32 s58, s58, 0x100
	s_addc_u32 s59, s59, 0
	s_cmp_gt_u32 s60, 13
	s_cbranch_scc0 .LBB0_266
	s_and_b64 vcc, exec, s[50:51]
	s_cbranch_vccz .LBB0_269
	s_barrier

;     __device__ __forceinline__ Pre prefetch(const Unit& u, int tid) const { return prenorm_load(stats, u.pn * BM, sW + (size_t)(u.pn >> 4) * SW_ROWS + u.pm * BM, tid); }
;     __device__ __forceinline__ Pre prefetch(const Unit& u, int tid) const { return prenorm_load(stats, u.pm * BM, sW + (size_t)(u.pm >> 4) * SW_ROWS + u.pn * BM, tid); }
;     __device__ __forceinline__ Pre prefetch(const Unit& u, int tid) const { return prenorm_load(stats, u.pm * BM, sW + (size_t)(u.pm >> 4) * SW_ROWS + u.pn * BM, tid); }
; #define PG8_STAGE(bufoff, gbase, voff) do { _Pragma("unroll") for (int _i = 0; _i < 2; ++_i) \
;         __builtin_amdgcn_global_load_lds((const unsigned*)((const char*)(gbase) + (voff)[_i]), (LAS unsigned*)(lds + (bufoff) + ldsw + _i * 8192), 16, 0, 0); } while (0)
; #define PG8_LDA(dst, b, h) do { _Pragma("unroll") for (int m = 0; m < 4; ++m) _Pragma("unroll") for (int k = 0; k < 2; ++k) dst[m][k] = *(const LAS bf16x8*)(lds + PG8_SA(b, h) + aoff + m * 2048 + k * 1024); } while (0)
; #define PG8_WAIT_V(n) asm volatile("s_waitcnt vmcnt(" #n ")" ::: "memory")
; #define PG8_WAIT_L(n) asm volatile("s_waitcnt lgkmcnt(" #n ")" ::: "memory")
; template <class Epi, class Sched>
; __device__ __forceinline__ void gemm_phase(LAS unsigned char* lds, const Gemm g, const Sched& S, const Epi& E, const int tid) {
;     ...
;         const bool has_next = S.next(ui + 1, nxt);
;         const char* nA = has_next ? (const char*)g.A + (size_t)nxt.pm * tstep : cA; const char* nB = has_next ? (const char*)g.Bt + (size_t)nxt.pn * tstep : cB;
;         const typename Epi::Pre pre = E.prefetch(cur, tid);
;         for (int t = 0; t < nt; t += 2) {
;             const bool last = (t == nt - 2);
;             const char* a1 = cA + (size_t)(t + 1) * kstep;
;             const char* a2 = last ? nA : cA + (size_t)(t + 2) * kstep; const char* b2 = last ? nB : cB + (size_t)(t + 2) * kstep;
;             const char* a3 = a2 + kstep; const char* b3 = b2 + kstep;
;             PG8_LDB(B0, 0, 0); PG8_LDB(B1, 0, 1); PG8_SCHED; PG8_LDA(At, 0, 0); PG8_STAGE(PG8_SA(1, 1), a1 + hstep, voffA);
;             PG8_WAIT_V(8); PG8_WAIT_L(0); PG8_BAR; PG8_MMA(0, 0, At, B0); PG8_MMA(0, 1, At, B1); PG8_BAR; PG8_SCHED;
;             PG8_LDA(At, 0, 1); PG8_STAGE(PG8_SB(0, 0), b2, voffB); PG8_STAGE(PG8_SB(0, 1), b2 + hstep, voffB); PG8_STAGE(PG8_SA(0, 0), a2, voffA);
.LBB0_325:
	s_or_b64 exec, exec, s[50:51]
	s_ashr_i32 s39, s38, 31
	s_lshl_b64 s[50:51], s[38:39], 19
	s_add_u32 s50, s85, s50
	s_addc_u32 s51, s86, s51
	s_and_b64 s[54:55], s[4:5], exec
	s_cselect_b32 s39, s51, s63
	s_cselect_b32 s74, s50, s62
	s_ashr_i32 s23, s22, 31
	s_lshl_b64 s[54:55], s[22:23], 19
	s_add_u32 s54, s46, s54
	s_addc_u32 s55, s47, s55
	s_and_b64 s[66:67], s[4:5], exec
	s_cselect_b32 s23, s55, s65
	s_cselect_b32 s75, s54, s64
	s_add_u32 s62, s62, 0x40080
	s_addc_u32 s63, s63, 0
	s_add_u32 s78, s64, 0x100
	s_addc_u32 s79, s65, 0
	s_mov_b32 s81, -2
	s_waitcnt lgkmcnt(0)
	s_add_u32 s64, s62, 0xfffc0080
	s_addc_u32 s65, s63, -1
	s_add_i32 s82, 0, 0x10000
	s_cmp_eq_u32 s81, 12
	s_cselect_b32 s67, s39, s65
	s_cselect_b32 s66, s74, s64
	v_add_u32_e32 v69, s82, v154
	s_cselect_b32 s65, s23, s79
	s_cselect_b32 s64, s75, s78
	s_add_i32 s90, 0, 0x14000
	ds_read_b128 v[70:73], v69
	ds_read_b128 v[74:77], v69 offset:1024
	ds_read_b128 v[172:175], v69 offset:2048
	ds_read_b128 v[176:179], v69 offset:3072
	v_add_u32_e32 v69, s90, v154
	ds_read_b128 v[180:183], v69
	ds_read_b128 v[184:187], v69 offset:1024
	ds_read_b128 v[188:191], v69 offset:2048
	ds_read_b128 v[198:201], v69 offset:3072
	v_lshl_add_u64 v[78:79], s[62:63], 0, v[144:145]
	s_add_i32 m0, s53, 0xc000
	ds_read_b128 v[202:205], v171
	ds_read_b128 v[206:209], v171 offset:1024
	ds_read_b128 v[210:213], v171 offset:2048
	ds_read_b128 v[214:217], v171 offset:3072
	ds_read_b128 v[218:221], v171 offset:4096
	ds_read_b128 v[230:233], v171 offset:5120
	ds_read_b128 v[234:237], v171 offset:6144
	ds_read_b128 v[238:241], v171 offset:7168
	global_load_lds_dwordx4 v[78:79], off
	v_lshl_add_u64 v[78:79], s[62:63], 0, v[146:147]
	s_add_i32 m0, s53, 0xe000
	s_nop 0
	global_load_lds_dwordx4 v[78:79], off
	s_waitcnt vmcnt(8)
	s_waitcnt lgkmcnt(0)
	s_barrier
	v_mfma_f32_16x16x32_bf16 v[140:143], v[70:73], v[202:205], 0
	v_mfma_f32_16x16x32_bf16 v[136:139], v[172:175], v[202:205], 0
	v_mfma_f32_16x16x32_bf16 v[128:131], v[172:175], v[210:213], 0
	v_mfma_f32_16x16x32_bf16 v[132:135], v[70:73], v[210:213], 0
	v_mfma_f32_16x16x32_bf16 v[116:119], v[70:73], v[218:221], 0
	v_mfma_f32_16x16x32_bf16 v[112:115], v[172:175], v[218:221], 0
	v_mfma_f32_16x16x32_bf16 v[96:99], v[172:175], v[234:237], 0
	v_mfma_f32_16x16x32_bf16 v[100:103], v[70:73], v[234:237], 0
	v_mfma_f32_16x16x32_bf16 v[140:143], v[74:77], v[206:209], v[140:143]
	v_mfma_f32_16x16x32_bf16 v[136:139], v[176:179], v[206:209], v[136:139]
	v_mfma_f32_16x16x32_bf16 v[128:131], v[176:179], v[214:217], v[128:131]
	v_mfma_f32_16x16x32_bf16 v[132:135], v[74:77], v[214:217], v[132:135]
	v_mfma_f32_16x16x32_bf16 v[116:119], v[74:77], v[230:233], v[116:119]
	v_mfma_f32_16x16x32_bf16 v[112:115], v[176:179], v[230:233], v[112:115]
	v_mfma_f32_16x16x32_bf16 v[96:99], v[176:179], v[238:241], v[96:99]
	v_mfma_f32_16x16x32_bf16 v[100:103], v[74:77], v[238:241], v[100:103]
	v_mfma_f32_16x16x32_bf16 v[124:127], v[180:183], v[202:205], 0
	v_mfma_f32_16x16x32_bf16 v[120:123], v[188:191], v[202:205], 0
	v_mfma_f32_16x16x32_bf16 v[104:107], v[188:191], v[210:213], 0
	v_mfma_f32_16x16x32_bf16 v[108:111], v[180:183], v[210:213], 0
	v_mfma_f32_16x16x32_bf16 v[92:95], v[180:183], v[218:221], 0
	v_mfma_f32_16x16x32_bf16 v[88:91], v[188:191], v[218:221], 0
	v_mfma_f32_16x16x32_bf16 v[78:81], v[188:191], v[234:237], 0
	v_mfma_f32_16x16x32_bf16 v[84:87], v[180:183], v[234:237], 0
	v_mfma_f32_16x16x32_bf16 v[124:127], v[184:187], v[206:209], v[124:127]
	v_mfma_f32_16x16x32_bf16 v[120:123], v[198:201], v[206:209], v[120:123]
	v_mfma_f32_16x16x32_bf16 v[104:107], v[198:201], v[214:217], v[104:107]
	v_mfma_f32_16x16x32_bf16 v[108:111], v[184:187], v[214:217], v[108:111]
	v_mfma_f32_16x16x32_bf16 v[92:95], v[184:187], v[230:233], v[92:95]
	v_mfma_f32_16x16x32_bf16 v[88:91], v[198:201], v[230:233], v[88:91]
	v_mfma_f32_16x16x32_bf16 v[78:81], v[198:201], v[238:241], v[78:81]
	v_mfma_f32_16x16x32_bf16 v[84:87], v[184:187], v[238:241], v[84:87]
	s_barrier
	s_add_i32 s82, s82, s52
	v_lshl_add_u64 v[224:225], s[64:65], 0, v[164:165]
	s_mov_b32 m0, s82
	ds_read_b128 v[202:205], v171 offset:16384
	ds_read_b128 v[206:209], v171 offset:17408
	ds_read_b128 v[210:213], v171 offset:18432
	ds_read_b128 v[214:217], v171 offset:19456
	ds_read_b128 v[218:221], v171 offset:20480
	ds_read_b128 v[230:233], v171 offset:21504
	ds_read_b128 v[234:237], v171 offset:22528
	ds_read_b128 v[238:241], v171 offset:23552
	global_load_lds_dwordx4 v[224:225], off
	s_add_i32 m0, s82, 0x2000
	s_add_u32 s82, s64, 0x40000
	v_lshl_add_u64 v[226:227], s[64:65], 0, v[168:169]
	s_addc_u32 s83, s65, 0
	s_add_i32 s90, s90, s52
	global_load_lds_dwordx4 v[226:227], off
	v_lshl_add_u64 v[82:83], s[82:83], 0, v[164:165]
	s_mov_b32 m0, s90
	v_lshl_add_u64 v[242:243], s[66:67], 0, v[162:163]
	global_load_lds_dwordx4 v[82:83], off
	v_lshl_add_u64 v[82:83], s[82:83], 0, v[168:169]
	s_add_i32 m0, s90, 0x2000
	v_lshl_add_u64 v[244:245], s[66:67], 0, v[166:167]
	global_load_lds_dwordx4 v[82:83], off
	s_mov_b32 m0, s53
	s_nop 0
	global_load_lds_dwordx4 v[242:243], off
	s_mov_b32 m0, s56
	s_nop 0
	global_load_lds_dwordx4 v[244:245], off
	s_waitcnt vmcnt(8)
	s_waitcnt lgkmcnt(0)
	s_barrier
; #define PG8_STAGE(bufoff, gbase, voff) do { _Pragma("unroll") for (int _i = 0; _i < 2; ++_i) \
;         __builtin_amdgcn_global_load_lds((const unsigned*)((const char*)(gbase) + (voff)[_i]), (LAS unsigned*)(lds + (bufoff) + ldsw + _i * 8192), 16, 0, 0); } while (0)
; #define PG8_LDA(dst, b, h) do { _Pragma("unroll") for (int m = 0; m < 4; ++m) _Pragma("unroll") for (int k = 0; k < 2; ++k) dst[m][k] = *(const LAS bf16x8*)(lds + PG8_SA(b, h) + aoff + m * 2048 + k * 1024); } while (0)
; #define PG8_LDB(dst, b, h) do { _Pragma("unroll") for (int n = 0; n < 2; ++n) _Pragma("unroll") for (int k = 0; k < 2; ++k) dst[n][k] = *(const LAS bf16x8*)(lds + PG8_SB(b, h) + boff + n * 2048 + k * 1024); } while (0)
; #define PG8_MMA(ai, bj, At, Bt) do { __builtin_amdgcn_s_setprio(1); _Pragma("unroll") for (int m = 0; m < 4; ++m) _Pragma("unroll") for (int n = 0; n < 2; ++n) _Pragma("unroll") for (int k = 0; k < 2; ++k) \
;         acc[ai][bj][m][n] = __builtin_amdgcn_mfma_f32_16x16x32_bf16(Bt[n][k], At[m][k], acc[ai][bj][m][n], 0, 0, 0); __builtin_amdgcn_s_setprio(0); } while (0)
; #define PG8_WAIT_V(n) asm volatile("s_waitcnt vmcnt(" #n ")" ::: "memory")
; #define PG8_WAIT_L(n) asm volatile("s_waitcnt lgkmcnt(" #n ")" ::: "memory")
; #define PG8_BAR __builtin_amdgcn_s_barrier()
; #define PG8_SCHED __builtin_amdgcn_sched_barrier(0)
; template <class Epi, class Sched>
; __device__ __forceinline__ void gemm_phase(LAS unsigned char* lds, const Gemm g, const Sched& S, const Epi& E, const int tid) {
;     ...
;             PG8_WAIT_V(8); PG8_WAIT_L(0); PG8_BAR; PG8_MMA(1, 0, At, B0); PG8_MMA(1, 1, At, B1); PG8_BAR; PG8_SCHED;
;             PG8_LDB(B0, 1, 0); PG8_LDB(B1, 1, 1); PG8_SCHED; PG8_LDA(At, 1, 0); PG8_STAGE(PG8_SA(0, 1), a2 + hstep, voffA);
;             PG8_WAIT_V(8); PG8_WAIT_L(0); PG8_BAR; PG8_MMA(0, 0, At, B0); PG8_MMA(0, 1, At, B1); PG8_BAR; PG8_SCHED;
	v_mfma_f32_16x16x32_bf16 v[60:63], v[70:73], v[202:205], 0
	v_mfma_f32_16x16x32_bf16 v[56:59], v[172:175], v[202:205], 0
	v_mfma_f32_16x16x32_bf16 v[44:47], v[172:175], v[210:213], 0
	v_mfma_f32_16x16x32_bf16 v[52:55], v[70:73], v[210:213], 0
	v_mfma_f32_16x16x32_bf16 v[28:31], v[70:73], v[218:221], 0
	v_mfma_f32_16x16x32_bf16 v[24:27], v[172:175], v[218:221], 0
	v_mfma_f32_16x16x32_bf16 v[8:11], v[172:175], v[234:237], 0
	v_mfma_f32_16x16x32_bf16 v[16:19], v[70:73], v[234:237], 0
	v_mfma_f32_16x16x32_bf16 v[60:63], v[74:77], v[206:209], v[60:63]
	v_mfma_f32_16x16x32_bf16 v[56:59], v[176:179], v[206:209], v[56:59]
	v_mfma_f32_16x16x32_bf16 v[44:47], v[176:179], v[214:217], v[44:47]
	v_mfma_f32_16x16x32_bf16 v[52:55], v[74:77], v[214:217], v[52:55]
	v_mfma_f32_16x16x32_bf16 v[28:31], v[74:77], v[230:233], v[28:31]
	v_mfma_f32_16x16x32_bf16 v[24:27], v[176:179], v[230:233], v[24:27]
	v_mfma_f32_16x16x32_bf16 v[8:11], v[176:179], v[238:241], v[8:11]
	v_mfma_f32_16x16x32_bf16 v[16:19], v[74:77], v[238:241], v[16:19]
	v_mfma_f32_16x16x32_bf16 v[48:51], v[180:183], v[202:205], 0
	v_mfma_f32_16x16x32_bf16 v[40:43], v[188:191], v[202:205], 0
	v_mfma_f32_16x16x32_bf16 v[32:35], v[188:191], v[210:213], 0
	v_mfma_f32_16x16x32_bf16 v[36:39], v[180:183], v[210:213], 0
	v_mfma_f32_16x16x32_bf16 v[20:23], v[180:183], v[218:221], 0
	v_mfma_f32_16x16x32_bf16 v[12:15], v[188:191], v[218:221], 0
	v_mfma_f32_16x16x32_bf16 v[0:3], v[188:191], v[234:237], 0
	v_mfma_f32_16x16x32_bf16 v[4:7], v[180:183], v[234:237], 0
	v_mfma_f32_16x16x32_bf16 v[48:51], v[184:187], v[206:209], v[48:51]
	v_mfma_f32_16x16x32_bf16 v[40:43], v[198:201], v[206:209], v[40:43]
	v_mfma_f32_16x16x32_bf16 v[32:35], v[198:201], v[214:217], v[32:35]
	v_mfma_f32_16x16x32_bf16 v[36:39], v[184:187], v[214:217], v[36:39]
	v_mfma_f32_16x16x32_bf16 v[20:23], v[184:187], v[230:233], v[20:23]
	v_mfma_f32_16x16x32_bf16 v[12:15], v[198:201], v[230:233], v[12:15]
	v_mfma_f32_16x16x32_bf16 v[0:3], v[198:201], v[238:241], v[0:3]
	v_mfma_f32_16x16x32_bf16 v[4:7], v[184:187], v[238:241], v[4:7]
	s_barrier
	s_add_i32 s82, 0, 0x18000
	v_add_u32_e32 v69, s82, v154
	s_add_i32 s83, 0, 0x1c000
	ds_read_b128 v[70:73], v69
	ds_read_b128 v[74:77], v69 offset:1024
	ds_read_b128 v[172:175], v69 offset:2048
	ds_read_b128 v[176:179], v69 offset:3072
	v_add_u32_e32 v69, s83, v154
	ds_read_b128 v[180:183], v69
	ds_read_b128 v[184:187], v69 offset:1024
	ds_read_b128 v[188:191], v69 offset:2048
	ds_read_b128 v[198:201], v69 offset:3072
	s_add_u32 s66, s66, 0x40000
	s_addc_u32 s67, s67, 0
	s_mov_b32 m0, s57
	v_lshl_add_u64 v[82:83], s[66:67], 0, v[162:163]
	ds_read_b128 v[202:205], v171 offset:32768
	ds_read_b128 v[206:209], v171 offset:33792
	ds_read_b128 v[210:213], v171 offset:34816
	ds_read_b128 v[214:217], v171 offset:35840
	ds_read_b128 v[218:221], v171 offset:36864
	ds_read_b128 v[230:233], v171 offset:37888
	ds_read_b128 v[234:237], v171 offset:38912
	ds_read_b128 v[238:241], v171 offset:39936
	global_load_lds_dwordx4 v[82:83], off
	v_lshl_add_u64 v[82:83], s[66:67], 0, v[166:167]
	s_mov_b32 m0, s58
	s_nop 0
	global_load_lds_dwordx4 v[82:83], off
	s_waitcnt vmcnt(8)
	s_waitcnt lgkmcnt(0)
	s_barrier
	v_mfma_f32_16x16x32_bf16 v[140:143], v[70:73], v[202:205], v[140:143]
	v_mfma_f32_16x16x32_bf16 v[136:139], v[172:175], v[202:205], v[136:139]
	v_mfma_f32_16x16x32_bf16 v[128:131], v[172:175], v[210:213], v[128:131]
	v_mfma_f32_16x16x32_bf16 v[132:135], v[70:73], v[210:213], v[132:135]
	v_mfma_f32_16x16x32_bf16 v[116:119], v[70:73], v[218:221], v[116:119]
	v_mfma_f32_16x16x32_bf16 v[112:115], v[172:175], v[218:221], v[112:115]
	v_mfma_f32_16x16x32_bf16 v[96:99], v[172:175], v[234:237], v[96:99]
	v_mfma_f32_16x16x32_bf16 v[100:103], v[70:73], v[234:237], v[100:103]
	v_mfma_f32_16x16x32_bf16 v[140:143], v[74:77], v[206:209], v[140:143]
	v_mfma_f32_16x16x32_bf16 v[136:139], v[176:179], v[206:209], v[136:139]
	v_mfma_f32_16x16x32_bf16 v[128:131], v[176:179], v[214:217], v[128:131]
	v_mfma_f32_16x16x32_bf16 v[132:135], v[74:77], v[214:217], v[132:135]
	v_mfma_f32_16x16x32_bf16 v[116:119], v[74:77], v[230:233], v[116:119]
	v_mfma_f32_16x16x32_bf16 v[112:115], v[176:179], v[230:233], v[112:115]
	v_mfma_f32_16x16x32_bf16 v[96:99], v[176:179], v[238:241], v[96:99]
	v_mfma_f32_16x16x32_bf16 v[100:103], v[74:77], v[238:241], v[100:103]
	v_mfma_f32_16x16x32_bf16 v[124:127], v[180:183], v[202:205], v[124:127]
	v_mfma_f32_16x16x32_bf16 v[120:123], v[188:191], v[202:205], v[120:123]
	v_mfma_f32_16x16x32_bf16 v[104:107], v[188:191], v[210:213], v[104:107]
	v_mfma_f32_16x16x32_bf16 v[108:111], v[180:183], v[210:213], v[108:111]
	v_mfma_f32_16x16x32_bf16 v[92:95], v[180:183], v[218:221], v[92:95]
	v_mfma_f32_16x16x32_bf16 v[88:91], v[188:191], v[218:221], v[88:91]
	v_mfma_f32_16x16x32_bf16 v[78:81], v[188:191], v[234:237], v[78:81]
	v_mfma_f32_16x16x32_bf16 v[82:85], v[180:183], v[234:237], v[84:87]
	v_mfma_f32_16x16x32_bf16 v[124:127], v[184:187], v[206:209], v[124:127]
	v_mfma_f32_16x16x32_bf16 v[120:123], v[198:201], v[206:209], v[120:123]
	v_mfma_f32_16x16x32_bf16 v[104:107], v[198:201], v[214:217], v[104:107]
	v_mfma_f32_16x16x32_bf16 v[108:111], v[184:187], v[214:217], v[108:111]
	v_mfma_f32_16x16x32_bf16 v[92:95], v[184:187], v[230:233], v[92:95]
	v_mfma_f32_16x16x32_bf16 v[88:91], v[198:201], v[230:233], v[88:91]
	v_mfma_f32_16x16x32_bf16 v[80:83], v[198:201], v[238:241], v[78:81]
	v_mfma_f32_16x16x32_bf16 v[84:87], v[184:187], v[238:241], v[82:85]
	s_barrier
; #define PG8_STAGE(bufoff, gbase, voff) do { _Pragma("unroll") for (int _i = 0; _i < 2; ++_i) \
;         __builtin_amdgcn_global_load_lds((const unsigned*)((const char*)(gbase) + (voff)[_i]), (LAS unsigned*)(lds + (bufoff) + ldsw + _i * 8192), 16, 0, 0); } while (0)
; #define PG8_LDA(dst, b, h) do { _Pragma("unroll") for (int m = 0; m < 4; ++m) _Pragma("unroll") for (int k = 0; k < 2; ++k) dst[m][k] = *(const LAS bf16x8*)(lds + PG8_SA(b, h) + aoff + m * 2048 + k * 1024); } while (0)
; #define PG8_LDB(dst, b, h) do { _Pragma("unroll") for (int n = 0; n < 2; ++n) _Pragma("unroll") for (int k = 0; k < 2; ++k) dst[n][k] = *(const LAS bf16x8*)(lds + PG8_SB(b, h) + boff + n * 2048 + k * 1024); } while (0)
; #define PG8_WAIT_V(n) asm volatile("s_waitcnt vmcnt(" #n ")" ::: "memory")
; #define PG8_BAR __builtin_amdgcn_s_barrier()
; template <class Epi, class Sched>
; __device__ __forceinline__ void gemm_phase(LAS unsigned char* lds, const Gemm g, const Sched& S, const Epi& E, const int tid) {
;     ...
;         for (int t = 0; t < nt; t += 2) {
;             const bool last = (t == nt - 2);
;             const char* a1 = cA + (size_t)(t + 1) * kstep;
;             const char* a2 = last ? nA : cA + (size_t)(t + 2) * kstep; const char* b2 = last ? nB : cB + (size_t)(t + 2) * kstep;
;             const char* a3 = a2 + kstep; const char* b3 = b2 + kstep;
;             PG8_LDB(B0, 0, 0); PG8_LDB(B1, 0, 1); PG8_SCHED; PG8_LDA(At, 0, 0); PG8_STAGE(PG8_SA(1, 1), a1 + hstep, voffA);
;             PG8_WAIT_V(8); PG8_WAIT_L(0); PG8_BAR; PG8_MMA(0, 0, At, B0); PG8_MMA(0, 1, At, B1); PG8_BAR; PG8_SCHED;
;             PG8_LDA(At, 0, 1); PG8_STAGE(PG8_SB(0, 0), b2, voffB); PG8_STAGE(PG8_SB(0, 1), b2 + hstep, voffB); PG8_STAGE(PG8_SA(0, 0), a2, voffA);
;             PG8_WAIT_V(8); PG8_WAIT_L(0); PG8_BAR; PG8_MMA(1, 0, At, B0); PG8_MMA(1, 1, At, B1); PG8_BAR; PG8_SCHED;
;             PG8_LDB(B0, 1, 0); PG8_LDB(B1, 1, 1); PG8_SCHED; PG8_LDA(At, 1, 0); PG8_STAGE(PG8_SA(0, 1), a2 + hstep, voffA);
;             PG8_WAIT_V(8); PG8_WAIT_L(0); PG8_BAR; PG8_MMA(0, 0, At, B0); PG8_MMA(0, 1, At, B1); PG8_BAR; PG8_SCHED;
;             PG8_LDA(At, 1, 1); PG8_STAGE(PG8_SB(1, 0), b3, voffB); PG8_STAGE(PG8_SB(1, 1), b3 + hstep, voffB); PG8_STAGE(PG8_SA(1, 0), a3, voffA);
;             PG8_WAIT_V(8); PG8_WAIT_L(0); PG8_BAR; PG8_MMA(1, 0, At, B0); PG8_MMA(1, 1, At, B1); PG8_BAR; PG8_SCHED;
	s_add_i32 s66, s82, s52
	v_lshl_add_u64 v[78:79], v[224:225], 0, s[68:69]
	s_mov_b32 m0, s66
	ds_read_b128 v[202:205], v171 offset:49152
	ds_read_b128 v[206:209], v171 offset:50176
	ds_read_b128 v[210:213], v171 offset:51200
	ds_read_b128 v[214:217], v171 offset:52224
	ds_read_b128 v[218:221], v171 offset:53248
	ds_read_b128 v[230:233], v171 offset:54272
	ds_read_b128 v[234:237], v171 offset:55296
	ds_read_b128 v[238:241], v171 offset:56320
	global_load_lds_dwordx4 v[78:79], off
	s_add_i32 m0, s66, 0x2000
	s_add_u32 s64, s64, 0x40080
	v_lshl_add_u64 v[78:79], v[226:227], 0, s[68:69]
	s_addc_u32 s65, s65, 0
	s_add_i32 s66, s83, s52
	global_load_lds_dwordx4 v[78:79], off
	v_lshl_add_u64 v[78:79], s[64:65], 0, v[164:165]
	s_mov_b32 m0, s66
	s_nop 0
	global_load_lds_dwordx4 v[78:79], off
	v_lshl_add_u64 v[78:79], s[64:65], 0, v[168:169]
	s_add_i32 m0, s66, 0x2000
	s_nop 0
	global_load_lds_dwordx4 v[78:79], off
	v_lshl_add_u64 v[78:79], v[242:243], 0, s[68:69]
	s_mov_b32 m0, s61
	s_nop 0
	global_load_lds_dwordx4 v[78:79], off
	v_lshl_add_u64 v[78:79], v[244:245], 0, s[68:69]
	s_mov_b32 m0, s70
	s_nop 0
	global_load_lds_dwordx4 v[78:79], off
	s_waitcnt vmcnt(8)
	s_waitcnt lgkmcnt(0)
	s_barrier
	v_mfma_f32_16x16x32_bf16 v[60:63], v[70:73], v[202:205], v[60:63]
	v_mfma_f32_16x16x32_bf16 v[56:59], v[172:175], v[202:205], v[56:59]
	v_mfma_f32_16x16x32_bf16 v[44:47], v[172:175], v[210:213], v[44:47]
	v_mfma_f32_16x16x32_bf16 v[52:55], v[70:73], v[210:213], v[52:55]
	v_mfma_f32_16x16x32_bf16 v[28:31], v[70:73], v[218:221], v[28:31]
	v_mfma_f32_16x16x32_bf16 v[24:27], v[172:175], v[218:221], v[24:27]
	v_mfma_f32_16x16x32_bf16 v[8:11], v[172:175], v[234:237], v[8:11]
	v_mfma_f32_16x16x32_bf16 v[16:19], v[70:73], v[234:237], v[16:19]
	v_mfma_f32_16x16x32_bf16 v[60:63], v[74:77], v[206:209], v[60:63]
	v_mfma_f32_16x16x32_bf16 v[56:59], v[176:179], v[206:209], v[56:59]
	v_mfma_f32_16x16x32_bf16 v[44:47], v[176:179], v[214:217], v[44:47]
	v_mfma_f32_16x16x32_bf16 v[52:55], v[74:77], v[214:217], v[52:55]
	v_mfma_f32_16x16x32_bf16 v[28:31], v[74:77], v[230:233], v[28:31]
	v_mfma_f32_16x16x32_bf16 v[24:27], v[176:179], v[230:233], v[24:27]
	v_mfma_f32_16x16x32_bf16 v[8:11], v[176:179], v[238:241], v[8:11]
	v_mfma_f32_16x16x32_bf16 v[16:19], v[74:77], v[238:241], v[16:19]
	v_mfma_f32_16x16x32_bf16 v[48:51], v[180:183], v[202:205], v[48:51]
	v_mfma_f32_16x16x32_bf16 v[40:43], v[188:191], v[202:205], v[40:43]
	v_mfma_f32_16x16x32_bf16 v[32:35], v[188:191], v[210:213], v[32:35]
	v_mfma_f32_16x16x32_bf16 v[36:39], v[180:183], v[210:213], v[36:39]
	v_mfma_f32_16x16x32_bf16 v[20:23], v[180:183], v[218:221], v[20:23]
	v_mfma_f32_16x16x32_bf16 v[12:15], v[188:191], v[218:221], v[12:15]
	v_mfma_f32_16x16x32_bf16 v[0:3], v[188:191], v[234:237], v[0:3]
	v_mfma_f32_16x16x32_bf16 v[4:7], v[180:183], v[234:237], v[4:7]
	v_mfma_f32_16x16x32_bf16 v[48:51], v[184:187], v[206:209], v[48:51]
	v_mfma_f32_16x16x32_bf16 v[40:43], v[198:201], v[206:209], v[40:43]
	v_mfma_f32_16x16x32_bf16 v[32:35], v[198:201], v[214:217], v[32:35]
	v_mfma_f32_16x16x32_bf16 v[36:39], v[184:187], v[214:217], v[36:39]
	v_mfma_f32_16x16x32_bf16 v[20:23], v[184:187], v[230:233], v[20:23]
	v_mfma_f32_16x16x32_bf16 v[12:15], v[198:201], v[230:233], v[12:15]
	v_mfma_f32_16x16x32_bf16 v[0:3], v[198:201], v[238:241], v[0:3]
	v_mfma_f32_16x16x32_bf16 v[4:7], v[184:187], v[238:241], v[4:7]
	s_barrier
	s_add_i32 s81, s81, 2
	s_add_u32 s62, s62, 0x100
	s_addc_u32 s63, s63, 0
	s_add_u32 s78, s78, 0x100
	s_addc_u32 s79, s79, 0
	s_cmp_gt_u32 s81, 13
.LBB0_326:
	s_add_u32 s64, s62, 0xfffc0080
	s_addc_u32 s65, s63, -1
	s_add_i32 s82, 0, 0x10000
	s_cmp_eq_u32 s81, 12
	s_cselect_b32 s67, s39, s65
	s_cselect_b32 s66, s74, s64
	v_add_u32_e32 v69, s82, v154
	s_cselect_b32 s65, s23, s79
	s_cselect_b32 s64, s75, s78
	s_add_i32 s90, 0, 0x14000
	ds_read_b128 v[70:73], v69
	ds_read_b128 v[74:77], v69 offset:1024
	ds_read_b128 v[172:175], v69 offset:2048
	ds_read_b128 v[176:179], v69 offset:3072
	v_add_u32_e32 v69, s90, v154
	ds_read_b128 v[180:183], v69
	ds_read_b128 v[184:187], v69 offset:1024
	ds_read_b128 v[188:191], v69 offset:2048
	ds_read_b128 v[198:201], v69 offset:3072
	v_lshl_add_u64 v[78:79], s[62:63], 0, v[144:145]
	s_add_i32 m0, s53, 0xc000
	ds_read_b128 v[202:205], v171
	ds_read_b128 v[206:209], v171 offset:1024
	ds_read_b128 v[210:213], v171 offset:2048
	ds_read_b128 v[214:217], v171 offset:3072
	ds_read_b128 v[218:221], v171 offset:4096
	ds_read_b128 v[230:233], v171 offset:5120
	ds_read_b128 v[234:237], v171 offset:6144
	ds_read_b128 v[238:241], v171 offset:7168
	global_load_lds_dwordx4 v[78:79], off
	v_lshl_add_u64 v[78:79], s[62:63], 0, v[146:147]
	s_add_i32 m0, s53, 0xe000
	s_nop 0
	global_load_lds_dwordx4 v[78:79], off
	s_waitcnt vmcnt(8)
	s_waitcnt lgkmcnt(0)
	s_barrier
; #define PG8_STAGE(bufoff, gbase, voff) do { _Pragma("unroll") for (int _i = 0; _i < 2; ++_i) \
;         __builtin_amdgcn_global_load_lds((const unsigned*)((const char*)(gbase) + (voff)[_i]), (LAS unsigned*)(lds + (bufoff) + ldsw + _i * 8192), 16, 0, 0); } while (0)
; #define PG8_LDA(dst, b, h) do { _Pragma("unroll") for (int m = 0; m < 4; ++m) _Pragma("unroll") for (int k = 0; k < 2; ++k) dst[m][k] = *(const LAS bf16x8*)(lds + PG8_SA(b, h) + aoff + m * 2048 + k * 1024); } while (0)
; #define PG8_MMA(ai, bj, At, Bt) do { __builtin_amdgcn_s_setprio(1); _Pragma("unroll") for (int m = 0; m < 4; ++m) _Pragma("unroll") for (int n = 0; n < 2; ++n) _Pragma("unroll") for (int k = 0; k < 2; ++k) \
;         acc[ai][bj][m][n] = __builtin_amdgcn_mfma_f32_16x16x32_bf16(Bt[n][k], At[m][k], acc[ai][bj][m][n], 0, 0, 0); __builtin_amdgcn_s_setprio(0); } while (0)
; #define PG8_WAIT_V(n) asm volatile("s_waitcnt vmcnt(" #n ")" ::: "memory")
; #define PG8_WAIT_L(n) asm volatile("s_waitcnt lgkmcnt(" #n ")" ::: "memory")
; #define PG8_BAR __builtin_amdgcn_s_barrier()
; #define PG8_SCHED __builtin_amdgcn_sched_barrier(0)
; template <class Epi, class Sched>
; __device__ __forceinline__ void gemm_phase(LAS unsigned char* lds, const Gemm g, const Sched& S, const Epi& E, const int tid) {
;     ...
;             PG8_WAIT_V(8); PG8_WAIT_L(0); PG8_BAR; PG8_MMA(0, 0, At, B0); PG8_MMA(0, 1, At, B1); PG8_BAR; PG8_SCHED;
;             PG8_LDA(At, 0, 1); PG8_STAGE(PG8_SB(0, 0), b2, voffB); PG8_STAGE(PG8_SB(0, 1), b2 + hstep, voffB); PG8_STAGE(PG8_SA(0, 0), a2, voffA);
;             PG8_WAIT_V(8); PG8_WAIT_L(0); PG8_BAR; PG8_MMA(1, 0, At, B0); PG8_MMA(1, 1, At, B1); PG8_BAR; PG8_SCHED;
	v_mfma_f32_16x16x32_bf16 v[140:143], v[70:73], v[202:205], v[140:143]
	v_mfma_f32_16x16x32_bf16 v[136:139], v[172:175], v[202:205], v[136:139]
	v_mfma_f32_16x16x32_bf16 v[128:131], v[172:175], v[210:213], v[128:131]
	v_mfma_f32_16x16x32_bf16 v[132:135], v[70:73], v[210:213], v[132:135]
	v_mfma_f32_16x16x32_bf16 v[116:119], v[70:73], v[218:221], v[116:119]
	v_mfma_f32_16x16x32_bf16 v[112:115], v[172:175], v[218:221], v[112:115]
	v_mfma_f32_16x16x32_bf16 v[96:99], v[172:175], v[234:237], v[96:99]
	v_mfma_f32_16x16x32_bf16 v[100:103], v[70:73], v[234:237], v[100:103]
	v_mfma_f32_16x16x32_bf16 v[140:143], v[74:77], v[206:209], v[140:143]
	v_mfma_f32_16x16x32_bf16 v[136:139], v[176:179], v[206:209], v[136:139]
	v_mfma_f32_16x16x32_bf16 v[128:131], v[176:179], v[214:217], v[128:131]
	v_mfma_f32_16x16x32_bf16 v[132:135], v[74:77], v[214:217], v[132:135]
	v_mfma_f32_16x16x32_bf16 v[116:119], v[74:77], v[230:233], v[116:119]
	v_mfma_f32_16x16x32_bf16 v[112:115], v[176:179], v[230:233], v[112:115]
	v_mfma_f32_16x16x32_bf16 v[96:99], v[176:179], v[238:241], v[96:99]
	v_mfma_f32_16x16x32_bf16 v[100:103], v[74:77], v[238:241], v[100:103]
	v_mfma_f32_16x16x32_bf16 v[124:127], v[180:183], v[202:205], v[124:127]
	v_mfma_f32_16x16x32_bf16 v[120:123], v[188:191], v[202:205], v[120:123]
	v_mfma_f32_16x16x32_bf16 v[104:107], v[188:191], v[210:213], v[104:107]
	v_mfma_f32_16x16x32_bf16 v[108:111], v[180:183], v[210:213], v[108:111]
	v_mfma_f32_16x16x32_bf16 v[92:95], v[180:183], v[218:221], v[92:95]
	v_mfma_f32_16x16x32_bf16 v[88:91], v[188:191], v[218:221], v[88:91]
	v_mfma_f32_16x16x32_bf16 v[78:81], v[188:191], v[234:237], v[80:83]
	v_mfma_f32_16x16x32_bf16 v[84:87], v[180:183], v[234:237], v[84:87]
	v_mfma_f32_16x16x32_bf16 v[124:127], v[184:187], v[206:209], v[124:127]
	v_mfma_f32_16x16x32_bf16 v[120:123], v[198:201], v[206:209], v[120:123]
	v_mfma_f32_16x16x32_bf16 v[104:107], v[198:201], v[214:217], v[104:107]
	v_mfma_f32_16x16x32_bf16 v[108:111], v[184:187], v[214:217], v[108:111]
	v_mfma_f32_16x16x32_bf16 v[92:95], v[184:187], v[230:233], v[92:95]
	v_mfma_f32_16x16x32_bf16 v[88:91], v[198:201], v[230:233], v[88:91]
	v_mfma_f32_16x16x32_bf16 v[78:81], v[198:201], v[238:241], v[78:81]
	v_mfma_f32_16x16x32_bf16 v[84:87], v[184:187], v[238:241], v[84:87]
	s_barrier
	s_add_i32 s82, s82, s52
	v_lshl_add_u64 v[224:225], s[64:65], 0, v[164:165]
	s_mov_b32 m0, s82
	ds_read_b128 v[202:205], v171 offset:16384
	ds_read_b128 v[206:209], v171 offset:17408
	ds_read_b128 v[210:213], v171 offset:18432
	ds_read_b128 v[214:217], v171 offset:19456
	ds_read_b128 v[218:221], v171 offset:20480
	ds_read_b128 v[230:233], v171 offset:21504
	ds_read_b128 v[234:237], v171 offset:22528
	ds_read_b128 v[238:241], v171 offset:23552
	global_load_lds_dwordx4 v[224:225], off
	s_add_i32 m0, s82, 0x2000
	s_add_u32 s82, s64, 0x40000
	v_lshl_add_u64 v[226:227], s[64:65], 0, v[168:169]
	s_addc_u32 s83, s65, 0
	s_add_i32 s90, s90, s52
	global_load_lds_dwordx4 v[226:227], off
	v_lshl_add_u64 v[82:83], s[82:83], 0, v[164:165]
	s_mov_b32 m0, s90
	v_lshl_add_u64 v[242:243], s[66:67], 0, v[162:163]
	global_load_lds_dwordx4 v[82:83], off
	v_lshl_add_u64 v[82:83], s[82:83], 0, v[168:169]
	s_add_i32 m0, s90, 0x2000
	v_lshl_add_u64 v[244:245], s[66:67], 0, v[166:167]
	global_load_lds_dwordx4 v[82:83], off
	s_mov_b32 m0, s53
	s_nop 0
	global_load_lds_dwordx4 v[242:243], off
	s_mov_b32 m0, s56
	s_nop 0
	global_load_lds_dwordx4 v[244:245], off
	s_waitcnt vmcnt(8)
	s_waitcnt lgkmcnt(0)
	s_barrier
	v_mfma_f32_16x16x32_bf16 v[60:63], v[70:73], v[202:205], v[60:63]
	v_mfma_f32_16x16x32_bf16 v[56:59], v[172:175], v[202:205], v[56:59]
	v_mfma_f32_16x16x32_bf16 v[44:47], v[172:175], v[210:213], v[44:47]
	v_mfma_f32_16x16x32_bf16 v[52:55], v[70:73], v[210:213], v[52:55]
	v_mfma_f32_16x16x32_bf16 v[28:31], v[70:73], v[218:221], v[28:31]
	v_mfma_f32_16x16x32_bf16 v[24:27], v[172:175], v[218:221], v[24:27]
	v_mfma_f32_16x16x32_bf16 v[8:11], v[172:175], v[234:237], v[8:11]
	v_mfma_f32_16x16x32_bf16 v[16:19], v[70:73], v[234:237], v[16:19]
	v_mfma_f32_16x16x32_bf16 v[60:63], v[74:77], v[206:209], v[60:63]
	v_mfma_f32_16x16x32_bf16 v[56:59], v[176:179], v[206:209], v[56:59]
	v_mfma_f32_16x16x32_bf16 v[44:47], v[176:179], v[214:217], v[44:47]
	v_mfma_f32_16x16x32_bf16 v[52:55], v[74:77], v[214:217], v[52:55]
	v_mfma_f32_16x16x32_bf16 v[28:31], v[74:77], v[230:233], v[28:31]
	v_mfma_f32_16x16x32_bf16 v[24:27], v[176:179], v[230:233], v[24:27]
	v_mfma_f32_16x16x32_bf16 v[8:11], v[176:179], v[238:241], v[8:11]
	v_mfma_f32_16x16x32_bf16 v[16:19], v[74:77], v[238:241], v[16:19]
	v_mfma_f32_16x16x32_bf16 v[48:51], v[180:183], v[202:205], v[48:51]
	v_mfma_f32_16x16x32_bf16 v[40:43], v[188:191], v[202:205], v[40:43]
	v_mfma_f32_16x16x32_bf16 v[32:35], v[188:191], v[210:213], v[32:35]
	v_mfma_f32_16x16x32_bf16 v[36:39], v[180:183], v[210:213], v[36:39]
	v_mfma_f32_16x16x32_bf16 v[20:23], v[180:183], v[218:221], v[20:23]
	v_mfma_f32_16x16x32_bf16 v[12:15], v[188:191], v[218:221], v[12:15]
	v_mfma_f32_16x16x32_bf16 v[0:3], v[188:191], v[234:237], v[0:3]
	v_mfma_f32_16x16x32_bf16 v[4:7], v[180:183], v[234:237], v[4:7]
	v_mfma_f32_16x16x32_bf16 v[48:51], v[184:187], v[206:209], v[48:51]
	v_mfma_f32_16x16x32_bf16 v[40:43], v[198:201], v[206:209], v[40:43]
	v_mfma_f32_16x16x32_bf16 v[32:35], v[198:201], v[214:217], v[32:35]
	v_mfma_f32_16x16x32_bf16 v[36:39], v[184:187], v[214:217], v[36:39]
	v_mfma_f32_16x16x32_bf16 v[20:23], v[184:187], v[230:233], v[20:23]
	v_mfma_f32_16x16x32_bf16 v[12:15], v[198:201], v[230:233], v[12:15]
	v_mfma_f32_16x16x32_bf16 v[0:3], v[198:201], v[238:241], v[0:3]
	v_mfma_f32_16x16x32_bf16 v[4:7], v[184:187], v[238:241], v[4:7]
	s_barrier
; #define PG8_STAGE(bufoff, gbase, voff) do { _Pragma("unroll") for (int _i = 0; _i < 2; ++_i) \
;         __builtin_amdgcn_global_load_lds((const unsigned*)((const char*)(gbase) + (voff)[_i]), (LAS unsigned*)(lds + (bufoff) + ldsw + _i * 8192), 16, 0, 0); } while (0)
; #define PG8_LDA(dst, b, h) do { _Pragma("unroll") for (int m = 0; m < 4; ++m) _Pragma("unroll") for (int k = 0; k < 2; ++k) dst[m][k] = *(const LAS bf16x8*)(lds + PG8_SA(b, h) + aoff + m * 2048 + k * 1024); } while (0)
; #define PG8_LDB(dst, b, h) do { _Pragma("unroll") for (int n = 0; n < 2; ++n) _Pragma("unroll") for (int k = 0; k < 2; ++k) dst[n][k] = *(const LAS bf16x8*)(lds + PG8_SB(b, h) + boff + n * 2048 + k * 1024); } while (0)
; #define PG8_MMA(ai, bj, At, Bt) do { __builtin_amdgcn_s_setprio(1); _Pragma("unroll") for (int m = 0; m < 4; ++m) _Pragma("unroll") for (int n = 0; n < 2; ++n) _Pragma("unroll") for (int k = 0; k < 2; ++k) \
;         acc[ai][bj][m][n] = __builtin_amdgcn_mfma_f32_16x16x32_bf16(Bt[n][k], At[m][k], acc[ai][bj][m][n], 0, 0, 0); __builtin_amdgcn_s_setprio(0); } while (0)
; #define PG8_WAIT_V(n) asm volatile("s_waitcnt vmcnt(" #n ")" ::: "memory")
; #define PG8_WAIT_L(n) asm volatile("s_waitcnt lgkmcnt(" #n ")" ::: "memory")
; #define PG8_BAR __builtin_amdgcn_s_barrier()
; #define PG8_SCHED __builtin_amdgcn_sched_barrier(0)
; template <class Epi, class Sched>
; __device__ __forceinline__ void gemm_phase(LAS unsigned char* lds, const Gemm g, const Sched& S, const Epi& E, const int tid) {
;     ...
;             PG8_LDB(B0, 1, 0); PG8_LDB(B1, 1, 1); PG8_SCHED; PG8_LDA(At, 1, 0); PG8_STAGE(PG8_SA(0, 1), a2 + hstep, voffA);
;             PG8_WAIT_V(8); PG8_WAIT_L(0); PG8_BAR; PG8_MMA(0, 0, At, B0); PG8_MMA(0, 1, At, B1); PG8_BAR; PG8_SCHED;
;             PG8_LDA(At, 1, 1); PG8_STAGE(PG8_SB(1, 0), b3, voffB); PG8_STAGE(PG8_SB(1, 1), b3 + hstep, voffB); PG8_STAGE(PG8_SA(1, 0), a3, voffA);
;             PG8_WAIT_V(8); PG8_WAIT_L(0); PG8_BAR; PG8_MMA(1, 0, At, B0); PG8_MMA(1, 1, At, B1); PG8_BAR; PG8_SCHED;
;         }
;         if (wr == 0) PG8_BAR;
	s_add_i32 s82, 0, 0x18000
	v_add_u32_e32 v69, s82, v154
	s_add_i32 s83, 0, 0x1c000
	ds_read_b128 v[70:73], v69
	ds_read_b128 v[74:77], v69 offset:1024
	ds_read_b128 v[172:175], v69 offset:2048
	ds_read_b128 v[176:179], v69 offset:3072
	v_add_u32_e32 v69, s83, v154
	ds_read_b128 v[180:183], v69
	ds_read_b128 v[184:187], v69 offset:1024
	ds_read_b128 v[188:191], v69 offset:2048
	ds_read_b128 v[198:201], v69 offset:3072
	s_add_u32 s66, s66, 0x40000
	s_addc_u32 s67, s67, 0
	s_mov_b32 m0, s57
	v_lshl_add_u64 v[82:83], s[66:67], 0, v[162:163]
	ds_read_b128 v[202:205], v171 offset:32768
	ds_read_b128 v[206:209], v171 offset:33792
	ds_read_b128 v[210:213], v171 offset:34816
	ds_read_b128 v[214:217], v171 offset:35840
	ds_read_b128 v[218:221], v171 offset:36864
	ds_read_b128 v[230:233], v171 offset:37888
	ds_read_b128 v[234:237], v171 offset:38912
	ds_read_b128 v[238:241], v171 offset:39936
	global_load_lds_dwordx4 v[82:83], off
	v_lshl_add_u64 v[82:83], s[66:67], 0, v[166:167]
	s_mov_b32 m0, s58
	s_nop 0
	global_load_lds_dwordx4 v[82:83], off
	s_waitcnt vmcnt(8)
	s_waitcnt lgkmcnt(0)
	s_barrier
	v_mfma_f32_16x16x32_bf16 v[140:143], v[70:73], v[202:205], v[140:143]
	v_mfma_f32_16x16x32_bf16 v[136:139], v[172:175], v[202:205], v[136:139]
	v_mfma_f32_16x16x32_bf16 v[128:131], v[172:175], v[210:213], v[128:131]
	v_mfma_f32_16x16x32_bf16 v[132:135], v[70:73], v[210:213], v[132:135]
	v_mfma_f32_16x16x32_bf16 v[116:119], v[70:73], v[218:221], v[116:119]
	v_mfma_f32_16x16x32_bf16 v[112:115], v[172:175], v[218:221], v[112:115]
	v_mfma_f32_16x16x32_bf16 v[96:99], v[172:175], v[234:237], v[96:99]
	v_mfma_f32_16x16x32_bf16 v[100:103], v[70:73], v[234:237], v[100:103]
	v_mfma_f32_16x16x32_bf16 v[140:143], v[74:77], v[206:209], v[140:143]
	v_mfma_f32_16x16x32_bf16 v[136:139], v[176:179], v[206:209], v[136:139]
	v_mfma_f32_16x16x32_bf16 v[128:131], v[176:179], v[214:217], v[128:131]
	v_mfma_f32_16x16x32_bf16 v[132:135], v[74:77], v[214:217], v[132:135]
	v_mfma_f32_16x16x32_bf16 v[116:119], v[74:77], v[230:233], v[116:119]
	v_mfma_f32_16x16x32_bf16 v[112:115], v[176:179], v[230:233], v[112:115]
	v_mfma_f32_16x16x32_bf16 v[96:99], v[176:179], v[238:241], v[96:99]
	v_mfma_f32_16x16x32_bf16 v[100:103], v[74:77], v[238:241], v[100:103]
	v_mfma_f32_16x16x32_bf16 v[124:127], v[180:183], v[202:205], v[124:127]
	v_mfma_f32_16x16x32_bf16 v[120:123], v[188:191], v[202:205], v[120:123]
	v_mfma_f32_16x16x32_bf16 v[104:107], v[188:191], v[210:213], v[104:107]
	v_mfma_f32_16x16x32_bf16 v[108:111], v[180:183], v[210:213], v[108:111]
	v_mfma_f32_16x16x32_bf16 v[92:95], v[180:183], v[218:221], v[92:95]
	v_mfma_f32_16x16x32_bf16 v[88:91], v[188:191], v[218:221], v[88:91]
	v_mfma_f32_16x16x32_bf16 v[78:81], v[188:191], v[234:237], v[78:81]
	v_mfma_f32_16x16x32_bf16 v[82:85], v[180:183], v[234:237], v[84:87]
	v_mfma_f32_16x16x32_bf16 v[124:127], v[184:187], v[206:209], v[124:127]
	v_mfma_f32_16x16x32_bf16 v[120:123], v[198:201], v[206:209], v[120:123]
	v_mfma_f32_16x16x32_bf16 v[104:107], v[198:201], v[214:217], v[104:107]
	v_mfma_f32_16x16x32_bf16 v[108:111], v[184:187], v[214:217], v[108:111]
	v_mfma_f32_16x16x32_bf16 v[92:95], v[184:187], v[230:233], v[92:95]
	v_mfma_f32_16x16x32_bf16 v[88:91], v[198:201], v[230:233], v[88:91]
	v_mfma_f32_16x16x32_bf16 v[80:83], v[198:201], v[238:241], v[78:81]
	v_mfma_f32_16x16x32_bf16 v[84:87], v[184:187], v[238:241], v[82:85]
	s_barrier
	s_add_i32 s66, s82, s52
	v_lshl_add_u64 v[78:79], v[224:225], 0, s[68:69]
	s_mov_b32 m0, s66
	ds_read_b128 v[202:205], v171 offset:49152
	ds_read_b128 v[206:209], v171 offset:50176
	ds_read_b128 v[210:213], v171 offset:51200
	ds_read_b128 v[214:217], v171 offset:52224
	ds_read_b128 v[218:221], v171 offset:53248
	ds_read_b128 v[230:233], v171 offset:54272
	ds_read_b128 v[234:237], v171 offset:55296
	ds_read_b128 v[238:241], v171 offset:56320
	global_load_lds_dwordx4 v[78:79], off
	s_add_i32 m0, s66, 0x2000
	s_add_u32 s64, s64, 0x40080
	v_lshl_add_u64 v[78:79], v[226:227], 0, s[68:69]
	s_addc_u32 s65, s65, 0
	s_add_i32 s66, s83, s52
	global_load_lds_dwordx4 v[78:79], off
	v_lshl_add_u64 v[78:79], s[64:65], 0, v[164:165]
	s_mov_b32 m0, s66
	s_nop 0
	global_load_lds_dwordx4 v[78:79], off
	v_lshl_add_u64 v[78:79], s[64:65], 0, v[168:169]
	s_add_i32 m0, s66, 0x2000
	s_nop 0
	global_load_lds_dwordx4 v[78:79], off
	v_lshl_add_u64 v[78:79], v[242:243], 0, s[68:69]
	s_mov_b32 m0, s61
	s_nop 0
	global_load_lds_dwordx4 v[78:79], off
	v_lshl_add_u64 v[78:79], v[244:245], 0, s[68:69]
	s_mov_b32 m0, s70
	s_nop 0
	global_load_lds_dwordx4 v[78:79], off
	s_waitcnt vmcnt(8)
	s_waitcnt lgkmcnt(0)
	s_barrier
	v_mfma_f32_16x16x32_bf16 v[60:63], v[70:73], v[202:205], v[60:63]
	v_mfma_f32_16x16x32_bf16 v[56:59], v[172:175], v[202:205], v[56:59]
	v_mfma_f32_16x16x32_bf16 v[44:47], v[172:175], v[210:213], v[44:47]
	v_mfma_f32_16x16x32_bf16 v[52:55], v[70:73], v[210:213], v[52:55]
	v_mfma_f32_16x16x32_bf16 v[28:31], v[70:73], v[218:221], v[28:31]
	v_mfma_f32_16x16x32_bf16 v[24:27], v[172:175], v[218:221], v[24:27]
	v_mfma_f32_16x16x32_bf16 v[8:11], v[172:175], v[234:237], v[8:11]
	v_mfma_f32_16x16x32_bf16 v[16:19], v[70:73], v[234:237], v[16:19]
	v_mfma_f32_16x16x32_bf16 v[60:63], v[74:77], v[206:209], v[60:63]
	v_mfma_f32_16x16x32_bf16 v[56:59], v[176:179], v[206:209], v[56:59]
	v_mfma_f32_16x16x32_bf16 v[44:47], v[176:179], v[214:217], v[44:47]
	v_mfma_f32_16x16x32_bf16 v[52:55], v[74:77], v[214:217], v[52:55]
	v_mfma_f32_16x16x32_bf16 v[28:31], v[74:77], v[230:233], v[28:31]
	v_mfma_f32_16x16x32_bf16 v[24:27], v[176:179], v[230:233], v[24:27]
	v_mfma_f32_16x16x32_bf16 v[8:11], v[176:179], v[238:241], v[8:11]
	v_mfma_f32_16x16x32_bf16 v[16:19], v[74:77], v[238:241], v[16:19]
	v_mfma_f32_16x16x32_bf16 v[48:51], v[180:183], v[202:205], v[48:51]
	v_mfma_f32_16x16x32_bf16 v[40:43], v[188:191], v[202:205], v[40:43]
	v_mfma_f32_16x16x32_bf16 v[32:35], v[188:191], v[210:213], v[32:35]
	v_mfma_f32_16x16x32_bf16 v[36:39], v[180:183], v[210:213], v[36:39]
	v_mfma_f32_16x16x32_bf16 v[20:23], v[180:183], v[218:221], v[20:23]
	v_mfma_f32_16x16x32_bf16 v[12:15], v[188:191], v[218:221], v[12:15]
	v_mfma_f32_16x16x32_bf16 v[0:3], v[188:191], v[234:237], v[0:3]
	v_mfma_f32_16x16x32_bf16 v[4:7], v[180:183], v[234:237], v[4:7]
	v_mfma_f32_16x16x32_bf16 v[48:51], v[184:187], v[206:209], v[48:51]
	v_mfma_f32_16x16x32_bf16 v[40:43], v[198:201], v[206:209], v[40:43]
	v_mfma_f32_16x16x32_bf16 v[32:35], v[198:201], v[214:217], v[32:35]
	v_mfma_f32_16x16x32_bf16 v[36:39], v[184:187], v[214:217], v[36:39]
	v_mfma_f32_16x16x32_bf16 v[20:23], v[184:187], v[230:233], v[20:23]
	v_mfma_f32_16x16x32_bf16 v[12:15], v[198:201], v[230:233], v[12:15]
	v_mfma_f32_16x16x32_bf16 v[0:3], v[198:201], v[238:241], v[0:3]
	v_mfma_f32_16x16x32_bf16 v[4:7], v[184:187], v[238:241], v[4:7]
	s_barrier
	s_add_i32 s81, s81, 2
	s_add_u32 s62, s62, 0x100
	s_addc_u32 s63, s63, 0
	s_add_u32 s78, s78, 0x100
	s_addc_u32 s79, s79, 0
	s_cmp_gt_u32 s81, 13
	s_cbranch_scc0 .LBB0_326
	s_and_b64 vcc, exec, s[8:9]
	s_cbranch_vccz .LBB0_329
	s_barrier

;     __device__ __forceinline__ Pre prefetch(const Unit& u, int tid) const { return prenorm_load(stats, u.pn * BM, sW + (size_t)(u.pn >> 4) * SW_ROWS + u.pm * BM, tid); }
;     __device__ __forceinline__ Pre prefetch(const Unit& u, int tid) const { return prenorm_load(stats, u.pm * BM, sW + (size_t)(u.pm >> 4) * SW_ROWS + u.pn * BM, tid); }
;     __device__ __forceinline__ Pre prefetch(const Unit& u, int tid) const { return prenorm_load(stats, u.pm * BM, sW + (size_t)(u.pm >> 4) * SW_ROWS + u.pn * BM, tid); }
; #define PG8_STAGE(bufoff, gbase, voff) do { _Pragma("unroll") for (int _i = 0; _i < 2; ++_i) \
;         __builtin_amdgcn_global_load_lds((const unsigned*)((const char*)(gbase) + (voff)[_i]), (LAS unsigned*)(lds + (bufoff) + ldsw + _i * 8192), 16, 0, 0); } while (0)
; #define PG8_LDA(dst, b, h) do { _Pragma("unroll") for (int m = 0; m < 4; ++m) _Pragma("unroll") for (int k = 0; k < 2; ++k) dst[m][k] = *(const LAS bf16x8*)(lds + PG8_SA(b, h) + aoff + m * 2048 + k * 1024); } while (0)
; #define PG8_WAIT_V(n) asm volatile("s_waitcnt vmcnt(" #n ")" ::: "memory")
; #define PG8_WAIT_L(n) asm volatile("s_waitcnt lgkmcnt(" #n ")" ::: "memory")
; template <class Epi, class Sched>
; __device__ __forceinline__ void gemm_phase(LAS unsigned char* lds, const Gemm g, const Sched& S, const Epi& E, const int tid) {
;     ...
;         const bool has_next = S.next(ui + 1, nxt);
;         const char* nA = has_next ? (const char*)g.A + (size_t)nxt.pm * tstep : cA; const char* nB = has_next ? (const char*)g.Bt + (size_t)nxt.pn * tstep : cB;
;         const typename Epi::Pre pre = E.prefetch(cur, tid);
;         for (int t = 0; t < nt; t += 2) {
;             const bool last = (t == nt - 2);
;             const char* a1 = cA + (size_t)(t + 1) * kstep;
;             const char* a2 = last ? nA : cA + (size_t)(t + 2) * kstep; const char* b2 = last ? nB : cB + (size_t)(t + 2) * kstep;
;             const char* a3 = a2 + kstep; const char* b3 = b2 + kstep;
;             PG8_LDB(B0, 0, 0); PG8_LDB(B1, 0, 1); PG8_SCHED; PG8_LDA(At, 0, 0); PG8_STAGE(PG8_SA(1, 1), a1 + hstep, voffA);
;             PG8_WAIT_V(8); PG8_WAIT_L(0); PG8_BAR; PG8_MMA(0, 0, At, B0); PG8_MMA(0, 1, At, B1); PG8_BAR; PG8_SCHED;
;             PG8_LDA(At, 0, 1); PG8_STAGE(PG8_SB(0, 0), b2, voffB); PG8_STAGE(PG8_SB(0, 1), b2 + hstep, voffB); PG8_STAGE(PG8_SA(0, 0), a2, voffA);
.LBB0_565:
.LBB0_566:
	s_or_b64 exec, exec, s[82:83]
	s_add_u32 vcc_lo, s80, 0x80
	s_addc_u32 vcc_hi, s81, 0
	s_add_u32 s61, s74, 0x100
	s_addc_u32 s67, s75, 0
	s_mov_b32 s74, 0
	s_add_i32 s80, s74, 2
	s_add_u32 s81, vcc_lo, 0x80
	s_addc_u32 s75, vcc_hi, 0
	s_add_i32 s3, 0, 0x10000
	s_cmp_eq_u32 s57, s74
	s_cselect_b32 s75, s71, s75
	s_cselect_b32 s74, s70, s81
	v_add_u32_e32 v70, s3, v232
	s_cselect_b32 s83, s73, s67
	s_cselect_b32 s82, s72, s61
	s_add_i32 s81, 0, 0x14000
	ds_read_b128 v[58:61], v70
	ds_read_b128 v[62:65], v70 offset:1024
	ds_read_b128 v[66:69], v70 offset:2048
	ds_read_b128 v[80:83], v70 offset:3072
	v_add_u32_e32 v70, s81, v232
	ds_read_b128 v[84:87], v70
	ds_read_b128 v[88:91], v70 offset:1024
	ds_read_b128 v[92:95], v70 offset:2048
	ds_read_b128 v[152:155], v70 offset:3072
	v_lshl_add_u64 v[70:71], vcc, 0, v[204:205]
	s_add_i32 m0, s97, 0xc000
	ds_read_b128 v[164:167], v240
	ds_read_b128 v[168:171], v240 offset:1024
	ds_read_b128 v[172:175], v240 offset:2048
	ds_read_b128 v[176:179], v240 offset:3072
	ds_read_b128 v[180:183], v240 offset:4096
	ds_read_b128 v[184:187], v240 offset:5120
	ds_read_b128 v[188:191], v240 offset:6144
	ds_read_b128 v[208:211], v240 offset:7168
	global_load_lds_dwordx4 v[70:71], off
	v_lshl_add_u64 v[70:71], vcc, 0, v[206:207]
	s_add_i32 m0, s97, 0xe000
	s_nop 0
	global_load_lds_dwordx4 v[70:71], off
	s_waitcnt vmcnt(8)
	s_waitcnt lgkmcnt(0)
	s_barrier
	v_mfma_f32_16x16x32_bf16 v[160:163], v[58:61], v[164:167], 0
	v_mfma_f32_16x16x32_bf16 v[156:159], v[66:69], v[164:167], 0
	v_mfma_f32_16x16x32_bf16 v[136:139], v[66:69], v[172:175], 0
	v_mfma_f32_16x16x32_bf16 v[140:143], v[58:61], v[172:175], 0
	v_mfma_f32_16x16x32_bf16 v[124:127], v[58:61], v[180:183], 0
	v_mfma_f32_16x16x32_bf16 v[120:123], v[66:69], v[180:183], 0
	v_mfma_f32_16x16x32_bf16 v[104:107], v[66:69], v[188:191], 0
	v_mfma_f32_16x16x32_bf16 v[108:111], v[58:61], v[188:191], 0
	v_mfma_f32_16x16x32_bf16 v[160:163], v[62:65], v[168:171], v[160:163]
	v_mfma_f32_16x16x32_bf16 v[156:159], v[80:83], v[168:171], v[156:159]
	v_mfma_f32_16x16x32_bf16 v[136:139], v[80:83], v[176:179], v[136:139]
	v_mfma_f32_16x16x32_bf16 v[140:143], v[62:65], v[176:179], v[140:143]
	v_mfma_f32_16x16x32_bf16 v[124:127], v[62:65], v[184:187], v[124:127]
	v_mfma_f32_16x16x32_bf16 v[120:123], v[80:83], v[184:187], v[120:123]
	v_mfma_f32_16x16x32_bf16 v[104:107], v[80:83], v[208:211], v[104:107]
	v_mfma_f32_16x16x32_bf16 v[108:111], v[62:65], v[208:211], v[108:111]
	v_mfma_f32_16x16x32_bf16 v[148:151], v[84:87], v[164:167], 0
	v_mfma_f32_16x16x32_bf16 v[144:147], v[92:95], v[164:167], 0
	v_mfma_f32_16x16x32_bf16 v[128:131], v[92:95], v[172:175], 0
	v_mfma_f32_16x16x32_bf16 v[132:135], v[84:87], v[172:175], 0
	v_mfma_f32_16x16x32_bf16 v[116:119], v[84:87], v[180:183], 0
	v_mfma_f32_16x16x32_bf16 v[112:115], v[92:95], v[180:183], 0
	v_mfma_f32_16x16x32_bf16 v[96:99], v[92:95], v[188:191], 0
	v_mfma_f32_16x16x32_bf16 v[100:103], v[84:87], v[188:191], 0
	v_mfma_f32_16x16x32_bf16 v[148:151], v[88:91], v[168:171], v[148:151]
	v_mfma_f32_16x16x32_bf16 v[144:147], v[152:155], v[168:171], v[144:147]
	v_mfma_f32_16x16x32_bf16 v[128:131], v[152:155], v[176:179], v[128:131]
	v_mfma_f32_16x16x32_bf16 v[132:135], v[88:91], v[176:179], v[132:135]
	v_mfma_f32_16x16x32_bf16 v[116:119], v[88:91], v[184:187], v[116:119]
	v_mfma_f32_16x16x32_bf16 v[112:115], v[152:155], v[184:187], v[112:115]
	v_mfma_f32_16x16x32_bf16 v[96:99], v[152:155], v[208:211], v[96:99]
	v_mfma_f32_16x16x32_bf16 v[100:103], v[88:91], v[208:211], v[100:103]
	s_barrier
	s_add_i32 s3, s3, s94
	v_lshl_add_u64 v[212:213], s[82:83], 0, v[192:193]
	s_mov_b32 m0, s3
	ds_read_b128 v[164:167], v240 offset:16384
	ds_read_b128 v[168:171], v240 offset:17408
	ds_read_b128 v[172:175], v240 offset:18432
	ds_read_b128 v[176:179], v240 offset:19456
	ds_read_b128 v[180:183], v240 offset:20480
	ds_read_b128 v[184:187], v240 offset:21504
	ds_read_b128 v[188:191], v240 offset:22528
	ds_read_b128 v[208:211], v240 offset:23552
	global_load_lds_dwordx4 v[212:213], off
	s_add_i32 m0, s3, 0x2000
	v_lshl_add_u64 v[214:215], s[82:83], 0, v[198:199]
	s_add_u32 s82, s82, s12
	s_addc_u32 s83, s83, 0
	s_add_i32 s3, s81, s94
	global_load_lds_dwordx4 v[214:215], off
	v_lshl_add_u64 v[216:217], s[82:83], 0, v[192:193]
	s_mov_b32 m0, s3
	v_lshl_add_u64 v[218:219], s[82:83], 0, v[198:199]
	global_load_lds_dwordx4 v[216:217], off
	s_add_i32 m0, s3, 0x2000
	v_lshl_add_u64 v[220:221], s[74:75], 0, v[202:203]
	global_load_lds_dwordx4 v[218:219], off
	s_mov_b32 m0, s97
	v_lshl_add_u64 v[224:225], s[74:75], 0, v[200:201]
	global_load_lds_dwordx4 v[220:221], off
	s_mov_b32 m0, s98
	s_nop 0
	global_load_lds_dwordx4 v[224:225], off
	s_waitcnt vmcnt(8)
	s_waitcnt lgkmcnt(0)
	s_barrier
; #define PG8_STAGE(bufoff, gbase, voff) do { _Pragma("unroll") for (int _i = 0; _i < 2; ++_i) \
;         __builtin_amdgcn_global_load_lds((const unsigned*)((const char*)(gbase) + (voff)[_i]), (LAS unsigned*)(lds + (bufoff) + ldsw + _i * 8192), 16, 0, 0); } while (0)
; #define PG8_LDA(dst, b, h) do { _Pragma("unroll") for (int m = 0; m < 4; ++m) _Pragma("unroll") for (int k = 0; k < 2; ++k) dst[m][k] = *(const LAS bf16x8*)(lds + PG8_SA(b, h) + aoff + m * 2048 + k * 1024); } while (0)
; #define PG8_LDB(dst, b, h) do { _Pragma("unroll") for (int n = 0; n < 2; ++n) _Pragma("unroll") for (int k = 0; k < 2; ++k) dst[n][k] = *(const LAS bf16x8*)(lds + PG8_SB(b, h) + boff + n * 2048 + k * 1024); } while (0)
; #define PG8_MMA(ai, bj, At, Bt) do { __builtin_amdgcn_s_setprio(1); _Pragma("unroll") for (int m = 0; m < 4; ++m) _Pragma("unroll") for (int n = 0; n < 2; ++n) _Pragma("unroll") for (int k = 0; k < 2; ++k) \
;         acc[ai][bj][m][n] = __builtin_amdgcn_mfma_f32_16x16x32_bf16(Bt[n][k], At[m][k], acc[ai][bj][m][n], 0, 0, 0); __builtin_amdgcn_s_setprio(0); } while (0)
; #define PG8_WAIT_V(n) asm volatile("s_waitcnt vmcnt(" #n ")" ::: "memory")
; #define PG8_WAIT_L(n) asm volatile("s_waitcnt lgkmcnt(" #n ")" ::: "memory")
; #define PG8_BAR __builtin_amdgcn_s_barrier()
; #define PG8_SCHED __builtin_amdgcn_sched_barrier(0)
; template <class Epi, class Sched>
; __device__ __forceinline__ void gemm_phase(LAS unsigned char* lds, const Gemm g, const Sched& S, const Epi& E, const int tid) {
;     ...
;             PG8_WAIT_V(8); PG8_WAIT_L(0); PG8_BAR; PG8_MMA(1, 0, At, B0); PG8_MMA(1, 1, At, B1); PG8_BAR; PG8_SCHED;
;             PG8_LDB(B0, 1, 0); PG8_LDB(B1, 1, 1); PG8_SCHED; PG8_LDA(At, 1, 0); PG8_STAGE(PG8_SA(0, 1), a2 + hstep, voffA);
;             PG8_WAIT_V(8); PG8_WAIT_L(0); PG8_BAR; PG8_MMA(0, 0, At, B0); PG8_MMA(0, 1, At, B1); PG8_BAR; PG8_SCHED;
	v_mfma_f32_16x16x32_bf16 v[76:79], v[58:61], v[164:167], 0
	v_mfma_f32_16x16x32_bf16 v[70:73], v[66:69], v[164:167], 0
	v_mfma_f32_16x16x32_bf16 v[40:43], v[66:69], v[172:175], 0
	v_mfma_f32_16x16x32_bf16 v[44:47], v[58:61], v[172:175], 0
	v_mfma_f32_16x16x32_bf16 v[28:31], v[58:61], v[180:183], 0
	v_mfma_f32_16x16x32_bf16 v[24:27], v[66:69], v[180:183], 0
	v_mfma_f32_16x16x32_bf16 v[8:11], v[66:69], v[188:191], 0
	v_mfma_f32_16x16x32_bf16 v[12:15], v[58:61], v[188:191], 0
	v_mfma_f32_16x16x32_bf16 v[76:79], v[62:65], v[168:171], v[76:79]
	v_mfma_f32_16x16x32_bf16 v[70:73], v[80:83], v[168:171], v[70:73]
	v_mfma_f32_16x16x32_bf16 v[40:43], v[80:83], v[176:179], v[40:43]
	v_mfma_f32_16x16x32_bf16 v[44:47], v[62:65], v[176:179], v[44:47]
	v_mfma_f32_16x16x32_bf16 v[28:31], v[62:65], v[184:187], v[28:31]
	v_mfma_f32_16x16x32_bf16 v[24:27], v[80:83], v[184:187], v[24:27]
	v_mfma_f32_16x16x32_bf16 v[8:11], v[80:83], v[208:211], v[8:11]
	v_mfma_f32_16x16x32_bf16 v[12:15], v[62:65], v[208:211], v[12:15]
	v_mfma_f32_16x16x32_bf16 v[52:55], v[84:87], v[164:167], 0
	v_mfma_f32_16x16x32_bf16 v[48:51], v[92:95], v[164:167], 0
	v_mfma_f32_16x16x32_bf16 v[32:35], v[92:95], v[172:175], 0
	v_mfma_f32_16x16x32_bf16 v[36:39], v[84:87], v[172:175], 0
	v_mfma_f32_16x16x32_bf16 v[20:23], v[84:87], v[180:183], 0
	v_mfma_f32_16x16x32_bf16 v[16:19], v[92:95], v[180:183], 0
	v_mfma_f32_16x16x32_bf16 v[0:3], v[92:95], v[188:191], 0
	v_mfma_f32_16x16x32_bf16 v[4:7], v[84:87], v[188:191], 0
	v_mfma_f32_16x16x32_bf16 v[52:55], v[88:91], v[168:171], v[52:55]
	v_mfma_f32_16x16x32_bf16 v[48:51], v[152:155], v[168:171], v[48:51]
	v_mfma_f32_16x16x32_bf16 v[32:35], v[152:155], v[176:179], v[32:35]
	v_mfma_f32_16x16x32_bf16 v[36:39], v[88:91], v[176:179], v[36:39]
	v_mfma_f32_16x16x32_bf16 v[20:23], v[88:91], v[184:187], v[20:23]
	v_mfma_f32_16x16x32_bf16 v[16:19], v[152:155], v[184:187], v[16:19]
	v_mfma_f32_16x16x32_bf16 v[0:3], v[152:155], v[208:211], v[0:3]
	v_mfma_f32_16x16x32_bf16 v[4:7], v[88:91], v[208:211], v[4:7]
	s_barrier
	s_add_i32 s3, 0, 0x18000
	v_add_u32_e32 v74, s3, v232
	s_add_i32 s81, 0, 0x1c000
	ds_read_b128 v[58:61], v74
	ds_read_b128 v[62:65], v74 offset:1024
	ds_read_b128 v[66:69], v74 offset:2048
	ds_read_b128 v[80:83], v74 offset:3072
	v_add_u32_e32 v74, s81, v232
	ds_read_b128 v[84:87], v74
	ds_read_b128 v[88:91], v74 offset:1024
	ds_read_b128 v[92:95], v74 offset:2048
	ds_read_b128 v[152:155], v74 offset:3072
	s_add_u32 s74, s74, s12
	s_addc_u32 s75, s75, 0
	s_mov_b32 m0, s99
	v_lshl_add_u64 v[74:75], s[74:75], 0, v[202:203]
	ds_read_b128 v[164:167], v240 offset:32768
	ds_read_b128 v[168:171], v240 offset:33792
	ds_read_b128 v[172:175], v240 offset:34816
	ds_read_b128 v[176:179], v240 offset:35840
	ds_read_b128 v[180:183], v240 offset:36864
	ds_read_b128 v[184:187], v240 offset:37888
	ds_read_b128 v[188:191], v240 offset:38912
	ds_read_b128 v[208:211], v240 offset:39936
	global_load_lds_dwordx4 v[74:75], off
	v_lshl_add_u64 v[74:75], s[74:75], 0, v[200:201]
	s_mov_b32 m0, s78
	s_nop 0
	global_load_lds_dwordx4 v[74:75], off
	s_waitcnt vmcnt(8)
	s_waitcnt lgkmcnt(0)
	s_barrier
	v_mfma_f32_16x16x32_bf16 v[160:163], v[58:61], v[164:167], v[160:163]
	v_mfma_f32_16x16x32_bf16 v[156:159], v[66:69], v[164:167], v[156:159]
	v_mfma_f32_16x16x32_bf16 v[136:139], v[66:69], v[172:175], v[136:139]
	v_mfma_f32_16x16x32_bf16 v[140:143], v[58:61], v[172:175], v[140:143]
	v_mfma_f32_16x16x32_bf16 v[124:127], v[58:61], v[180:183], v[124:127]
	v_mfma_f32_16x16x32_bf16 v[120:123], v[66:69], v[180:183], v[120:123]
	v_mfma_f32_16x16x32_bf16 v[104:107], v[66:69], v[188:191], v[104:107]
	v_mfma_f32_16x16x32_bf16 v[108:111], v[58:61], v[188:191], v[108:111]
	v_mfma_f32_16x16x32_bf16 v[160:163], v[62:65], v[168:171], v[160:163]
	v_mfma_f32_16x16x32_bf16 v[156:159], v[80:83], v[168:171], v[156:159]
	v_mfma_f32_16x16x32_bf16 v[136:139], v[80:83], v[176:179], v[136:139]
	v_mfma_f32_16x16x32_bf16 v[140:143], v[62:65], v[176:179], v[140:143]
	v_mfma_f32_16x16x32_bf16 v[124:127], v[62:65], v[184:187], v[124:127]
	v_mfma_f32_16x16x32_bf16 v[120:123], v[80:83], v[184:187], v[120:123]
	v_mfma_f32_16x16x32_bf16 v[104:107], v[80:83], v[208:211], v[104:107]
	v_mfma_f32_16x16x32_bf16 v[108:111], v[62:65], v[208:211], v[108:111]
	v_mfma_f32_16x16x32_bf16 v[148:151], v[84:87], v[164:167], v[148:151]
	v_mfma_f32_16x16x32_bf16 v[144:147], v[92:95], v[164:167], v[144:147]
	v_mfma_f32_16x16x32_bf16 v[128:131], v[92:95], v[172:175], v[128:131]
	v_mfma_f32_16x16x32_bf16 v[132:135], v[84:87], v[172:175], v[132:135]
	v_mfma_f32_16x16x32_bf16 v[116:119], v[84:87], v[180:183], v[116:119]
	v_mfma_f32_16x16x32_bf16 v[112:115], v[92:95], v[180:183], v[112:115]
	v_mfma_f32_16x16x32_bf16 v[96:99], v[92:95], v[188:191], v[96:99]
	v_mfma_f32_16x16x32_bf16 v[100:103], v[84:87], v[188:191], v[100:103]
	v_mfma_f32_16x16x32_bf16 v[148:151], v[88:91], v[168:171], v[148:151]
	v_mfma_f32_16x16x32_bf16 v[144:147], v[152:155], v[168:171], v[144:147]
	v_mfma_f32_16x16x32_bf16 v[128:131], v[152:155], v[176:179], v[128:131]
	v_mfma_f32_16x16x32_bf16 v[132:135], v[88:91], v[176:179], v[132:135]
	v_mfma_f32_16x16x32_bf16 v[116:119], v[88:91], v[184:187], v[116:119]
	v_mfma_f32_16x16x32_bf16 v[112:115], v[152:155], v[184:187], v[112:115]
	v_mfma_f32_16x16x32_bf16 v[96:99], v[152:155], v[208:211], v[96:99]
	v_mfma_f32_16x16x32_bf16 v[100:103], v[88:91], v[208:211], v[100:103]
	s_barrier
; #define PG8_STAGE(bufoff, gbase, voff) do { _Pragma("unroll") for (int _i = 0; _i < 2; ++_i) \
;         __builtin_amdgcn_global_load_lds((const unsigned*)((const char*)(gbase) + (voff)[_i]), (LAS unsigned*)(lds + (bufoff) + ldsw + _i * 8192), 16, 0, 0); } while (0)
; #define PG8_LDA(dst, b, h) do { _Pragma("unroll") for (int m = 0; m < 4; ++m) _Pragma("unroll") for (int k = 0; k < 2; ++k) dst[m][k] = *(const LAS bf16x8*)(lds + PG8_SA(b, h) + aoff + m * 2048 + k * 1024); } while (0)
; #define PG8_LDB(dst, b, h) do { _Pragma("unroll") for (int n = 0; n < 2; ++n) _Pragma("unroll") for (int k = 0; k < 2; ++k) dst[n][k] = *(const LAS bf16x8*)(lds + PG8_SB(b, h) + boff + n * 2048 + k * 1024); } while (0)
; #define PG8_WAIT_V(n) asm volatile("s_waitcnt vmcnt(" #n ")" ::: "memory")
; #define PG8_BAR __builtin_amdgcn_s_barrier()
; template <class Epi, class Sched>
; __device__ __forceinline__ void gemm_phase(LAS unsigned char* lds, const Gemm g, const Sched& S, const Epi& E, const int tid) {
;     ...
;         for (int t = 0; t < nt; t += 2) {
;             const bool last = (t == nt - 2);
;             const char* a1 = cA + (size_t)(t + 1) * kstep;
;             const char* a2 = last ? nA : cA + (size_t)(t + 2) * kstep; const char* b2 = last ? nB : cB + (size_t)(t + 2) * kstep;
;             const char* a3 = a2 + kstep; const char* b3 = b2 + kstep;
;             PG8_LDB(B0, 0, 0); PG8_LDB(B1, 0, 1); PG8_SCHED; PG8_LDA(At, 0, 0); PG8_STAGE(PG8_SA(1, 1), a1 + hstep, voffA);
;             PG8_WAIT_V(8); PG8_WAIT_L(0); PG8_BAR; PG8_MMA(0, 0, At, B0); PG8_MMA(0, 1, At, B1); PG8_BAR; PG8_SCHED;
;             PG8_LDA(At, 0, 1); PG8_STAGE(PG8_SB(0, 0), b2, voffB); PG8_STAGE(PG8_SB(0, 1), b2 + hstep, voffB); PG8_STAGE(PG8_SA(0, 0), a2, voffA);
;             PG8_WAIT_V(8); PG8_WAIT_L(0); PG8_BAR; PG8_MMA(1, 0, At, B0); PG8_MMA(1, 1, At, B1); PG8_BAR; PG8_SCHED;
;             PG8_LDB(B0, 1, 0); PG8_LDB(B1, 1, 1); PG8_SCHED; PG8_LDA(At, 1, 0); PG8_STAGE(PG8_SA(0, 1), a2 + hstep, voffA);
;             PG8_WAIT_V(8); PG8_WAIT_L(0); PG8_BAR; PG8_MMA(0, 0, At, B0); PG8_MMA(0, 1, At, B1); PG8_BAR; PG8_SCHED;
;             PG8_LDA(At, 1, 1); PG8_STAGE(PG8_SB(1, 0), b3, voffB); PG8_STAGE(PG8_SB(1, 1), b3 + hstep, voffB); PG8_STAGE(PG8_SA(1, 0), a3, voffA);
;             PG8_WAIT_V(8); PG8_WAIT_L(0); PG8_BAR; PG8_MMA(1, 0, At, B0); PG8_MMA(1, 1, At, B1); PG8_BAR; PG8_SCHED;
	s_add_i32 s3, s3, s94
	v_lshl_add_u64 v[74:75], v[212:213], 0, s[68:69]
	s_mov_b32 m0, s3
	ds_read_b128 v[164:167], v240 offset:49152
	ds_read_b128 v[168:171], v240 offset:50176
	ds_read_b128 v[172:175], v240 offset:51200
	ds_read_b128 v[176:179], v240 offset:52224
	ds_read_b128 v[180:183], v240 offset:53248
	ds_read_b128 v[184:187], v240 offset:54272
	ds_read_b128 v[188:191], v240 offset:55296
	ds_read_b128 v[208:211], v240 offset:56320
	global_load_lds_dwordx4 v[74:75], off
	v_lshl_add_u64 v[74:75], v[214:215], 0, s[68:69]
	s_add_i32 m0, s3, 0x2000
	s_add_i32 s3, s81, s94
	global_load_lds_dwordx4 v[74:75], off
	v_lshl_add_u64 v[74:75], v[216:217], 0, s[68:69]
	s_mov_b32 m0, s3
	s_nop 0
	global_load_lds_dwordx4 v[74:75], off
	v_lshl_add_u64 v[74:75], v[218:219], 0, s[68:69]
	s_add_i32 m0, s3, 0x2000
	s_nop 0
	global_load_lds_dwordx4 v[74:75], off
	v_lshl_add_u64 v[74:75], v[220:221], 0, s[68:69]
	s_mov_b32 m0, s53
	s_nop 0
	global_load_lds_dwordx4 v[74:75], off
	v_lshl_add_u64 v[74:75], v[224:225], 0, s[68:69]
	s_mov_b32 m0, s56
	s_nop 0
	global_load_lds_dwordx4 v[74:75], off
	s_waitcnt vmcnt(8)
	s_waitcnt lgkmcnt(0)
	s_barrier
	v_mfma_f32_16x16x32_bf16 v[74:77], v[58:61], v[164:167], v[76:79]
	v_mfma_f32_16x16x32_bf16 v[70:73], v[66:69], v[164:167], v[70:73]
	v_mfma_f32_16x16x32_bf16 v[40:43], v[66:69], v[172:175], v[40:43]
	v_mfma_f32_16x16x32_bf16 v[44:47], v[58:61], v[172:175], v[44:47]
	v_mfma_f32_16x16x32_bf16 v[28:31], v[58:61], v[180:183], v[28:31]
	v_mfma_f32_16x16x32_bf16 v[24:27], v[66:69], v[180:183], v[24:27]
	v_mfma_f32_16x16x32_bf16 v[8:11], v[66:69], v[188:191], v[8:11]
	v_mfma_f32_16x16x32_bf16 v[12:15], v[58:61], v[188:191], v[12:15]
	v_mfma_f32_16x16x32_bf16 v[76:79], v[62:65], v[168:171], v[74:77]
	v_mfma_f32_16x16x32_bf16 v[72:75], v[80:83], v[168:171], v[70:73]
	v_mfma_f32_16x16x32_bf16 v[40:43], v[80:83], v[176:179], v[40:43]
	v_mfma_f32_16x16x32_bf16 v[44:47], v[62:65], v[176:179], v[44:47]
	v_mfma_f32_16x16x32_bf16 v[28:31], v[62:65], v[184:187], v[28:31]
	v_mfma_f32_16x16x32_bf16 v[24:27], v[80:83], v[184:187], v[24:27]
	v_mfma_f32_16x16x32_bf16 v[8:11], v[80:83], v[208:211], v[8:11]
	v_mfma_f32_16x16x32_bf16 v[12:15], v[62:65], v[208:211], v[12:15]
	v_mfma_f32_16x16x32_bf16 v[52:55], v[84:87], v[164:167], v[52:55]
	v_mfma_f32_16x16x32_bf16 v[48:51], v[92:95], v[164:167], v[48:51]
	v_mfma_f32_16x16x32_bf16 v[32:35], v[92:95], v[172:175], v[32:35]
	v_mfma_f32_16x16x32_bf16 v[36:39], v[84:87], v[172:175], v[36:39]
	v_mfma_f32_16x16x32_bf16 v[20:23], v[84:87], v[180:183], v[20:23]
	v_mfma_f32_16x16x32_bf16 v[16:19], v[92:95], v[180:183], v[16:19]
	v_mfma_f32_16x16x32_bf16 v[0:3], v[92:95], v[188:191], v[0:3]
	v_mfma_f32_16x16x32_bf16 v[4:7], v[84:87], v[188:191], v[4:7]
	v_mfma_f32_16x16x32_bf16 v[52:55], v[88:91], v[168:171], v[52:55]
	v_mfma_f32_16x16x32_bf16 v[48:51], v[152:155], v[168:171], v[48:51]
	v_mfma_f32_16x16x32_bf16 v[32:35], v[152:155], v[176:179], v[32:35]
	v_mfma_f32_16x16x32_bf16 v[36:39], v[88:91], v[176:179], v[36:39]
	v_mfma_f32_16x16x32_bf16 v[20:23], v[88:91], v[184:187], v[20:23]
	v_mfma_f32_16x16x32_bf16 v[16:19], v[152:155], v[184:187], v[16:19]
	v_mfma_f32_16x16x32_bf16 v[0:3], v[152:155], v[208:211], v[0:3]
	v_mfma_f32_16x16x32_bf16 v[4:7], v[88:91], v[208:211], v[4:7]
	s_barrier
	s_add_u32 vcc_lo, vcc_lo, 0x100
	s_addc_u32 vcc_hi, vcc_hi, 0
	s_add_u32 s61, s61, 0x100
	s_addc_u32 s67, s67, 0
	s_cmp_ge_u32 s80, s52
	s_mov_b32 s74, s80
.LBB0_567:
	s_add_i32 s80, s74, 2
	s_add_u32 s81, vcc_lo, 0x80
	s_addc_u32 s75, vcc_hi, 0
	s_add_i32 s3, 0, 0x10000
	s_cmp_eq_u32 s57, s74
	s_cselect_b32 s75, s71, s75
	s_cselect_b32 s74, s70, s81
	v_add_u32_e32 v70, s3, v232
	s_cselect_b32 s83, s73, s67
	s_cselect_b32 s82, s72, s61
	s_add_i32 s81, 0, 0x14000
	ds_read_b128 v[58:61], v70
	ds_read_b128 v[62:65], v70 offset:1024
	ds_read_b128 v[66:69], v70 offset:2048
	ds_read_b128 v[80:83], v70 offset:3072
	v_add_u32_e32 v70, s81, v232
	ds_read_b128 v[84:87], v70
	ds_read_b128 v[88:91], v70 offset:1024
	ds_read_b128 v[92:95], v70 offset:2048
	ds_read_b128 v[152:155], v70 offset:3072
	v_lshl_add_u64 v[70:71], vcc, 0, v[204:205]
	s_add_i32 m0, s97, 0xc000
	ds_read_b128 v[164:167], v240
	ds_read_b128 v[168:171], v240 offset:1024
	ds_read_b128 v[172:175], v240 offset:2048
	ds_read_b128 v[176:179], v240 offset:3072
	ds_read_b128 v[180:183], v240 offset:4096
	ds_read_b128 v[184:187], v240 offset:5120
	ds_read_b128 v[188:191], v240 offset:6144
	ds_read_b128 v[208:211], v240 offset:7168
	global_load_lds_dwordx4 v[70:71], off
	v_lshl_add_u64 v[70:71], vcc, 0, v[206:207]
	s_add_i32 m0, s97, 0xe000
	s_nop 0
	global_load_lds_dwordx4 v[70:71], off
	s_waitcnt vmcnt(8)
	s_waitcnt lgkmcnt(0)
	s_barrier
; #define PG8_STAGE(bufoff, gbase, voff) do { _Pragma("unroll") for (int _i = 0; _i < 2; ++_i) \
;         __builtin_amdgcn_global_load_lds((const unsigned*)((const char*)(gbase) + (voff)[_i]), (LAS unsigned*)(lds + (bufoff) + ldsw + _i * 8192), 16, 0, 0); } while (0)
; #define PG8_LDA(dst, b, h) do { _Pragma("unroll") for (int m = 0; m < 4; ++m) _Pragma("unroll") for (int k = 0; k < 2; ++k) dst[m][k] = *(const LAS bf16x8*)(lds + PG8_SA(b, h) + aoff + m * 2048 + k * 1024); } while (0)
; #define PG8_MMA(ai, bj, At, Bt) do { __builtin_amdgcn_s_setprio(1); _Pragma("unroll") for (int m = 0; m < 4; ++m) _Pragma("unroll") for (int n = 0; n < 2; ++n) _Pragma("unroll") for (int k = 0; k < 2; ++k) \
;         acc[ai][bj][m][n] = __builtin_amdgcn_mfma_f32_16x16x32_bf16(Bt[n][k], At[m][k], acc[ai][bj][m][n], 0, 0, 0); __builtin_amdgcn_s_setprio(0); } while (0)
; #define PG8_WAIT_V(n) asm volatile("s_waitcnt vmcnt(" #n ")" ::: "memory")
; #define PG8_WAIT_L(n) asm volatile("s_waitcnt lgkmcnt(" #n ")" ::: "memory")
; #define PG8_BAR __builtin_amdgcn_s_barrier()
; #define PG8_SCHED __builtin_amdgcn_sched_barrier(0)
; template <class Epi, class Sched>
; __device__ __forceinline__ void gemm_phase(LAS unsigned char* lds, const Gemm g, const Sched& S, const Epi& E, const int tid) {
;     ...
;             PG8_WAIT_V(8); PG8_WAIT_L(0); PG8_BAR; PG8_MMA(0, 0, At, B0); PG8_MMA(0, 1, At, B1); PG8_BAR; PG8_SCHED;
;             PG8_LDA(At, 0, 1); PG8_STAGE(PG8_SB(0, 0), b2, voffB); PG8_STAGE(PG8_SB(0, 1), b2 + hstep, voffB); PG8_STAGE(PG8_SA(0, 0), a2, voffA);
;             PG8_WAIT_V(8); PG8_WAIT_L(0); PG8_BAR; PG8_MMA(1, 0, At, B0); PG8_MMA(1, 1, At, B1); PG8_BAR; PG8_SCHED;
	v_mfma_f32_16x16x32_bf16 v[160:163], v[58:61], v[164:167], v[160:163]
	v_mfma_f32_16x16x32_bf16 v[156:159], v[66:69], v[164:167], v[156:159]
	v_mfma_f32_16x16x32_bf16 v[136:139], v[66:69], v[172:175], v[136:139]
	v_mfma_f32_16x16x32_bf16 v[140:143], v[58:61], v[172:175], v[140:143]
	v_mfma_f32_16x16x32_bf16 v[124:127], v[58:61], v[180:183], v[124:127]
	v_mfma_f32_16x16x32_bf16 v[120:123], v[66:69], v[180:183], v[120:123]
	v_mfma_f32_16x16x32_bf16 v[104:107], v[66:69], v[188:191], v[104:107]
	v_mfma_f32_16x16x32_bf16 v[108:111], v[58:61], v[188:191], v[108:111]
	v_mfma_f32_16x16x32_bf16 v[160:163], v[62:65], v[168:171], v[160:163]
	v_mfma_f32_16x16x32_bf16 v[156:159], v[80:83], v[168:171], v[156:159]
	v_mfma_f32_16x16x32_bf16 v[136:139], v[80:83], v[176:179], v[136:139]
	v_mfma_f32_16x16x32_bf16 v[140:143], v[62:65], v[176:179], v[140:143]
	v_mfma_f32_16x16x32_bf16 v[124:127], v[62:65], v[184:187], v[124:127]
	v_mfma_f32_16x16x32_bf16 v[120:123], v[80:83], v[184:187], v[120:123]
	v_mfma_f32_16x16x32_bf16 v[104:107], v[80:83], v[208:211], v[104:107]
	v_mfma_f32_16x16x32_bf16 v[108:111], v[62:65], v[208:211], v[108:111]
	v_mfma_f32_16x16x32_bf16 v[148:151], v[84:87], v[164:167], v[148:151]
	v_mfma_f32_16x16x32_bf16 v[144:147], v[92:95], v[164:167], v[144:147]
	v_mfma_f32_16x16x32_bf16 v[128:131], v[92:95], v[172:175], v[128:131]
	v_mfma_f32_16x16x32_bf16 v[132:135], v[84:87], v[172:175], v[132:135]
	v_mfma_f32_16x16x32_bf16 v[116:119], v[84:87], v[180:183], v[116:119]
	v_mfma_f32_16x16x32_bf16 v[112:115], v[92:95], v[180:183], v[112:115]
	v_mfma_f32_16x16x32_bf16 v[96:99], v[92:95], v[188:191], v[96:99]
	v_mfma_f32_16x16x32_bf16 v[100:103], v[84:87], v[188:191], v[100:103]
	v_mfma_f32_16x16x32_bf16 v[148:151], v[88:91], v[168:171], v[148:151]
	v_mfma_f32_16x16x32_bf16 v[144:147], v[152:155], v[168:171], v[144:147]
	v_mfma_f32_16x16x32_bf16 v[128:131], v[152:155], v[176:179], v[128:131]
	v_mfma_f32_16x16x32_bf16 v[132:135], v[88:91], v[176:179], v[132:135]
	v_mfma_f32_16x16x32_bf16 v[116:119], v[88:91], v[184:187], v[116:119]
	v_mfma_f32_16x16x32_bf16 v[112:115], v[152:155], v[184:187], v[112:115]
	v_mfma_f32_16x16x32_bf16 v[96:99], v[152:155], v[208:211], v[96:99]
	v_mfma_f32_16x16x32_bf16 v[100:103], v[88:91], v[208:211], v[100:103]
	s_barrier
	s_add_i32 s3, s3, s94
	v_lshl_add_u64 v[212:213], s[82:83], 0, v[192:193]
	s_mov_b32 m0, s3
	ds_read_b128 v[164:167], v240 offset:16384
	ds_read_b128 v[168:171], v240 offset:17408
	ds_read_b128 v[172:175], v240 offset:18432
	ds_read_b128 v[176:179], v240 offset:19456
	ds_read_b128 v[180:183], v240 offset:20480
	ds_read_b128 v[184:187], v240 offset:21504
	ds_read_b128 v[188:191], v240 offset:22528
	ds_read_b128 v[208:211], v240 offset:23552
	global_load_lds_dwordx4 v[212:213], off
	s_add_i32 m0, s3, 0x2000
	v_lshl_add_u64 v[214:215], s[82:83], 0, v[198:199]
	s_add_u32 s82, s82, s12
	s_addc_u32 s83, s83, 0
	s_add_i32 s3, s81, s94
	global_load_lds_dwordx4 v[214:215], off
	v_lshl_add_u64 v[216:217], s[82:83], 0, v[192:193]
	s_mov_b32 m0, s3
	v_lshl_add_u64 v[218:219], s[82:83], 0, v[198:199]
	global_load_lds_dwordx4 v[216:217], off
	s_add_i32 m0, s3, 0x2000
	v_lshl_add_u64 v[220:221], s[74:75], 0, v[202:203]
	global_load_lds_dwordx4 v[218:219], off
	s_mov_b32 m0, s97
	v_lshl_add_u64 v[224:225], s[74:75], 0, v[200:201]
	global_load_lds_dwordx4 v[220:221], off
	s_mov_b32 m0, s98
	s_nop 0
	global_load_lds_dwordx4 v[224:225], off
	s_waitcnt vmcnt(8)
	s_waitcnt lgkmcnt(0)
	s_barrier
	v_mfma_f32_16x16x32_bf16 v[76:79], v[58:61], v[164:167], v[76:79]
	v_mfma_f32_16x16x32_bf16 v[70:73], v[66:69], v[164:167], v[72:75]
	v_mfma_f32_16x16x32_bf16 v[40:43], v[66:69], v[172:175], v[40:43]
	v_mfma_f32_16x16x32_bf16 v[44:47], v[58:61], v[172:175], v[44:47]
	v_mfma_f32_16x16x32_bf16 v[28:31], v[58:61], v[180:183], v[28:31]
	v_mfma_f32_16x16x32_bf16 v[24:27], v[66:69], v[180:183], v[24:27]
	v_mfma_f32_16x16x32_bf16 v[8:11], v[66:69], v[188:191], v[8:11]
	v_mfma_f32_16x16x32_bf16 v[12:15], v[58:61], v[188:191], v[12:15]
	v_mfma_f32_16x16x32_bf16 v[76:79], v[62:65], v[168:171], v[76:79]
	v_mfma_f32_16x16x32_bf16 v[70:73], v[80:83], v[168:171], v[70:73]
	v_mfma_f32_16x16x32_bf16 v[40:43], v[80:83], v[176:179], v[40:43]
	v_mfma_f32_16x16x32_bf16 v[44:47], v[62:65], v[176:179], v[44:47]
	v_mfma_f32_16x16x32_bf16 v[28:31], v[62:65], v[184:187], v[28:31]
	v_mfma_f32_16x16x32_bf16 v[24:27], v[80:83], v[184:187], v[24:27]
	v_mfma_f32_16x16x32_bf16 v[8:11], v[80:83], v[208:211], v[8:11]
	v_mfma_f32_16x16x32_bf16 v[12:15], v[62:65], v[208:211], v[12:15]
	v_mfma_f32_16x16x32_bf16 v[52:55], v[84:87], v[164:167], v[52:55]
	v_mfma_f32_16x16x32_bf16 v[48:51], v[92:95], v[164:167], v[48:51]
	v_mfma_f32_16x16x32_bf16 v[32:35], v[92:95], v[172:175], v[32:35]
	v_mfma_f32_16x16x32_bf16 v[36:39], v[84:87], v[172:175], v[36:39]
	v_mfma_f32_16x16x32_bf16 v[20:23], v[84:87], v[180:183], v[20:23]
	v_mfma_f32_16x16x32_bf16 v[16:19], v[92:95], v[180:183], v[16:19]
	v_mfma_f32_16x16x32_bf16 v[0:3], v[92:95], v[188:191], v[0:3]
	v_mfma_f32_16x16x32_bf16 v[4:7], v[84:87], v[188:191], v[4:7]
	v_mfma_f32_16x16x32_bf16 v[52:55], v[88:91], v[168:171], v[52:55]
	v_mfma_f32_16x16x32_bf16 v[48:51], v[152:155], v[168:171], v[48:51]
	v_mfma_f32_16x16x32_bf16 v[32:35], v[152:155], v[176:179], v[32:35]
	v_mfma_f32_16x16x32_bf16 v[36:39], v[88:91], v[176:179], v[36:39]
	v_mfma_f32_16x16x32_bf16 v[20:23], v[88:91], v[184:187], v[20:23]
	v_mfma_f32_16x16x32_bf16 v[16:19], v[152:155], v[184:187], v[16:19]
	v_mfma_f32_16x16x32_bf16 v[0:3], v[152:155], v[208:211], v[0:3]
	v_mfma_f32_16x16x32_bf16 v[4:7], v[88:91], v[208:211], v[4:7]
	s_barrier
; #define PG8_STAGE(bufoff, gbase, voff) do { _Pragma("unroll") for (int _i = 0; _i < 2; ++_i) \
;         __builtin_amdgcn_global_load_lds((const unsigned*)((const char*)(gbase) + (voff)[_i]), (LAS unsigned*)(lds + (bufoff) + ldsw + _i * 8192), 16, 0, 0); } while (0)
; #define PG8_LDA(dst, b, h) do { _Pragma("unroll") for (int m = 0; m < 4; ++m) _Pragma("unroll") for (int k = 0; k < 2; ++k) dst[m][k] = *(const LAS bf16x8*)(lds + PG8_SA(b, h) + aoff + m * 2048 + k * 1024); } while (0)
; #define PG8_LDB(dst, b, h) do { _Pragma("unroll") for (int n = 0; n < 2; ++n) _Pragma("unroll") for (int k = 0; k < 2; ++k) dst[n][k] = *(const LAS bf16x8*)(lds + PG8_SB(b, h) + boff + n * 2048 + k * 1024); } while (0)
; #define PG8_MMA(ai, bj, At, Bt) do { __builtin_amdgcn_s_setprio(1); _Pragma("unroll") for (int m = 0; m < 4; ++m) _Pragma("unroll") for (int n = 0; n < 2; ++n) _Pragma("unroll") for (int k = 0; k < 2; ++k) \
;         acc[ai][bj][m][n] = __builtin_amdgcn_mfma_f32_16x16x32_bf16(Bt[n][k], At[m][k], acc[ai][bj][m][n], 0, 0, 0); __builtin_amdgcn_s_setprio(0); } while (0)
; #define PG8_WAIT_V(n) asm volatile("s_waitcnt vmcnt(" #n ")" ::: "memory")
; #define PG8_WAIT_L(n) asm volatile("s_waitcnt lgkmcnt(" #n ")" ::: "memory")
; #define PG8_BAR __builtin_amdgcn_s_barrier()
; #define PG8_SCHED __builtin_amdgcn_sched_barrier(0)
; template <class Epi, class Sched>
; __device__ __forceinline__ void gemm_phase(LAS unsigned char* lds, const Gemm g, const Sched& S, const Epi& E, const int tid) {
;     ...
;             PG8_LDB(B0, 1, 0); PG8_LDB(B1, 1, 1); PG8_SCHED; PG8_LDA(At, 1, 0); PG8_STAGE(PG8_SA(0, 1), a2 + hstep, voffA);
;             PG8_WAIT_V(8); PG8_WAIT_L(0); PG8_BAR; PG8_MMA(0, 0, At, B0); PG8_MMA(0, 1, At, B1); PG8_BAR; PG8_SCHED;
;             PG8_LDA(At, 1, 1); PG8_STAGE(PG8_SB(1, 0), b3, voffB); PG8_STAGE(PG8_SB(1, 1), b3 + hstep, voffB); PG8_STAGE(PG8_SA(1, 0), a3, voffA);
;             PG8_WAIT_V(8); PG8_WAIT_L(0); PG8_BAR; PG8_MMA(1, 0, At, B0); PG8_MMA(1, 1, At, B1); PG8_BAR; PG8_SCHED;
;         }
;         if (wr == 0) PG8_BAR;
	s_add_i32 s3, 0, 0x18000
	v_add_u32_e32 v74, s3, v232
	s_add_i32 s81, 0, 0x1c000
	ds_read_b128 v[58:61], v74
	ds_read_b128 v[62:65], v74 offset:1024
	ds_read_b128 v[66:69], v74 offset:2048
	ds_read_b128 v[80:83], v74 offset:3072
	v_add_u32_e32 v74, s81, v232
	ds_read_b128 v[84:87], v74
	ds_read_b128 v[88:91], v74 offset:1024
	ds_read_b128 v[92:95], v74 offset:2048
	ds_read_b128 v[152:155], v74 offset:3072
	s_add_u32 s74, s74, s12
	s_addc_u32 s75, s75, 0
	s_mov_b32 m0, s99
	v_lshl_add_u64 v[74:75], s[74:75], 0, v[202:203]
	ds_read_b128 v[164:167], v240 offset:32768
	ds_read_b128 v[168:171], v240 offset:33792
	ds_read_b128 v[172:175], v240 offset:34816
	ds_read_b128 v[176:179], v240 offset:35840
	ds_read_b128 v[180:183], v240 offset:36864
	ds_read_b128 v[184:187], v240 offset:37888
	ds_read_b128 v[188:191], v240 offset:38912
	ds_read_b128 v[208:211], v240 offset:39936
	global_load_lds_dwordx4 v[74:75], off
	v_lshl_add_u64 v[74:75], s[74:75], 0, v[200:201]
	s_mov_b32 m0, s78
	s_nop 0
	global_load_lds_dwordx4 v[74:75], off
	s_waitcnt vmcnt(8)
	s_waitcnt lgkmcnt(0)
	s_barrier
	v_mfma_f32_16x16x32_bf16 v[160:163], v[58:61], v[164:167], v[160:163]
	v_mfma_f32_16x16x32_bf16 v[156:159], v[66:69], v[164:167], v[156:159]
	v_mfma_f32_16x16x32_bf16 v[136:139], v[66:69], v[172:175], v[136:139]
	v_mfma_f32_16x16x32_bf16 v[140:143], v[58:61], v[172:175], v[140:143]
	v_mfma_f32_16x16x32_bf16 v[124:127], v[58:61], v[180:183], v[124:127]
	v_mfma_f32_16x16x32_bf16 v[120:123], v[66:69], v[180:183], v[120:123]
	v_mfma_f32_16x16x32_bf16 v[104:107], v[66:69], v[188:191], v[104:107]
	v_mfma_f32_16x16x32_bf16 v[108:111], v[58:61], v[188:191], v[108:111]
	v_mfma_f32_16x16x32_bf16 v[160:163], v[62:65], v[168:171], v[160:163]
	v_mfma_f32_16x16x32_bf16 v[156:159], v[80:83], v[168:171], v[156:159]
	v_mfma_f32_16x16x32_bf16 v[136:139], v[80:83], v[176:179], v[136:139]
	v_mfma_f32_16x16x32_bf16 v[140:143], v[62:65], v[176:179], v[140:143]
	v_mfma_f32_16x16x32_bf16 v[124:127], v[62:65], v[184:187], v[124:127]
	v_mfma_f32_16x16x32_bf16 v[120:123], v[80:83], v[184:187], v[120:123]
	v_mfma_f32_16x16x32_bf16 v[104:107], v[80:83], v[208:211], v[104:107]
	v_mfma_f32_16x16x32_bf16 v[108:111], v[62:65], v[208:211], v[108:111]
	v_mfma_f32_16x16x32_bf16 v[148:151], v[84:87], v[164:167], v[148:151]
	v_mfma_f32_16x16x32_bf16 v[144:147], v[92:95], v[164:167], v[144:147]
	v_mfma_f32_16x16x32_bf16 v[128:131], v[92:95], v[172:175], v[128:131]
	v_mfma_f32_16x16x32_bf16 v[132:135], v[84:87], v[172:175], v[132:135]
	v_mfma_f32_16x16x32_bf16 v[116:119], v[84:87], v[180:183], v[116:119]
	v_mfma_f32_16x16x32_bf16 v[112:115], v[92:95], v[180:183], v[112:115]
	v_mfma_f32_16x16x32_bf16 v[96:99], v[92:95], v[188:191], v[96:99]
	v_mfma_f32_16x16x32_bf16 v[100:103], v[84:87], v[188:191], v[100:103]
	v_mfma_f32_16x16x32_bf16 v[148:151], v[88:91], v[168:171], v[148:151]
	v_mfma_f32_16x16x32_bf16 v[144:147], v[152:155], v[168:171], v[144:147]
	v_mfma_f32_16x16x32_bf16 v[128:131], v[152:155], v[176:179], v[128:131]
	v_mfma_f32_16x16x32_bf16 v[132:135], v[88:91], v[176:179], v[132:135]
	v_mfma_f32_16x16x32_bf16 v[116:119], v[88:91], v[184:187], v[116:119]
	v_mfma_f32_16x16x32_bf16 v[112:115], v[152:155], v[184:187], v[112:115]
	v_mfma_f32_16x16x32_bf16 v[96:99], v[152:155], v[208:211], v[96:99]
	v_mfma_f32_16x16x32_bf16 v[100:103], v[88:91], v[208:211], v[100:103]
	s_barrier
	s_add_i32 s3, s3, s94
	v_lshl_add_u64 v[74:75], v[212:213], 0, s[68:69]
	s_mov_b32 m0, s3
	ds_read_b128 v[164:167], v240 offset:49152
	ds_read_b128 v[168:171], v240 offset:50176
	ds_read_b128 v[172:175], v240 offset:51200
	ds_read_b128 v[176:179], v240 offset:52224
	ds_read_b128 v[180:183], v240 offset:53248
	ds_read_b128 v[184:187], v240 offset:54272
	ds_read_b128 v[188:191], v240 offset:55296
	ds_read_b128 v[208:211], v240 offset:56320
	global_load_lds_dwordx4 v[74:75], off
	v_lshl_add_u64 v[74:75], v[214:215], 0, s[68:69]
	s_add_i32 m0, s3, 0x2000
	s_add_i32 s3, s81, s94
	global_load_lds_dwordx4 v[74:75], off
	v_lshl_add_u64 v[74:75], v[216:217], 0, s[68:69]
	s_mov_b32 m0, s3
	s_nop 0
	global_load_lds_dwordx4 v[74:75], off
	v_lshl_add_u64 v[74:75], v[218:219], 0, s[68:69]
	s_add_i32 m0, s3, 0x2000
	s_nop 0
	global_load_lds_dwordx4 v[74:75], off
	v_lshl_add_u64 v[74:75], v[220:221], 0, s[68:69]
	s_mov_b32 m0, s53
	s_nop 0
	global_load_lds_dwordx4 v[74:75], off
	v_lshl_add_u64 v[74:75], v[224:225], 0, s[68:69]
	s_mov_b32 m0, s56
	s_nop 0
	global_load_lds_dwordx4 v[74:75], off
	s_waitcnt vmcnt(8)
	s_waitcnt lgkmcnt(0)
	s_barrier
	v_mfma_f32_16x16x32_bf16 v[74:77], v[58:61], v[164:167], v[76:79]
	v_mfma_f32_16x16x32_bf16 v[70:73], v[66:69], v[164:167], v[70:73]
	v_mfma_f32_16x16x32_bf16 v[40:43], v[66:69], v[172:175], v[40:43]
	v_mfma_f32_16x16x32_bf16 v[44:47], v[58:61], v[172:175], v[44:47]
	v_mfma_f32_16x16x32_bf16 v[28:31], v[58:61], v[180:183], v[28:31]
	v_mfma_f32_16x16x32_bf16 v[24:27], v[66:69], v[180:183], v[24:27]
	v_mfma_f32_16x16x32_bf16 v[8:11], v[66:69], v[188:191], v[8:11]
	v_mfma_f32_16x16x32_bf16 v[12:15], v[58:61], v[188:191], v[12:15]
	v_mfma_f32_16x16x32_bf16 v[76:79], v[62:65], v[168:171], v[74:77]
	v_mfma_f32_16x16x32_bf16 v[72:75], v[80:83], v[168:171], v[70:73]
	v_mfma_f32_16x16x32_bf16 v[40:43], v[80:83], v[176:179], v[40:43]
	v_mfma_f32_16x16x32_bf16 v[44:47], v[62:65], v[176:179], v[44:47]
	v_mfma_f32_16x16x32_bf16 v[28:31], v[62:65], v[184:187], v[28:31]
	v_mfma_f32_16x16x32_bf16 v[24:27], v[80:83], v[184:187], v[24:27]
	v_mfma_f32_16x16x32_bf16 v[8:11], v[80:83], v[208:211], v[8:11]
	v_mfma_f32_16x16x32_bf16 v[12:15], v[62:65], v[208:211], v[12:15]
	v_mfma_f32_16x16x32_bf16 v[52:55], v[84:87], v[164:167], v[52:55]
	v_mfma_f32_16x16x32_bf16 v[48:51], v[92:95], v[164:167], v[48:51]
	v_mfma_f32_16x16x32_bf16 v[32:35], v[92:95], v[172:175], v[32:35]
	v_mfma_f32_16x16x32_bf16 v[36:39], v[84:87], v[172:175], v[36:39]
	v_mfma_f32_16x16x32_bf16 v[20:23], v[84:87], v[180:183], v[20:23]
	v_mfma_f32_16x16x32_bf16 v[16:19], v[92:95], v[180:183], v[16:19]
	v_mfma_f32_16x16x32_bf16 v[0:3], v[92:95], v[188:191], v[0:3]
	v_mfma_f32_16x16x32_bf16 v[4:7], v[84:87], v[188:191], v[4:7]
	v_mfma_f32_16x16x32_bf16 v[52:55], v[88:91], v[168:171], v[52:55]
	v_mfma_f32_16x16x32_bf16 v[48:51], v[152:155], v[168:171], v[48:51]
	v_mfma_f32_16x16x32_bf16 v[32:35], v[152:155], v[176:179], v[32:35]
	v_mfma_f32_16x16x32_bf16 v[36:39], v[88:91], v[176:179], v[36:39]
	v_mfma_f32_16x16x32_bf16 v[20:23], v[88:91], v[184:187], v[20:23]
	v_mfma_f32_16x16x32_bf16 v[16:19], v[152:155], v[184:187], v[16:19]
	v_mfma_f32_16x16x32_bf16 v[0:3], v[152:155], v[208:211], v[0:3]
	v_mfma_f32_16x16x32_bf16 v[4:7], v[88:91], v[208:211], v[4:7]
	s_barrier
	s_add_u32 vcc_lo, vcc_lo, 0x100
	s_addc_u32 vcc_hi, vcc_hi, 0
	s_add_u32 s61, s61, 0x100
	s_addc_u32 s67, s67, 0
	s_cmp_ge_u32 s80, s52
	s_mov_b32 s74, s80
	s_cbranch_scc0 .LBB0_567
	s_and_b64 vcc, exec, s[64:65]
	s_cbranch_vccz .LBB0_570
	s_barrier
